# store-drain epilogue plus inverted s_setprio in the GEMM K-loops (load segment high, MFMA segment low)
# baseline (speedup 1.0000x reference)
; #define PG8_STAGE(bufoff, gbase, voff) do { _Pragma("unroll") for (int _i = 0; _i < 2; ++_i) \
;         __builtin_amdgcn_global_load_lds((const unsigned*)((const char*)(gbase) + (voff)[_i]), (PG8_LAS unsigned*)(lds + (bufoff) + ldsw + _i * 8192), 16, 0, 0); } while (0)
; #define PG8_LDA(dst, b, h) do { _Pragma("unroll") for (int m = 0; m < 4; ++m) _Pragma("unroll") for (int k = 0; k < 2; ++k) dst[m][k] = *(const PG8_LAS bf16x8*)(lds + PG8_SA(b, h) + aoff + m * 2048 + k * 1024); } while (0)
; #define PG8_LDB(dst, b, h) do { _Pragma("unroll") for (int n = 0; n < 2; ++n) _Pragma("unroll") for (int k = 0; k < 2; ++k) dst[n][k] = *(const PG8_LAS bf16x8*)(lds + PG8_SB(b, h) + boff + n * 2048 + k * 1024); } while (0)
; #define PG8_WAIT_V(n) asm volatile("s_waitcnt vmcnt(" #n ")" ::: "memory")
; #define PG8_WAIT_L(n) asm volatile("s_waitcnt lgkmcnt(" #n ")" ::: "memory")
; #define PG8_BAR __builtin_amdgcn_s_barrier()
; #define PG8_SCHED __builtin_amdgcn_sched_barrier(0)
; template <class Epi, class Sched, bool ALIGN_EPI = false, bool SP2 = false, bool I8 = false>
; __device__ __forceinline__ void gemm_phase(PG8_LAS unsigned char* lds, const Gemm g, const Sched& S, const Epi& E) {
;     ...
;             PG8_LDB(B0, 0, 0); PG8_LDB(B1, 0, 1); PG8_SCHED; PG8_LDA(At, 0, 0); PG8_STAGE(PG8_SA(1, 1), a1 + hstepA, voffA);
;             PG8_WAIT_V(8); PG8_WAIT_L(0); PG8_BAR; PG8_MMA(0, 0, At, B0); PG8_MMA(0, 1, At, B1); PG8_BAR; PG8_SCHED;
;             PG8_LDA(At, 0, 1); PG8_STAGE(PG8_SB(0, 0), b2, voffB); PG8_STAGE(PG8_SB(0, 1), b2 + hstepB, voffB); PG8_STAGE(PG8_SA(0, 0), a2, voffA);
.LBB0_278:
	s_waitcnt vmcnt(8)
	ds_read_b128 v[26:29], v202
	ds_read_b128 v[30:33], v202 offset:1024
	ds_read_b128 v[34:37], v202 offset:2048
	ds_read_b128 v[38:41], v202 offset:3072
	ds_read_b128 v[164:167], v203
	ds_read_b128 v[168:171], v203 offset:1024
	ds_read_b128 v[172:175], v203 offset:2048
	ds_read_b128 v[180:183], v203 offset:3072
	s_add_u32 s28, s34, 0x4000
	s_addc_u32 s29, s35, 0
	s_cmp_eq_u32 s76, 28
	s_cselect_b32 s74, s6, s28
	s_cselect_b32 s75, s3, s29
	s_cselect_b32 s72, s13, s19
	s_cselect_b32 s73, s12, s21
	s_add_u32 s70, s74, 0x8000
	s_addc_u32 s71, s75, 0
	v_lshl_add_u64 v[176:177], s[34:35], 0, v[158:159]
	s_add_i32 m0, s25, 0xc000
	ds_read_b128 v[184:187], v204
	ds_read_b128 v[206:209], v204 offset:1024
	ds_read_b128 v[218:221], v204 offset:2048
	ds_read_b128 v[222:225], v204 offset:3072
	ds_read_b128 v[226:229], v204 offset:4096
	ds_read_b128 v[230:233], v204 offset:5120
	ds_read_b128 v[234:237], v204 offset:6144
	ds_read_b128 v[238:241], v204 offset:7168
	global_load_lds_dwordx4 v[176:177], off
	v_lshl_add_u64 v[176:177], s[34:35], 0, v[160:161]
	s_add_i32 m0, s25, 0xe000
	s_nop 0
	global_load_lds_dwordx4 v[176:177], off
	s_waitcnt vmcnt(8)
	s_waitcnt lgkmcnt(0)
	s_barrier
	s_setprio 0
	s_waitcnt lgkmcnt(0)
	v_mfma_i32_16x16x64_i8 v[142:145], v[26:29], v[184:187], v[142:145]
	v_mfma_i32_16x16x64_i8 v[138:141], v[34:37], v[184:187], v[138:141]
	v_mfma_i32_16x16x64_i8 v[134:137], v[26:29], v[218:221], v[134:137]
	v_mfma_i32_16x16x64_i8 v[130:133], v[34:37], v[218:221], v[130:133]
	v_mfma_i32_16x16x64_i8 v[118:121], v[26:29], v[226:229], v[118:121]
	v_mfma_i32_16x16x64_i8 v[114:117], v[34:37], v[226:229], v[114:117]
	v_mfma_i32_16x16x64_i8 v[102:105], v[26:29], v[234:237], v[102:105]
	v_mfma_i32_16x16x64_i8 v[98:101], v[34:37], v[234:237], v[98:101]
	v_mfma_i32_16x16x64_i8 v[142:145], v[30:33], v[206:209], v[142:145]
	v_mfma_i32_16x16x64_i8 v[138:141], v[38:41], v[206:209], v[138:141]
	v_mfma_i32_16x16x64_i8 v[134:137], v[30:33], v[222:225], v[134:137]
	v_mfma_i32_16x16x64_i8 v[130:133], v[38:41], v[222:225], v[130:133]
	v_mfma_i32_16x16x64_i8 v[118:121], v[30:33], v[230:233], v[118:121]
	v_mfma_i32_16x16x64_i8 v[114:117], v[38:41], v[230:233], v[114:117]
	v_mfma_i32_16x16x64_i8 v[102:105], v[30:33], v[238:241], v[102:105]
	v_mfma_i32_16x16x64_i8 v[98:101], v[38:41], v[238:241], v[98:101]
	s_setprio 1
	s_setprio 0
	v_mfma_i32_16x16x64_i8 v[126:129], v[164:167], v[184:187], v[126:129]
	v_mfma_i32_16x16x64_i8 v[122:125], v[172:175], v[184:187], v[122:125]
	v_mfma_i32_16x16x64_i8 v[110:113], v[164:167], v[218:221], v[110:113]
	v_mfma_i32_16x16x64_i8 v[106:109], v[172:175], v[218:221], v[106:109]
	v_mfma_i32_16x16x64_i8 v[94:97], v[164:167], v[226:229], v[94:97]
	v_mfma_i32_16x16x64_i8 v[90:93], v[172:175], v[226:229], v[90:93]
	v_mfma_i32_16x16x64_i8 v[86:89], v[164:167], v[234:237], v[86:89]
	v_mfma_i32_16x16x64_i8 v[82:85], v[172:175], v[234:237], v[82:85]
	v_mfma_i32_16x16x64_i8 v[126:129], v[168:171], v[206:209], v[126:129]
	v_mfma_i32_16x16x64_i8 v[122:125], v[180:183], v[206:209], v[122:125]
	v_mfma_i32_16x16x64_i8 v[110:113], v[168:171], v[222:225], v[110:113]
	v_mfma_i32_16x16x64_i8 v[106:109], v[180:183], v[222:225], v[106:109]
	v_mfma_i32_16x16x64_i8 v[94:97], v[168:171], v[230:233], v[94:97]
	v_mfma_i32_16x16x64_i8 v[90:93], v[180:183], v[230:233], v[90:93]
	v_mfma_i32_16x16x64_i8 v[86:89], v[168:171], v[238:241], v[86:89]
	v_mfma_i32_16x16x64_i8 v[82:85], v[180:183], v[238:241], v[82:85]
	s_setprio 1
	s_barrier
	s_add_i32 s28, s81, s84
	v_lshl_add_u64 v[176:177], s[72:73], 0, v[148:149]
	s_mov_b32 m0, s28
	ds_read_b128 v[184:187], v204 offset:16384
	ds_read_b128 v[206:209], v204 offset:17408
	ds_read_b128 v[218:221], v204 offset:18432
	ds_read_b128 v[222:225], v204 offset:19456
	ds_read_b128 v[226:229], v204 offset:20480
	ds_read_b128 v[230:233], v204 offset:21504
	ds_read_b128 v[234:237], v204 offset:22528
	ds_read_b128 v[238:241], v204 offset:23552
	global_load_lds_dwordx4 v[176:177], off
	s_add_i32 m0, s28, 0x2000
	s_add_u32 s86, s72, 0x4000
	v_lshl_add_u64 v[176:177], s[72:73], 0, v[152:153]
	s_addc_u32 s87, s73, 0
	s_add_i32 s28, s14, s84
	global_load_lds_dwordx4 v[176:177], off
	v_lshl_add_u64 v[176:177], s[86:87], 0, v[148:149]
	s_mov_b32 m0, s28
	s_nop 0
	global_load_lds_dwordx4 v[176:177], off
	v_lshl_add_u64 v[176:177], s[86:87], 0, v[152:153]
	s_add_i32 m0, s28, 0x2000
	s_nop 0
	global_load_lds_dwordx4 v[176:177], off
	v_lshl_add_u64 v[176:177], s[74:75], 0, v[146:147]
	s_mov_b32 m0, s25
	s_nop 0
	global_load_lds_dwordx4 v[176:177], off
	v_lshl_add_u64 v[176:177], s[74:75], 0, v[150:151]
	s_mov_b32 m0, s90
	s_nop 0
	global_load_lds_dwordx4 v[176:177], off
	s_waitcnt vmcnt(8)
	s_waitcnt lgkmcnt(0)
	s_barrier
; #define PG8_STAGE(bufoff, gbase, voff) do { _Pragma("unroll") for (int _i = 0; _i < 2; ++_i) \
;         __builtin_amdgcn_global_load_lds((const unsigned*)((const char*)(gbase) + (voff)[_i]), (PG8_LAS unsigned*)(lds + (bufoff) + ldsw + _i * 8192), 16, 0, 0); } while (0)
; #define PG8_LDA(dst, b, h) do { _Pragma("unroll") for (int m = 0; m < 4; ++m) _Pragma("unroll") for (int k = 0; k < 2; ++k) dst[m][k] = *(const PG8_LAS bf16x8*)(lds + PG8_SA(b, h) + aoff + m * 2048 + k * 1024); } while (0)
; #define PG8_LDB(dst, b, h) do { _Pragma("unroll") for (int n = 0; n < 2; ++n) _Pragma("unroll") for (int k = 0; k < 2; ++k) dst[n][k] = *(const PG8_LAS bf16x8*)(lds + PG8_SB(b, h) + boff + n * 2048 + k * 1024); } while (0)
; #define PG8_WAIT_V(n) asm volatile("s_waitcnt vmcnt(" #n ")" ::: "memory")
; #define PG8_WAIT_L(n) asm volatile("s_waitcnt lgkmcnt(" #n ")" ::: "memory")
; #define PG8_BAR __builtin_amdgcn_s_barrier()
; #define PG8_SCHED __builtin_amdgcn_sched_barrier(0)
; template <class Epi, class Sched, bool ALIGN_EPI = false, bool SP2 = false, bool I8 = false>
; __device__ __forceinline__ void gemm_phase(PG8_LAS unsigned char* lds, const Gemm g, const Sched& S, const Epi& E) {
;     ...
;             PG8_WAIT_V(8); PG8_WAIT_L(0); PG8_BAR; PG8_MMA(1, 0, At, B0); PG8_MMA(1, 1, At, B1); PG8_BAR; PG8_SCHED;
;             PG8_LDB(B0, 1, 0); PG8_LDB(B1, 1, 1); PG8_SCHED; PG8_LDA(At, 1, 0); PG8_STAGE(PG8_SA(0, 1), a2 + hstepA, voffA);
;             PG8_WAIT_V(8); PG8_WAIT_L(0); PG8_BAR; PG8_MMA(0, 0, At, B0); PG8_MMA(0, 1, At, B1); PG8_BAR; PG8_SCHED;
	s_setprio 0
	s_waitcnt lgkmcnt(0)
	v_mfma_i32_16x16x64_i8 v[78:81], v[26:29], v[184:187], v[78:81]
	v_mfma_i32_16x16x64_i8 v[74:77], v[34:37], v[184:187], v[74:77]
	v_mfma_i32_16x16x64_i8 v[70:73], v[26:29], v[218:221], v[70:73]
	v_mfma_i32_16x16x64_i8 v[66:69], v[34:37], v[218:221], v[66:69]
	v_mfma_i32_16x16x64_i8 v[54:57], v[26:29], v[226:229], v[54:57]
	v_mfma_i32_16x16x64_i8 v[50:53], v[34:37], v[226:229], v[50:53]
	v_mfma_i32_16x16x64_i8 v[14:17], v[26:29], v[234:237], v[14:17]
	v_mfma_i32_16x16x64_i8 v[10:13], v[34:37], v[234:237], v[10:13]
	v_mfma_i32_16x16x64_i8 v[78:81], v[30:33], v[206:209], v[78:81]
	v_mfma_i32_16x16x64_i8 v[74:77], v[38:41], v[206:209], v[74:77]
	v_mfma_i32_16x16x64_i8 v[70:73], v[30:33], v[222:225], v[70:73]
	v_mfma_i32_16x16x64_i8 v[66:69], v[38:41], v[222:225], v[66:69]
	v_mfma_i32_16x16x64_i8 v[54:57], v[30:33], v[230:233], v[54:57]
	v_mfma_i32_16x16x64_i8 v[50:53], v[38:41], v[230:233], v[50:53]
	v_mfma_i32_16x16x64_i8 v[14:17], v[30:33], v[238:241], v[14:17]
	v_mfma_i32_16x16x64_i8 v[10:13], v[38:41], v[238:241], v[10:13]
	s_setprio 1
	s_setprio 0
	v_mfma_i32_16x16x64_i8 v[22:25], v[164:167], v[226:229], v[22:25]
	v_mfma_i32_16x16x64_i8 v[18:21], v[172:175], v[226:229], v[18:21]
	v_mfma_i32_16x16x64_i8 v[6:9], v[164:167], v[234:237], v[6:9]
	v_mfma_i32_16x16x64_i8 v[2:5], v[172:175], v[234:237], v[2:5]
	v_mfma_i32_16x16x64_i8 v[26:29], v[164:167], v[184:187], v[62:65]
	v_mfma_i32_16x16x64_i8 v[30:33], v[172:175], v[184:187], v[58:61]
	v_mfma_i32_16x16x64_i8 v[34:37], v[164:167], v[218:221], v[46:49]
	v_mfma_i32_16x16x64_i8 v[38:41], v[172:175], v[218:221], v[42:45]
	v_mfma_i32_16x16x64_i8 v[22:25], v[168:171], v[230:233], v[22:25]
	v_mfma_i32_16x16x64_i8 v[18:21], v[180:183], v[230:233], v[18:21]
	v_mfma_i32_16x16x64_i8 v[6:9], v[168:171], v[238:241], v[6:9]
	v_mfma_i32_16x16x64_i8 v[2:5], v[180:183], v[238:241], v[2:5]
	v_mfma_i32_16x16x64_i8 v[26:29], v[168:171], v[206:209], v[26:29]
	v_mfma_i32_16x16x64_i8 v[30:33], v[180:183], v[206:209], v[30:33]
	v_mfma_i32_16x16x64_i8 v[34:37], v[168:171], v[222:225], v[34:37]
	v_mfma_i32_16x16x64_i8 v[38:41], v[180:183], v[222:225], v[38:41]
	s_setprio 1
	s_barrier
	s_add_i32 s28, 0, 0x18000
	s_add_i32 s29, 0, 0x1c000
	v_add_u32_e32 v62, s28, v200
	v_add_u32_e32 v176, s29, v200
	ds_read_b128 v[42:45], v62
	ds_read_b128 v[46:49], v62 offset:1024
	ds_read_b128 v[58:61], v62 offset:2048
	ds_read_b128 v[62:65], v62 offset:3072
	ds_read_b128 v[164:167], v176
	ds_read_b128 v[168:171], v176 offset:1024
	ds_read_b128 v[172:175], v176 offset:2048
	ds_read_b128 v[180:183], v176 offset:3072
	s_add_u32 s74, s74, 0x4000
	s_addc_u32 s75, s75, 0
	s_mov_b32 m0, s91
	v_lshl_add_u64 v[176:177], s[74:75], 0, v[146:147]
	ds_read_b128 v[184:187], v204 offset:32768
	ds_read_b128 v[206:209], v204 offset:33792
	ds_read_b128 v[218:221], v204 offset:34816
	ds_read_b128 v[222:225], v204 offset:35840
	ds_read_b128 v[226:229], v204 offset:36864
	ds_read_b128 v[230:233], v204 offset:37888
	ds_read_b128 v[234:237], v204 offset:38912
	ds_read_b128 v[238:241], v204 offset:39936
	global_load_lds_dwordx4 v[176:177], off
	v_lshl_add_u64 v[176:177], s[74:75], 0, v[150:151]
	s_mov_b32 m0, s92
	s_nop 0
	global_load_lds_dwordx4 v[176:177], off
	s_waitcnt vmcnt(8)
	s_waitcnt lgkmcnt(0)
	s_barrier
	s_setprio 0
	s_waitcnt lgkmcnt(0)
	v_mfma_i32_16x16x64_i8 v[142:145], v[42:45], v[184:187], v[142:145]
	v_mfma_i32_16x16x64_i8 v[138:141], v[58:61], v[184:187], v[138:141]
	v_mfma_i32_16x16x64_i8 v[134:137], v[42:45], v[218:221], v[134:137]
	v_mfma_i32_16x16x64_i8 v[130:133], v[58:61], v[218:221], v[130:133]
	v_mfma_i32_16x16x64_i8 v[118:121], v[42:45], v[226:229], v[118:121]
	v_mfma_i32_16x16x64_i8 v[114:117], v[58:61], v[226:229], v[114:117]
	v_mfma_i32_16x16x64_i8 v[102:105], v[42:45], v[234:237], v[102:105]
	v_mfma_i32_16x16x64_i8 v[98:101], v[58:61], v[234:237], v[98:101]
	v_mfma_i32_16x16x64_i8 v[142:145], v[46:49], v[206:209], v[142:145]
	v_mfma_i32_16x16x64_i8 v[138:141], v[62:65], v[206:209], v[138:141]
	v_mfma_i32_16x16x64_i8 v[134:137], v[46:49], v[222:225], v[134:137]
	v_mfma_i32_16x16x64_i8 v[130:133], v[62:65], v[222:225], v[130:133]
	v_mfma_i32_16x16x64_i8 v[118:121], v[46:49], v[230:233], v[118:121]
	v_mfma_i32_16x16x64_i8 v[114:117], v[62:65], v[230:233], v[114:117]
	v_mfma_i32_16x16x64_i8 v[102:105], v[46:49], v[238:241], v[102:105]
	v_mfma_i32_16x16x64_i8 v[98:101], v[62:65], v[238:241], v[98:101]
	s_setprio 1
	s_setprio 0
	v_mfma_i32_16x16x64_i8 v[126:129], v[164:167], v[184:187], v[126:129]
	v_mfma_i32_16x16x64_i8 v[122:125], v[172:175], v[184:187], v[122:125]
	v_mfma_i32_16x16x64_i8 v[110:113], v[164:167], v[218:221], v[110:113]
	v_mfma_i32_16x16x64_i8 v[106:109], v[172:175], v[218:221], v[106:109]
	v_mfma_i32_16x16x64_i8 v[94:97], v[164:167], v[226:229], v[94:97]
	v_mfma_i32_16x16x64_i8 v[90:93], v[172:175], v[226:229], v[90:93]
	v_mfma_i32_16x16x64_i8 v[86:89], v[164:167], v[234:237], v[86:89]
	v_mfma_i32_16x16x64_i8 v[82:85], v[172:175], v[234:237], v[82:85]
	v_mfma_i32_16x16x64_i8 v[126:129], v[168:171], v[206:209], v[126:129]
	v_mfma_i32_16x16x64_i8 v[122:125], v[180:183], v[206:209], v[122:125]
	v_mfma_i32_16x16x64_i8 v[110:113], v[168:171], v[222:225], v[110:113]
	v_mfma_i32_16x16x64_i8 v[106:109], v[180:183], v[222:225], v[106:109]
	v_mfma_i32_16x16x64_i8 v[94:97], v[168:171], v[230:233], v[94:97]
	v_mfma_i32_16x16x64_i8 v[90:93], v[180:183], v[230:233], v[90:93]
	v_mfma_i32_16x16x64_i8 v[86:89], v[168:171], v[238:241], v[86:89]
	v_mfma_i32_16x16x64_i8 v[82:85], v[180:183], v[238:241], v[82:85]
	s_setprio 1
	s_barrier
; #define PG8_STAGE(bufoff, gbase, voff) do { _Pragma("unroll") for (int _i = 0; _i < 2; ++_i) \
;         __builtin_amdgcn_global_load_lds((const unsigned*)((const char*)(gbase) + (voff)[_i]), (PG8_LAS unsigned*)(lds + (bufoff) + ldsw + _i * 8192), 16, 0, 0); } while (0)
; #define PG8_LDA(dst, b, h) do { _Pragma("unroll") for (int m = 0; m < 4; ++m) _Pragma("unroll") for (int k = 0; k < 2; ++k) dst[m][k] = *(const PG8_LAS bf16x8*)(lds + PG8_SA(b, h) + aoff + m * 2048 + k * 1024); } while (0)
; #define PG8_WAIT_V(n) asm volatile("s_waitcnt vmcnt(" #n ")" ::: "memory")
; #define PG8_WAIT_L(n) asm volatile("s_waitcnt lgkmcnt(" #n ")" ::: "memory")
; #define PG8_BAR __builtin_amdgcn_s_barrier()
; #define PG8_SCHED __builtin_amdgcn_sched_barrier(0)
; template <class Epi, class Sched, bool ALIGN_EPI = false, bool SP2 = false, bool I8 = false>
; __device__ __forceinline__ void gemm_phase(PG8_LAS unsigned char* lds, const Gemm g, const Sched& S, const Epi& E) {
;     ...
;             PG8_LDA(At, 1, 1); PG8_STAGE(PG8_SB(1, 0), b3, voffB); PG8_STAGE(PG8_SB(1, 1), b3 + hstepB, voffB); PG8_STAGE(PG8_SA(1, 0), a3, voffA);
;             PG8_WAIT_V(8); PG8_WAIT_L(0); PG8_BAR; PG8_MMA(1, 0, At, B0); PG8_MMA(1, 1, At, B1); PG8_BAR; PG8_SCHED;
	s_add_u32 s74, s72, 0x8000
	s_addc_u32 s75, s73, 0
	s_add_i32 s28, s28, s84
	v_lshl_add_u64 v[176:177], s[74:75], 0, v[148:149]
	s_mov_b32 m0, s28
	ds_read_b128 v[184:187], v204 offset:49152
	ds_read_b128 v[206:209], v204 offset:50176
	ds_read_b128 v[218:221], v204 offset:51200
	ds_read_b128 v[222:225], v204 offset:52224
	ds_read_b128 v[226:229], v204 offset:53248
	ds_read_b128 v[230:233], v204 offset:54272
	ds_read_b128 v[234:237], v204 offset:55296
	ds_read_b128 v[238:241], v204 offset:56320
	global_load_lds_dwordx4 v[176:177], off
	s_add_i32 m0, s28, 0x2000
	s_add_u32 s72, s72, 0xc000
	v_lshl_add_u64 v[176:177], s[74:75], 0, v[152:153]
	s_addc_u32 s73, s73, 0
	s_add_i32 s28, s29, s84
	global_load_lds_dwordx4 v[176:177], off
	v_lshl_add_u64 v[176:177], s[72:73], 0, v[148:149]
	s_mov_b32 m0, s28
	s_nop 0
	global_load_lds_dwordx4 v[176:177], off
	v_lshl_add_u64 v[176:177], s[72:73], 0, v[152:153]
	s_add_i32 m0, s28, 0x2000
	s_nop 0
	global_load_lds_dwordx4 v[176:177], off
	v_lshl_add_u64 v[176:177], s[70:71], 0, v[146:147]
	s_mov_b32 m0, s97
	s_nop 0
	global_load_lds_dwordx4 v[176:177], off
	v_lshl_add_u64 v[176:177], s[70:71], 0, v[150:151]
	s_mov_b32 m0, s82
	s_nop 0
	global_load_lds_dwordx4 v[176:177], off
	s_waitcnt vmcnt(8)
	s_waitcnt lgkmcnt(0)
	s_barrier
	s_setprio 0
	s_waitcnt lgkmcnt(0)
	v_mfma_i32_16x16x64_i8 v[78:81], v[42:45], v[184:187], v[78:81]
	v_mfma_i32_16x16x64_i8 v[74:77], v[58:61], v[184:187], v[74:77]
	v_mfma_i32_16x16x64_i8 v[70:73], v[42:45], v[218:221], v[70:73]
	v_mfma_i32_16x16x64_i8 v[66:69], v[58:61], v[218:221], v[66:69]
	v_mfma_i32_16x16x64_i8 v[54:57], v[42:45], v[226:229], v[54:57]
	v_mfma_i32_16x16x64_i8 v[50:53], v[58:61], v[226:229], v[50:53]
	v_mfma_i32_16x16x64_i8 v[14:17], v[42:45], v[234:237], v[14:17]
	v_mfma_i32_16x16x64_i8 v[10:13], v[58:61], v[234:237], v[10:13]
	v_mfma_i32_16x16x64_i8 v[78:81], v[46:49], v[206:209], v[78:81]
	v_mfma_i32_16x16x64_i8 v[74:77], v[62:65], v[206:209], v[74:77]
	v_mfma_i32_16x16x64_i8 v[70:73], v[46:49], v[222:225], v[70:73]
	v_mfma_i32_16x16x64_i8 v[66:69], v[62:65], v[222:225], v[66:69]
	v_mfma_i32_16x16x64_i8 v[54:57], v[46:49], v[230:233], v[54:57]
	v_mfma_i32_16x16x64_i8 v[50:53], v[62:65], v[230:233], v[50:53]
	v_mfma_i32_16x16x64_i8 v[14:17], v[46:49], v[238:241], v[14:17]
	v_mfma_i32_16x16x64_i8 v[10:13], v[62:65], v[238:241], v[10:13]
	s_setprio 1
	s_setprio 0
	v_mfma_i32_16x16x64_i8 v[26:29], v[164:167], v[184:187], v[26:29]
	v_mfma_i32_16x16x64_i8 v[62:65], v[168:171], v[206:209], v[26:29]
	v_mfma_i32_16x16x64_i8 v[26:29], v[172:175], v[184:187], v[30:33]
	v_mfma_i32_16x16x64_i8 v[58:61], v[180:183], v[206:209], v[26:29]
	v_mfma_i32_16x16x64_i8 v[26:29], v[164:167], v[218:221], v[34:37]
	v_mfma_i32_16x16x64_i8 v[46:49], v[168:171], v[222:225], v[26:29]
	v_mfma_i32_16x16x64_i8 v[26:29], v[172:175], v[218:221], v[38:41]
	v_mfma_i32_16x16x64_i8 v[22:25], v[164:167], v[226:229], v[22:25]
	v_mfma_i32_16x16x64_i8 v[18:21], v[172:175], v[226:229], v[18:21]
	v_mfma_i32_16x16x64_i8 v[6:9], v[164:167], v[234:237], v[6:9]
	v_mfma_i32_16x16x64_i8 v[2:5], v[172:175], v[234:237], v[2:5]
	v_mfma_i32_16x16x64_i8 v[42:45], v[180:183], v[222:225], v[26:29]
	v_mfma_i32_16x16x64_i8 v[22:25], v[168:171], v[230:233], v[22:25]
	v_mfma_i32_16x16x64_i8 v[18:21], v[180:183], v[230:233], v[18:21]
	v_mfma_i32_16x16x64_i8 v[6:9], v[168:171], v[238:241], v[6:9]
	v_mfma_i32_16x16x64_i8 v[2:5], v[180:183], v[238:241], v[2:5]
	s_setprio 1
	s_barrier
	s_add_i32 s76, s76, 2
	s_add_u32 s34, s34, 0x10000
	s_addc_u32 s35, s35, 0
	s_add_u32 s19, s19, 0x10000
	s_addc_u32 s21, s21, 0
	s_cmp_gt_u32 s76, 29
	s_cbranch_scc0 .LBB0_278
	s_and_b64 vcc, exec, s[16:17]
	s_cbranch_vccz .LBB0_281
	s_barrier

; #define PG8_STAGE(bufoff, gbase, voff) do { _Pragma("unroll") for (int _i = 0; _i < 2; ++_i) \
;         __builtin_amdgcn_global_load_lds((const unsigned*)((const char*)(gbase) + (voff)[_i]), (PG8_LAS unsigned*)(lds + (bufoff) + ldsw + _i * 8192), 16, 0, 0); } while (0)
; #define PG8_LDA(dst, b, h) do { _Pragma("unroll") for (int m = 0; m < 4; ++m) _Pragma("unroll") for (int k = 0; k < 2; ++k) dst[m][k] = *(const PG8_LAS bf16x8*)(lds + PG8_SA(b, h) + aoff + m * 2048 + k * 1024); } while (0)
; #define PG8_LDB(dst, b, h) do { _Pragma("unroll") for (int n = 0; n < 2; ++n) _Pragma("unroll") for (int k = 0; k < 2; ++k) dst[n][k] = *(const PG8_LAS bf16x8*)(lds + PG8_SB(b, h) + boff + n * 2048 + k * 1024); } while (0)
; #define PG8_WAIT_V(n) asm volatile("s_waitcnt vmcnt(" #n ")" ::: "memory")
; #define PG8_WAIT_L(n) asm volatile("s_waitcnt lgkmcnt(" #n ")" ::: "memory")
; #define PG8_BAR __builtin_amdgcn_s_barrier()
; #define PG8_SCHED __builtin_amdgcn_sched_barrier(0)
; template <class Epi, class Sched, bool ALIGN_EPI = false, bool SP2 = false, bool I8 = false>
; __device__ __forceinline__ void gemm_phase(PG8_LAS unsigned char* lds, const Gemm g, const Sched& S, const Epi& E) {
;     ...
;             PG8_LDB(B0, 0, 0); PG8_LDB(B1, 0, 1); PG8_SCHED; PG8_LDA(At, 0, 0); PG8_STAGE(PG8_SA(1, 1), a1 + hstepA, voffA);
;             PG8_WAIT_V(8); PG8_WAIT_L(0); PG8_BAR; PG8_MMA(0, 0, At, B0); PG8_MMA(0, 1, At, B1); PG8_BAR; PG8_SCHED;
;             PG8_LDA(At, 0, 1); PG8_STAGE(PG8_SB(0, 0), b2, voffB); PG8_STAGE(PG8_SB(0, 1), b2 + hstepB, voffB); PG8_STAGE(PG8_SA(0, 0), a2, voffA);
.LBB0_316:
	ds_read_b128 v[130:133], v161
	ds_read_b128 v[134:137], v161 offset:1024
	ds_read_b128 v[164:167], v161 offset:2048
	ds_read_b128 v[168:171], v161 offset:3072
	ds_read_b128 v[172:175], v162
	ds_read_b128 v[180:183], v162 offset:1024
	ds_read_b128 v[184:187], v162 offset:2048
	ds_read_b128 v[188:191], v162 offset:3072
	s_add_u32 s26, s24, 0x4000
	s_addc_u32 s27, s25, 0
	s_cmp_eq_u32 s89, 60
	s_cselect_b32 s70, s13, s26
	s_cselect_b32 s71, s7, s27
	s_cselect_b32 s34, s19, vcc_lo
	s_cselect_b32 s35, s17, vcc_hi
	s_add_u32 s26, s70, 0x8000
	s_addc_u32 s27, s71, 0
	v_lshl_add_u64 v[138:139], s[24:25], 0, v[142:143]
	s_add_i32 m0, s78, 0xc000
	ds_read_b128 v[192:195], v163
	ds_read_b128 v[198:201], v163 offset:1024
	ds_read_b128 v[202:205], v163 offset:2048
	ds_read_b128 v[206:209], v163 offset:3072
	ds_read_b128 v[218:221], v163 offset:4096
	ds_read_b128 v[222:225], v163 offset:5120
	ds_read_b128 v[226:229], v163 offset:6144
	ds_read_b128 v[230:233], v163 offset:7168
	global_load_lds_dwordx4 v[138:139], off
	v_lshl_add_u64 v[138:139], s[24:25], 0, v[144:145]
	s_add_i32 m0, s78, 0xe000
	s_nop 0
	global_load_lds_dwordx4 v[138:139], off
	s_waitcnt vmcnt(8)
	s_waitcnt lgkmcnt(0)
	s_barrier
	s_setprio 0
	s_waitcnt lgkmcnt(0)
	v_mfma_f32_16x16x32_bf16 v[126:129], v[130:133], v[192:195], v[126:129]
	v_mfma_f32_16x16x32_bf16 v[122:125], v[164:167], v[192:195], v[122:125]
	v_mfma_f32_16x16x32_bf16 v[110:113], v[130:133], v[202:205], v[110:113]
	v_mfma_f32_16x16x32_bf16 v[106:109], v[164:167], v[202:205], v[106:109]
	v_mfma_f32_16x16x32_bf16 v[94:97], v[130:133], v[218:221], v[94:97]
	v_mfma_f32_16x16x32_bf16 v[90:93], v[164:167], v[218:221], v[90:93]
	v_mfma_f32_16x16x32_bf16 v[78:81], v[130:133], v[226:229], v[78:81]
	v_mfma_f32_16x16x32_bf16 v[74:77], v[164:167], v[226:229], v[74:77]
	v_mfma_f32_16x16x32_bf16 v[126:129], v[134:137], v[198:201], v[126:129]
	v_mfma_f32_16x16x32_bf16 v[122:125], v[168:171], v[198:201], v[122:125]
	v_mfma_f32_16x16x32_bf16 v[110:113], v[134:137], v[206:209], v[110:113]
	v_mfma_f32_16x16x32_bf16 v[106:109], v[168:171], v[206:209], v[106:109]
	v_mfma_f32_16x16x32_bf16 v[94:97], v[134:137], v[222:225], v[94:97]
	v_mfma_f32_16x16x32_bf16 v[90:93], v[168:171], v[222:225], v[90:93]
	v_mfma_f32_16x16x32_bf16 v[78:81], v[134:137], v[230:233], v[78:81]
	v_mfma_f32_16x16x32_bf16 v[74:77], v[168:171], v[230:233], v[74:77]
	s_setprio 1
	s_setprio 0
	v_mfma_f32_16x16x32_bf16 v[118:121], v[172:175], v[192:195], v[118:121]
	v_mfma_f32_16x16x32_bf16 v[114:117], v[184:187], v[192:195], v[114:117]
	v_mfma_f32_16x16x32_bf16 v[102:105], v[172:175], v[202:205], v[102:105]
	v_mfma_f32_16x16x32_bf16 v[98:101], v[184:187], v[202:205], v[98:101]
	v_mfma_f32_16x16x32_bf16 v[86:89], v[172:175], v[218:221], v[86:89]
	v_mfma_f32_16x16x32_bf16 v[82:85], v[184:187], v[218:221], v[82:85]
	v_mfma_f32_16x16x32_bf16 v[70:73], v[172:175], v[226:229], v[70:73]
	v_mfma_f32_16x16x32_bf16 v[66:69], v[184:187], v[226:229], v[66:69]
	v_mfma_f32_16x16x32_bf16 v[118:121], v[180:183], v[198:201], v[118:121]
	v_mfma_f32_16x16x32_bf16 v[114:117], v[188:191], v[198:201], v[114:117]
	v_mfma_f32_16x16x32_bf16 v[102:105], v[180:183], v[206:209], v[102:105]
	v_mfma_f32_16x16x32_bf16 v[98:101], v[188:191], v[206:209], v[98:101]
	v_mfma_f32_16x16x32_bf16 v[86:89], v[180:183], v[222:225], v[86:89]
	v_mfma_f32_16x16x32_bf16 v[82:85], v[188:191], v[222:225], v[82:85]
	v_mfma_f32_16x16x32_bf16 v[70:73], v[180:183], v[230:233], v[70:73]
	v_mfma_f32_16x16x32_bf16 v[66:69], v[188:191], v[230:233], v[66:69]
	s_setprio 1
	s_barrier
	s_add_i32 s28, s97, s75
	v_lshl_add_u64 v[138:139], s[34:35], 0, v[148:149]
	s_mov_b32 m0, s28
	ds_read_b128 v[192:195], v163 offset:16384
	ds_read_b128 v[198:201], v163 offset:17408
	ds_read_b128 v[202:205], v163 offset:18432
	ds_read_b128 v[206:209], v163 offset:19456
	ds_read_b128 v[218:221], v163 offset:20480
	ds_read_b128 v[222:225], v163 offset:21504
	ds_read_b128 v[226:229], v163 offset:22528
	ds_read_b128 v[230:233], v163 offset:23552
	global_load_lds_dwordx4 v[138:139], off
	s_add_i32 m0, s28, 0x2000
	s_add_u32 s28, s34, 0x4000
	v_lshl_add_u64 v[138:139], s[34:35], 0, v[152:153]
	s_addc_u32 s29, s35, 0
	s_add_i32 s8, s76, s75
	global_load_lds_dwordx4 v[138:139], off
	v_lshl_add_u64 v[138:139], s[28:29], 0, v[148:149]
	s_mov_b32 m0, s8
	s_nop 0
	global_load_lds_dwordx4 v[138:139], off
	v_lshl_add_u64 v[138:139], s[28:29], 0, v[152:153]
	s_add_i32 m0, s8, 0x2000
	s_nop 0
	global_load_lds_dwordx4 v[138:139], off
	v_lshl_add_u64 v[138:139], s[70:71], 0, v[146:147]
	s_mov_b32 m0, s78
	s_nop 0
	global_load_lds_dwordx4 v[138:139], off
	v_lshl_add_u64 v[138:139], s[70:71], 0, v[150:151]
	s_mov_b32 m0, s79
	s_nop 0
	global_load_lds_dwordx4 v[138:139], off
	s_waitcnt vmcnt(8)
	s_waitcnt lgkmcnt(0)
	s_barrier
; #define PG8_STAGE(bufoff, gbase, voff) do { _Pragma("unroll") for (int _i = 0; _i < 2; ++_i) \
;         __builtin_amdgcn_global_load_lds((const unsigned*)((const char*)(gbase) + (voff)[_i]), (PG8_LAS unsigned*)(lds + (bufoff) + ldsw + _i * 8192), 16, 0, 0); } while (0)
; #define PG8_LDA(dst, b, h) do { _Pragma("unroll") for (int m = 0; m < 4; ++m) _Pragma("unroll") for (int k = 0; k < 2; ++k) dst[m][k] = *(const PG8_LAS bf16x8*)(lds + PG8_SA(b, h) + aoff + m * 2048 + k * 1024); } while (0)
; #define PG8_LDB(dst, b, h) do { _Pragma("unroll") for (int n = 0; n < 2; ++n) _Pragma("unroll") for (int k = 0; k < 2; ++k) dst[n][k] = *(const PG8_LAS bf16x8*)(lds + PG8_SB(b, h) + boff + n * 2048 + k * 1024); } while (0)
; #define PG8_WAIT_V(n) asm volatile("s_waitcnt vmcnt(" #n ")" ::: "memory")
; #define PG8_WAIT_L(n) asm volatile("s_waitcnt lgkmcnt(" #n ")" ::: "memory")
; #define PG8_BAR __builtin_amdgcn_s_barrier()
; #define PG8_SCHED __builtin_amdgcn_sched_barrier(0)
; template <class Epi, class Sched, bool ALIGN_EPI = false, bool SP2 = false, bool I8 = false>
; __device__ __forceinline__ void gemm_phase(PG8_LAS unsigned char* lds, const Gemm g, const Sched& S, const Epi& E) {
;     ...
;             PG8_WAIT_V(8); PG8_WAIT_L(0); PG8_BAR; PG8_MMA(1, 0, At, B0); PG8_MMA(1, 1, At, B1); PG8_BAR; PG8_SCHED;
;             PG8_LDB(B0, 1, 0); PG8_LDB(B1, 1, 1); PG8_SCHED; PG8_LDA(At, 1, 0); PG8_STAGE(PG8_SA(0, 1), a2 + hstepA, voffA);
;             PG8_WAIT_V(8); PG8_WAIT_L(0); PG8_BAR; PG8_MMA(0, 0, At, B0); PG8_MMA(0, 1, At, B1); PG8_BAR; PG8_SCHED;
	s_setprio 0
	s_waitcnt lgkmcnt(0)
	v_mfma_f32_16x16x32_bf16 v[62:65], v[130:133], v[192:195], v[62:65]
	v_mfma_f32_16x16x32_bf16 v[58:61], v[164:167], v[192:195], v[58:61]
	v_mfma_f32_16x16x32_bf16 v[46:49], v[130:133], v[202:205], v[46:49]
	v_mfma_f32_16x16x32_bf16 v[42:45], v[164:167], v[202:205], v[42:45]
	v_mfma_f32_16x16x32_bf16 v[30:33], v[130:133], v[218:221], v[30:33]
	v_mfma_f32_16x16x32_bf16 v[26:29], v[164:167], v[218:221], v[26:29]
	v_mfma_f32_16x16x32_bf16 v[14:17], v[130:133], v[226:229], v[14:17]
	v_mfma_f32_16x16x32_bf16 v[10:13], v[164:167], v[226:229], v[10:13]
	v_mfma_f32_16x16x32_bf16 v[62:65], v[134:137], v[198:201], v[62:65]
	v_mfma_f32_16x16x32_bf16 v[58:61], v[168:171], v[198:201], v[58:61]
	v_mfma_f32_16x16x32_bf16 v[46:49], v[134:137], v[206:209], v[46:49]
	v_mfma_f32_16x16x32_bf16 v[42:45], v[168:171], v[206:209], v[42:45]
	v_mfma_f32_16x16x32_bf16 v[30:33], v[134:137], v[222:225], v[30:33]
	v_mfma_f32_16x16x32_bf16 v[26:29], v[168:171], v[222:225], v[26:29]
	v_mfma_f32_16x16x32_bf16 v[14:17], v[134:137], v[230:233], v[14:17]
	v_mfma_f32_16x16x32_bf16 v[10:13], v[168:171], v[230:233], v[10:13]
	s_setprio 1
	s_setprio 0
	v_mfma_f32_16x16x32_bf16 v[54:57], v[172:175], v[192:195], v[54:57]
	v_mfma_f32_16x16x32_bf16 v[50:53], v[184:187], v[192:195], v[50:53]
	v_mfma_f32_16x16x32_bf16 v[38:41], v[172:175], v[202:205], v[38:41]
	v_mfma_f32_16x16x32_bf16 v[34:37], v[184:187], v[202:205], v[34:37]
	v_mfma_f32_16x16x32_bf16 v[22:25], v[172:175], v[218:221], v[22:25]
	v_mfma_f32_16x16x32_bf16 v[18:21], v[184:187], v[218:221], v[18:21]
	v_mfma_f32_16x16x32_bf16 v[6:9], v[172:175], v[226:229], v[6:9]
	v_mfma_f32_16x16x32_bf16 v[2:5], v[184:187], v[226:229], v[2:5]
	v_mfma_f32_16x16x32_bf16 v[54:57], v[180:183], v[198:201], v[54:57]
	v_mfma_f32_16x16x32_bf16 v[50:53], v[188:191], v[198:201], v[50:53]
	v_mfma_f32_16x16x32_bf16 v[38:41], v[180:183], v[206:209], v[38:41]
	v_mfma_f32_16x16x32_bf16 v[34:37], v[188:191], v[206:209], v[34:37]
	v_mfma_f32_16x16x32_bf16 v[22:25], v[180:183], v[222:225], v[22:25]
	v_mfma_f32_16x16x32_bf16 v[18:21], v[188:191], v[222:225], v[18:21]
	v_mfma_f32_16x16x32_bf16 v[6:9], v[180:183], v[230:233], v[6:9]
	v_mfma_f32_16x16x32_bf16 v[2:5], v[188:191], v[230:233], v[2:5]
	s_setprio 1
	s_barrier
	s_add_i32 s8, 0, 0x18000
	v_add_u32_e32 v138, s8, v159
	s_add_i32 s9, 0, 0x1c000
	ds_read_b128 v[130:133], v138
	ds_read_b128 v[134:137], v138 offset:1024
	ds_read_b128 v[164:167], v138 offset:2048
	ds_read_b128 v[168:171], v138 offset:3072
	v_add_u32_e32 v138, s9, v159
	ds_read_b128 v[172:175], v138
	ds_read_b128 v[180:183], v138 offset:1024
	ds_read_b128 v[184:187], v138 offset:2048
	ds_read_b128 v[188:191], v138 offset:3072
	s_add_u32 s28, s70, 0x4000
	s_addc_u32 s29, s71, 0
	s_mov_b32 m0, s80
	v_lshl_add_u64 v[138:139], s[28:29], 0, v[146:147]
	ds_read_b128 v[192:195], v163 offset:32768
	ds_read_b128 v[198:201], v163 offset:33792
	ds_read_b128 v[202:205], v163 offset:34816
	ds_read_b128 v[206:209], v163 offset:35840
	ds_read_b128 v[218:221], v163 offset:36864
	ds_read_b128 v[222:225], v163 offset:37888
	ds_read_b128 v[226:229], v163 offset:38912
	ds_read_b128 v[230:233], v163 offset:39936
	global_load_lds_dwordx4 v[138:139], off
	v_lshl_add_u64 v[138:139], s[28:29], 0, v[150:151]
	s_mov_b32 m0, s81
	s_nop 0
	global_load_lds_dwordx4 v[138:139], off
	s_waitcnt vmcnt(8)
	s_waitcnt lgkmcnt(0)
	s_barrier
	s_setprio 0
	s_waitcnt lgkmcnt(0)
	v_mfma_f32_16x16x32_bf16 v[126:129], v[130:133], v[192:195], v[126:129]
	v_mfma_f32_16x16x32_bf16 v[122:125], v[164:167], v[192:195], v[122:125]
	v_mfma_f32_16x16x32_bf16 v[110:113], v[130:133], v[202:205], v[110:113]
	v_mfma_f32_16x16x32_bf16 v[106:109], v[164:167], v[202:205], v[106:109]
	v_mfma_f32_16x16x32_bf16 v[94:97], v[130:133], v[218:221], v[94:97]
	v_mfma_f32_16x16x32_bf16 v[90:93], v[164:167], v[218:221], v[90:93]
	v_mfma_f32_16x16x32_bf16 v[78:81], v[130:133], v[226:229], v[78:81]
	v_mfma_f32_16x16x32_bf16 v[74:77], v[164:167], v[226:229], v[74:77]
	v_mfma_f32_16x16x32_bf16 v[126:129], v[134:137], v[198:201], v[126:129]
	v_mfma_f32_16x16x32_bf16 v[122:125], v[168:171], v[198:201], v[122:125]
	v_mfma_f32_16x16x32_bf16 v[110:113], v[134:137], v[206:209], v[110:113]
	v_mfma_f32_16x16x32_bf16 v[106:109], v[168:171], v[206:209], v[106:109]
	v_mfma_f32_16x16x32_bf16 v[94:97], v[134:137], v[222:225], v[94:97]
	v_mfma_f32_16x16x32_bf16 v[90:93], v[168:171], v[222:225], v[90:93]
	v_mfma_f32_16x16x32_bf16 v[78:81], v[134:137], v[230:233], v[78:81]
	v_mfma_f32_16x16x32_bf16 v[74:77], v[168:171], v[230:233], v[74:77]
	s_setprio 1
	s_setprio 0
	v_mfma_f32_16x16x32_bf16 v[118:121], v[172:175], v[192:195], v[118:121]
	v_mfma_f32_16x16x32_bf16 v[114:117], v[184:187], v[192:195], v[114:117]
	v_mfma_f32_16x16x32_bf16 v[102:105], v[172:175], v[202:205], v[102:105]
	v_mfma_f32_16x16x32_bf16 v[98:101], v[184:187], v[202:205], v[98:101]
	v_mfma_f32_16x16x32_bf16 v[86:89], v[172:175], v[218:221], v[86:89]
	v_mfma_f32_16x16x32_bf16 v[82:85], v[184:187], v[218:221], v[82:85]
	v_mfma_f32_16x16x32_bf16 v[70:73], v[172:175], v[226:229], v[70:73]
	v_mfma_f32_16x16x32_bf16 v[66:69], v[184:187], v[226:229], v[66:69]
	v_mfma_f32_16x16x32_bf16 v[118:121], v[180:183], v[198:201], v[118:121]
	v_mfma_f32_16x16x32_bf16 v[114:117], v[188:191], v[198:201], v[114:117]
	v_mfma_f32_16x16x32_bf16 v[102:105], v[180:183], v[206:209], v[102:105]
	v_mfma_f32_16x16x32_bf16 v[98:101], v[188:191], v[206:209], v[98:101]
	v_mfma_f32_16x16x32_bf16 v[86:89], v[180:183], v[222:225], v[86:89]
	v_mfma_f32_16x16x32_bf16 v[82:85], v[188:191], v[222:225], v[82:85]
	v_mfma_f32_16x16x32_bf16 v[70:73], v[180:183], v[230:233], v[70:73]
	v_mfma_f32_16x16x32_bf16 v[66:69], v[188:191], v[230:233], v[66:69]
	s_setprio 1
	s_barrier
; #define PG8_STAGE(bufoff, gbase, voff) do { _Pragma("unroll") for (int _i = 0; _i < 2; ++_i) \
;         __builtin_amdgcn_global_load_lds((const unsigned*)((const char*)(gbase) + (voff)[_i]), (PG8_LAS unsigned*)(lds + (bufoff) + ldsw + _i * 8192), 16, 0, 0); } while (0)
; #define PG8_LDA(dst, b, h) do { _Pragma("unroll") for (int m = 0; m < 4; ++m) _Pragma("unroll") for (int k = 0; k < 2; ++k) dst[m][k] = *(const PG8_LAS bf16x8*)(lds + PG8_SA(b, h) + aoff + m * 2048 + k * 1024); } while (0)
; #define PG8_WAIT_V(n) asm volatile("s_waitcnt vmcnt(" #n ")" ::: "memory")
; #define PG8_WAIT_L(n) asm volatile("s_waitcnt lgkmcnt(" #n ")" ::: "memory")
; #define PG8_BAR __builtin_amdgcn_s_barrier()
; #define PG8_SCHED __builtin_amdgcn_sched_barrier(0)
; template <class Epi, class Sched, bool ALIGN_EPI = false, bool SP2 = false, bool I8 = false>
; __device__ __forceinline__ void gemm_phase(PG8_LAS unsigned char* lds, const Gemm g, const Sched& S, const Epi& E) {
;     ...
;             PG8_LDA(At, 1, 1); PG8_STAGE(PG8_SB(1, 0), b3, voffB); PG8_STAGE(PG8_SB(1, 1), b3 + hstepB, voffB); PG8_STAGE(PG8_SA(1, 0), a3, voffA);
;             PG8_WAIT_V(8); PG8_WAIT_L(0); PG8_BAR; PG8_MMA(1, 0, At, B0); PG8_MMA(1, 1, At, B1); PG8_BAR; PG8_SCHED;
	s_add_u32 s28, s34, 0x8000
	s_addc_u32 s29, s35, 0
	s_add_i32 s8, s8, s75
	v_lshl_add_u64 v[138:139], s[28:29], 0, v[148:149]
	s_mov_b32 m0, s8
	ds_read_b128 v[192:195], v163 offset:49152
	ds_read_b128 v[198:201], v163 offset:50176
	ds_read_b128 v[202:205], v163 offset:51200
	ds_read_b128 v[206:209], v163 offset:52224
	ds_read_b128 v[218:221], v163 offset:53248
	ds_read_b128 v[222:225], v163 offset:54272
	ds_read_b128 v[226:229], v163 offset:55296
	ds_read_b128 v[230:233], v163 offset:56320
	global_load_lds_dwordx4 v[138:139], off
	s_add_i32 m0, s8, 0x2000
	v_lshl_add_u64 v[138:139], s[28:29], 0, v[152:153]
	s_add_u32 s28, s34, 0xc000
	s_addc_u32 s29, s35, 0
	s_add_i32 s8, s9, s75
	global_load_lds_dwordx4 v[138:139], off
	v_lshl_add_u64 v[138:139], s[28:29], 0, v[148:149]
	s_mov_b32 m0, s8
	s_nop 0
	global_load_lds_dwordx4 v[138:139], off
	v_lshl_add_u64 v[138:139], s[28:29], 0, v[152:153]
	s_add_i32 m0, s8, 0x2000
	s_nop 0
	global_load_lds_dwordx4 v[138:139], off
	v_lshl_add_u64 v[138:139], s[26:27], 0, v[146:147]
	s_mov_b32 m0, s83
	s_nop 0
	global_load_lds_dwordx4 v[138:139], off
	v_lshl_add_u64 v[138:139], s[26:27], 0, v[150:151]
	s_mov_b32 m0, s84
	s_nop 0
	global_load_lds_dwordx4 v[138:139], off
	s_waitcnt vmcnt(8)
	s_waitcnt lgkmcnt(0)
	s_barrier
	s_setprio 0
	s_waitcnt lgkmcnt(0)
	v_mfma_f32_16x16x32_bf16 v[62:65], v[130:133], v[192:195], v[62:65]
	v_mfma_f32_16x16x32_bf16 v[58:61], v[164:167], v[192:195], v[58:61]
	v_mfma_f32_16x16x32_bf16 v[46:49], v[130:133], v[202:205], v[46:49]
	v_mfma_f32_16x16x32_bf16 v[42:45], v[164:167], v[202:205], v[42:45]
	v_mfma_f32_16x16x32_bf16 v[30:33], v[130:133], v[218:221], v[30:33]
	v_mfma_f32_16x16x32_bf16 v[26:29], v[164:167], v[218:221], v[26:29]
	v_mfma_f32_16x16x32_bf16 v[14:17], v[130:133], v[226:229], v[14:17]
	v_mfma_f32_16x16x32_bf16 v[10:13], v[164:167], v[226:229], v[10:13]
	v_mfma_f32_16x16x32_bf16 v[62:65], v[134:137], v[198:201], v[62:65]
	v_mfma_f32_16x16x32_bf16 v[58:61], v[168:171], v[198:201], v[58:61]
	v_mfma_f32_16x16x32_bf16 v[46:49], v[134:137], v[206:209], v[46:49]
	v_mfma_f32_16x16x32_bf16 v[42:45], v[168:171], v[206:209], v[42:45]
	v_mfma_f32_16x16x32_bf16 v[30:33], v[134:137], v[222:225], v[30:33]
	v_mfma_f32_16x16x32_bf16 v[26:29], v[168:171], v[222:225], v[26:29]
	v_mfma_f32_16x16x32_bf16 v[14:17], v[134:137], v[230:233], v[14:17]
	v_mfma_f32_16x16x32_bf16 v[10:13], v[168:171], v[230:233], v[10:13]
	s_setprio 1
	s_setprio 0
	v_mfma_f32_16x16x32_bf16 v[54:57], v[172:175], v[192:195], v[54:57]
	v_mfma_f32_16x16x32_bf16 v[50:53], v[184:187], v[192:195], v[50:53]
	v_mfma_f32_16x16x32_bf16 v[38:41], v[172:175], v[202:205], v[38:41]
	v_mfma_f32_16x16x32_bf16 v[34:37], v[184:187], v[202:205], v[34:37]
	v_mfma_f32_16x16x32_bf16 v[22:25], v[172:175], v[218:221], v[22:25]
	v_mfma_f32_16x16x32_bf16 v[18:21], v[184:187], v[218:221], v[18:21]
	v_mfma_f32_16x16x32_bf16 v[6:9], v[172:175], v[226:229], v[6:9]
	v_mfma_f32_16x16x32_bf16 v[2:5], v[184:187], v[226:229], v[2:5]
	v_mfma_f32_16x16x32_bf16 v[54:57], v[180:183], v[198:201], v[54:57]
	v_mfma_f32_16x16x32_bf16 v[50:53], v[188:191], v[198:201], v[50:53]
	v_mfma_f32_16x16x32_bf16 v[38:41], v[180:183], v[206:209], v[38:41]
	v_mfma_f32_16x16x32_bf16 v[34:37], v[188:191], v[206:209], v[34:37]
	v_mfma_f32_16x16x32_bf16 v[22:25], v[180:183], v[222:225], v[22:25]
	v_mfma_f32_16x16x32_bf16 v[18:21], v[188:191], v[222:225], v[18:21]
	v_mfma_f32_16x16x32_bf16 v[6:9], v[180:183], v[230:233], v[6:9]
	v_mfma_f32_16x16x32_bf16 v[2:5], v[188:191], v[230:233], v[2:5]
	s_setprio 1
	s_barrier
	s_add_i32 s89, s89, 2
	s_add_u32 s24, s24, 0x10000
	s_addc_u32 s25, s25, 0
	s_add_u32 vcc_lo, vcc_lo, 0x10000
	s_addc_u32 vcc_hi, vcc_hi, 0
	s_cmp_gt_u32 s89, 61
	s_cbranch_scc0 .LBB0_316
	s_and_b64 vcc, exec, s[14:15]
	s_cbranch_vccz .LBB0_319
	s_barrier

; #define PG8_STAGE(bufoff, gbase, voff) do { _Pragma("unroll") for (int _i = 0; _i < 2; ++_i) \
;         __builtin_amdgcn_global_load_lds((const unsigned*)((const char*)(gbase) + (voff)[_i]), (PG8_LAS unsigned*)(lds + (bufoff) + ldsw + _i * 8192), 16, 0, 0); } while (0)
; #define PG8_LDA(dst, b, h) do { _Pragma("unroll") for (int m = 0; m < 4; ++m) _Pragma("unroll") for (int k = 0; k < 2; ++k) dst[m][k] = *(const PG8_LAS bf16x8*)(lds + PG8_SA(b, h) + aoff + m * 2048 + k * 1024); } while (0)
; #define PG8_LDB(dst, b, h) do { _Pragma("unroll") for (int n = 0; n < 2; ++n) _Pragma("unroll") for (int k = 0; k < 2; ++k) dst[n][k] = *(const PG8_LAS bf16x8*)(lds + PG8_SB(b, h) + boff + n * 2048 + k * 1024); } while (0)
; #define PG8_WAIT_V(n) asm volatile("s_waitcnt vmcnt(" #n ")" ::: "memory")
; #define PG8_WAIT_L(n) asm volatile("s_waitcnt lgkmcnt(" #n ")" ::: "memory")
; #define PG8_BAR __builtin_amdgcn_s_barrier()
; #define PG8_SCHED __builtin_amdgcn_sched_barrier(0)
; template <class Epi, class Sched, bool ALIGN_EPI = false, bool SP2 = false, bool I8 = false>
; __device__ __forceinline__ void gemm_phase(PG8_LAS unsigned char* lds, const Gemm g, const Sched& S, const Epi& E) {
;     ...
;             PG8_LDB(B0, 0, 0); PG8_LDB(B1, 0, 1); PG8_SCHED; PG8_LDA(At, 0, 0); PG8_STAGE(PG8_SA(1, 1), a1 + hstepA, voffA);
;             PG8_WAIT_V(8); PG8_WAIT_L(0); PG8_BAR; PG8_MMA(0, 0, At, B0); PG8_MMA(0, 1, At, B1); PG8_BAR; PG8_SCHED;
;             PG8_LDA(At, 0, 1); PG8_STAGE(PG8_SB(0, 0), b2, voffB); PG8_STAGE(PG8_SB(0, 1), b2 + hstepB, voffB); PG8_STAGE(PG8_SA(0, 0), a2, voffA);
.LBB0_682:
	ds_read_b128 v[156:159], v153
	ds_read_b128 v[160:163], v153 offset:1024
	ds_read_b128 v[164:167], v153 offset:2048
	ds_read_b128 v[168:171], v153 offset:3072
	ds_read_b128 v[172:175], v154
	ds_read_b128 v[176:179], v154 offset:1024
	ds_read_b128 v[180:183], v154 offset:2048
	ds_read_b128 v[184:187], v154 offset:3072
	s_add_u32 s20, s18, 0x4000
	s_addc_u32 s21, s19, 0
	s_cmp_eq_u32 s83, 60
	s_cselect_b32 s24, s79, s20
	s_cselect_b32 s25, s11, s21
	s_cselect_b32 s22, s80, s81
	s_cselect_b32 s23, s9, s82
	s_add_u32 s20, s24, 0x8000
	s_addc_u32 s21, s25, 0
	v_lshl_add_u64 v[148:149], s[18:19], 0, v[140:141]
	s_add_i32 m0, s17, 0xc000
	ds_read_b128 v[188:191], v155
	ds_read_b128 v[192:195], v155 offset:1024
	ds_read_b128 v[198:201], v155 offset:2048
	ds_read_b128 v[202:205], v155 offset:3072
	ds_read_b128 v[206:209], v155 offset:4096
	ds_read_b128 v[218:221], v155 offset:5120
	ds_read_b128 v[222:225], v155 offset:6144
	ds_read_b128 v[226:229], v155 offset:7168
	global_load_lds_dwordx4 v[148:149], off
	v_lshl_add_u64 v[148:149], s[18:19], 0, v[142:143]
	s_add_i32 m0, s17, 0xe000
	s_nop 0
	global_load_lds_dwordx4 v[148:149], off
	s_waitcnt vmcnt(8)
	s_waitcnt lgkmcnt(0)
	s_barrier
	s_setprio 0
	s_waitcnt lgkmcnt(0)
	v_mfma_f32_16x16x32_bf16 v[126:129], v[156:159], v[188:191], v[126:129]
	v_mfma_f32_16x16x32_bf16 v[122:125], v[164:167], v[188:191], v[122:125]
	v_mfma_f32_16x16x32_bf16 v[118:121], v[156:159], v[198:201], v[118:121]
	v_mfma_f32_16x16x32_bf16 v[110:113], v[164:167], v[198:201], v[110:113]
	v_mfma_f32_16x16x32_bf16 v[102:105], v[156:159], v[206:209], v[102:105]
	v_mfma_f32_16x16x32_bf16 v[94:97], v[164:167], v[206:209], v[94:97]
	v_mfma_f32_16x16x32_bf16 v[86:89], v[156:159], v[222:225], v[86:89]
	v_mfma_f32_16x16x32_bf16 v[78:81], v[164:167], v[222:225], v[78:81]
	v_mfma_f32_16x16x32_bf16 v[126:129], v[160:163], v[192:195], v[126:129]
	v_mfma_f32_16x16x32_bf16 v[122:125], v[168:171], v[192:195], v[122:125]
	v_mfma_f32_16x16x32_bf16 v[118:121], v[160:163], v[202:205], v[118:121]
	v_mfma_f32_16x16x32_bf16 v[110:113], v[168:171], v[202:205], v[110:113]
	v_mfma_f32_16x16x32_bf16 v[102:105], v[160:163], v[218:221], v[102:105]
	v_mfma_f32_16x16x32_bf16 v[94:97], v[168:171], v[218:221], v[94:97]
	v_mfma_f32_16x16x32_bf16 v[86:89], v[160:163], v[226:229], v[86:89]
	v_mfma_f32_16x16x32_bf16 v[78:81], v[168:171], v[226:229], v[78:81]
	s_setprio 1
	s_setprio 0
	v_mfma_f32_16x16x32_bf16 v[114:117], v[172:175], v[188:191], v[114:117]
	v_mfma_f32_16x16x32_bf16 v[106:109], v[180:183], v[188:191], v[106:109]
	v_mfma_f32_16x16x32_bf16 v[98:101], v[172:175], v[198:201], v[98:101]
	v_mfma_f32_16x16x32_bf16 v[90:93], v[180:183], v[198:201], v[90:93]
	v_mfma_f32_16x16x32_bf16 v[82:85], v[172:175], v[206:209], v[82:85]
	v_mfma_f32_16x16x32_bf16 v[74:77], v[180:183], v[206:209], v[74:77]
	v_mfma_f32_16x16x32_bf16 v[70:73], v[172:175], v[222:225], v[70:73]
	v_mfma_f32_16x16x32_bf16 v[66:69], v[180:183], v[222:225], v[66:69]
	v_mfma_f32_16x16x32_bf16 v[114:117], v[176:179], v[192:195], v[114:117]
	v_mfma_f32_16x16x32_bf16 v[106:109], v[184:187], v[192:195], v[106:109]
	v_mfma_f32_16x16x32_bf16 v[98:101], v[176:179], v[202:205], v[98:101]
	v_mfma_f32_16x16x32_bf16 v[90:93], v[184:187], v[202:205], v[90:93]
	v_mfma_f32_16x16x32_bf16 v[82:85], v[176:179], v[218:221], v[82:85]
	v_mfma_f32_16x16x32_bf16 v[74:77], v[184:187], v[218:221], v[74:77]
	v_mfma_f32_16x16x32_bf16 v[70:73], v[176:179], v[226:229], v[70:73]
	v_mfma_f32_16x16x32_bf16 v[66:69], v[184:187], v[226:229], v[66:69]
	s_setprio 1
	s_barrier
	s_add_i32 s84, s76, s26
	v_lshl_add_u64 v[148:149], s[22:23], 0, v[136:137]
	s_mov_b32 m0, s84
	ds_read_b128 v[188:191], v155 offset:16384
	ds_read_b128 v[192:195], v155 offset:17408
	ds_read_b128 v[198:201], v155 offset:18432
	ds_read_b128 v[202:205], v155 offset:19456
	ds_read_b128 v[206:209], v155 offset:20480
	ds_read_b128 v[218:221], v155 offset:21504
	ds_read_b128 v[222:225], v155 offset:22528
	ds_read_b128 v[226:229], v155 offset:23552
	global_load_lds_dwordx4 v[148:149], off
	s_add_i32 m0, s84, 0x2000
	s_add_u32 s84, s22, 0x4000
	v_lshl_add_u64 v[148:149], s[22:23], 0, v[132:133]
	s_addc_u32 s85, s23, 0
	s_add_i32 s86, s77, s26
	global_load_lds_dwordx4 v[148:149], off
	v_lshl_add_u64 v[148:149], s[84:85], 0, v[136:137]
	s_mov_b32 m0, s86
	s_nop 0
	global_load_lds_dwordx4 v[148:149], off
	v_lshl_add_u64 v[148:149], s[84:85], 0, v[132:133]
	s_add_i32 m0, s86, 0x2000
	s_nop 0
	global_load_lds_dwordx4 v[148:149], off
	v_lshl_add_u64 v[148:149], s[24:25], 0, v[138:139]
	s_mov_b32 m0, s17
	s_nop 0
	global_load_lds_dwordx4 v[148:149], off
	v_lshl_add_u64 v[148:149], s[24:25], 0, v[134:135]
	s_mov_b32 m0, s29
	s_nop 0
	global_load_lds_dwordx4 v[148:149], off
	s_waitcnt vmcnt(8)
	s_waitcnt lgkmcnt(0)
	s_barrier
; #define PG8_STAGE(bufoff, gbase, voff) do { _Pragma("unroll") for (int _i = 0; _i < 2; ++_i) \
;         __builtin_amdgcn_global_load_lds((const unsigned*)((const char*)(gbase) + (voff)[_i]), (PG8_LAS unsigned*)(lds + (bufoff) + ldsw + _i * 8192), 16, 0, 0); } while (0)
; #define PG8_LDA(dst, b, h) do { _Pragma("unroll") for (int m = 0; m < 4; ++m) _Pragma("unroll") for (int k = 0; k < 2; ++k) dst[m][k] = *(const PG8_LAS bf16x8*)(lds + PG8_SA(b, h) + aoff + m * 2048 + k * 1024); } while (0)
; #define PG8_LDB(dst, b, h) do { _Pragma("unroll") for (int n = 0; n < 2; ++n) _Pragma("unroll") for (int k = 0; k < 2; ++k) dst[n][k] = *(const PG8_LAS bf16x8*)(lds + PG8_SB(b, h) + boff + n * 2048 + k * 1024); } while (0)
; #define PG8_WAIT_V(n) asm volatile("s_waitcnt vmcnt(" #n ")" ::: "memory")
; #define PG8_WAIT_L(n) asm volatile("s_waitcnt lgkmcnt(" #n ")" ::: "memory")
; #define PG8_BAR __builtin_amdgcn_s_barrier()
; #define PG8_SCHED __builtin_amdgcn_sched_barrier(0)
; template <class Epi, class Sched, bool ALIGN_EPI = false, bool SP2 = false, bool I8 = false>
; __device__ __forceinline__ void gemm_phase(PG8_LAS unsigned char* lds, const Gemm g, const Sched& S, const Epi& E) {
;     ...
;             PG8_WAIT_V(8); PG8_WAIT_L(0); PG8_BAR; PG8_MMA(1, 0, At, B0); PG8_MMA(1, 1, At, B1); PG8_BAR; PG8_SCHED;
;             PG8_LDB(B0, 1, 0); PG8_LDB(B1, 1, 1); PG8_SCHED; PG8_LDA(At, 1, 0); PG8_STAGE(PG8_SA(0, 1), a2 + hstepA, voffA);
;             PG8_WAIT_V(8); PG8_WAIT_L(0); PG8_BAR; PG8_MMA(0, 0, At, B0); PG8_MMA(0, 1, At, B1); PG8_BAR; PG8_SCHED;
	s_setprio 0
	s_waitcnt lgkmcnt(0)
	v_mfma_f32_16x16x32_bf16 v[62:65], v[156:159], v[188:191], v[62:65]
	v_mfma_f32_16x16x32_bf16 v[58:61], v[164:167], v[188:191], v[58:61]
	v_mfma_f32_16x16x32_bf16 v[54:57], v[156:159], v[198:201], v[54:57]
	v_mfma_f32_16x16x32_bf16 v[46:49], v[164:167], v[198:201], v[46:49]
	v_mfma_f32_16x16x32_bf16 v[38:41], v[156:159], v[206:209], v[38:41]
	v_mfma_f32_16x16x32_bf16 v[30:33], v[164:167], v[206:209], v[30:33]
	v_mfma_f32_16x16x32_bf16 v[22:25], v[156:159], v[222:225], v[22:25]
	v_mfma_f32_16x16x32_bf16 v[14:17], v[164:167], v[222:225], v[14:17]
	v_mfma_f32_16x16x32_bf16 v[62:65], v[160:163], v[192:195], v[62:65]
	v_mfma_f32_16x16x32_bf16 v[58:61], v[168:171], v[192:195], v[58:61]
	v_mfma_f32_16x16x32_bf16 v[54:57], v[160:163], v[202:205], v[54:57]
	v_mfma_f32_16x16x32_bf16 v[46:49], v[168:171], v[202:205], v[46:49]
	v_mfma_f32_16x16x32_bf16 v[38:41], v[160:163], v[218:221], v[38:41]
	v_mfma_f32_16x16x32_bf16 v[30:33], v[168:171], v[218:221], v[30:33]
	v_mfma_f32_16x16x32_bf16 v[22:25], v[160:163], v[226:229], v[22:25]
	v_mfma_f32_16x16x32_bf16 v[14:17], v[168:171], v[226:229], v[14:17]
	s_setprio 1
	s_setprio 0
	v_mfma_f32_16x16x32_bf16 v[50:53], v[172:175], v[188:191], v[50:53]
	v_mfma_f32_16x16x32_bf16 v[42:45], v[180:183], v[188:191], v[42:45]
	v_mfma_f32_16x16x32_bf16 v[34:37], v[172:175], v[198:201], v[34:37]
	v_mfma_f32_16x16x32_bf16 v[26:29], v[180:183], v[198:201], v[26:29]
	v_mfma_f32_16x16x32_bf16 v[18:21], v[172:175], v[206:209], v[18:21]
	v_mfma_f32_16x16x32_bf16 v[10:13], v[180:183], v[206:209], v[10:13]
	v_mfma_f32_16x16x32_bf16 v[6:9], v[172:175], v[222:225], v[6:9]
	v_mfma_f32_16x16x32_bf16 v[2:5], v[180:183], v[222:225], v[2:5]
	v_mfma_f32_16x16x32_bf16 v[50:53], v[176:179], v[192:195], v[50:53]
	v_mfma_f32_16x16x32_bf16 v[42:45], v[184:187], v[192:195], v[42:45]
	v_mfma_f32_16x16x32_bf16 v[34:37], v[176:179], v[202:205], v[34:37]
	v_mfma_f32_16x16x32_bf16 v[26:29], v[184:187], v[202:205], v[26:29]
	v_mfma_f32_16x16x32_bf16 v[18:21], v[176:179], v[218:221], v[18:21]
	v_mfma_f32_16x16x32_bf16 v[10:13], v[184:187], v[218:221], v[10:13]
	v_mfma_f32_16x16x32_bf16 v[6:9], v[176:179], v[226:229], v[6:9]
	v_mfma_f32_16x16x32_bf16 v[2:5], v[184:187], v[226:229], v[2:5]
	s_setprio 1
	s_barrier
	s_add_i32 s84, 0, 0x18000
	v_add_u32_e32 v148, s84, v151
	s_add_i32 s85, 0, 0x1c000
	ds_read_b128 v[156:159], v148
	ds_read_b128 v[160:163], v148 offset:1024
	ds_read_b128 v[164:167], v148 offset:2048
	ds_read_b128 v[168:171], v148 offset:3072
	v_add_u32_e32 v148, s85, v151
	ds_read_b128 v[172:175], v148
	ds_read_b128 v[176:179], v148 offset:1024
	ds_read_b128 v[180:183], v148 offset:2048
	ds_read_b128 v[184:187], v148 offset:3072
	s_add_u32 s24, s24, 0x4000
	s_addc_u32 s25, s25, 0
	s_mov_b32 m0, s34
	v_lshl_add_u64 v[148:149], s[24:25], 0, v[138:139]
	ds_read_b128 v[188:191], v155 offset:32768
	ds_read_b128 v[192:195], v155 offset:33792
	ds_read_b128 v[198:201], v155 offset:34816
	ds_read_b128 v[202:205], v155 offset:35840
	ds_read_b128 v[206:209], v155 offset:36864
	ds_read_b128 v[218:221], v155 offset:37888
	ds_read_b128 v[222:225], v155 offset:38912
	ds_read_b128 v[226:229], v155 offset:39936
	global_load_lds_dwordx4 v[148:149], off
	v_lshl_add_u64 v[148:149], s[24:25], 0, v[134:135]
	s_mov_b32 m0, s35
	s_nop 0
	global_load_lds_dwordx4 v[148:149], off
	s_waitcnt vmcnt(8)
	s_waitcnt lgkmcnt(0)
	s_barrier
	s_setprio 0
	s_waitcnt lgkmcnt(0)
	v_mfma_f32_16x16x32_bf16 v[126:129], v[156:159], v[188:191], v[126:129]
	v_mfma_f32_16x16x32_bf16 v[122:125], v[164:167], v[188:191], v[122:125]
	v_mfma_f32_16x16x32_bf16 v[118:121], v[156:159], v[198:201], v[118:121]
	v_mfma_f32_16x16x32_bf16 v[110:113], v[164:167], v[198:201], v[110:113]
	v_mfma_f32_16x16x32_bf16 v[102:105], v[156:159], v[206:209], v[102:105]
	v_mfma_f32_16x16x32_bf16 v[94:97], v[164:167], v[206:209], v[94:97]
	v_mfma_f32_16x16x32_bf16 v[86:89], v[156:159], v[222:225], v[86:89]
	v_mfma_f32_16x16x32_bf16 v[78:81], v[164:167], v[222:225], v[78:81]
	v_mfma_f32_16x16x32_bf16 v[126:129], v[160:163], v[192:195], v[126:129]
	v_mfma_f32_16x16x32_bf16 v[122:125], v[168:171], v[192:195], v[122:125]
	v_mfma_f32_16x16x32_bf16 v[118:121], v[160:163], v[202:205], v[118:121]
	v_mfma_f32_16x16x32_bf16 v[110:113], v[168:171], v[202:205], v[110:113]
	v_mfma_f32_16x16x32_bf16 v[102:105], v[160:163], v[218:221], v[102:105]
	v_mfma_f32_16x16x32_bf16 v[94:97], v[168:171], v[218:221], v[94:97]
	v_mfma_f32_16x16x32_bf16 v[86:89], v[160:163], v[226:229], v[86:89]
	v_mfma_f32_16x16x32_bf16 v[78:81], v[168:171], v[226:229], v[78:81]
	s_setprio 1
	s_setprio 0
	v_mfma_f32_16x16x32_bf16 v[114:117], v[172:175], v[188:191], v[114:117]
	v_mfma_f32_16x16x32_bf16 v[106:109], v[180:183], v[188:191], v[106:109]
	v_mfma_f32_16x16x32_bf16 v[98:101], v[172:175], v[198:201], v[98:101]
	v_mfma_f32_16x16x32_bf16 v[90:93], v[180:183], v[198:201], v[90:93]
	v_mfma_f32_16x16x32_bf16 v[82:85], v[172:175], v[206:209], v[82:85]
	v_mfma_f32_16x16x32_bf16 v[74:77], v[180:183], v[206:209], v[74:77]
	v_mfma_f32_16x16x32_bf16 v[70:73], v[172:175], v[222:225], v[70:73]
	v_mfma_f32_16x16x32_bf16 v[66:69], v[180:183], v[222:225], v[66:69]
	v_mfma_f32_16x16x32_bf16 v[114:117], v[176:179], v[192:195], v[114:117]
	v_mfma_f32_16x16x32_bf16 v[106:109], v[184:187], v[192:195], v[106:109]
	v_mfma_f32_16x16x32_bf16 v[98:101], v[176:179], v[202:205], v[98:101]
	v_mfma_f32_16x16x32_bf16 v[90:93], v[184:187], v[202:205], v[90:93]
	v_mfma_f32_16x16x32_bf16 v[82:85], v[176:179], v[218:221], v[82:85]
	v_mfma_f32_16x16x32_bf16 v[74:77], v[184:187], v[218:221], v[74:77]
	v_mfma_f32_16x16x32_bf16 v[70:73], v[176:179], v[226:229], v[70:73]
	v_mfma_f32_16x16x32_bf16 v[66:69], v[184:187], v[226:229], v[66:69]
	s_setprio 1
	s_barrier
; #define PG8_STAGE(bufoff, gbase, voff) do { _Pragma("unroll") for (int _i = 0; _i < 2; ++_i) \
;         __builtin_amdgcn_global_load_lds((const unsigned*)((const char*)(gbase) + (voff)[_i]), (PG8_LAS unsigned*)(lds + (bufoff) + ldsw + _i * 8192), 16, 0, 0); } while (0)
; #define PG8_LDA(dst, b, h) do { _Pragma("unroll") for (int m = 0; m < 4; ++m) _Pragma("unroll") for (int k = 0; k < 2; ++k) dst[m][k] = *(const PG8_LAS bf16x8*)(lds + PG8_SA(b, h) + aoff + m * 2048 + k * 1024); } while (0)
; #define PG8_WAIT_V(n) asm volatile("s_waitcnt vmcnt(" #n ")" ::: "memory")
; #define PG8_WAIT_L(n) asm volatile("s_waitcnt lgkmcnt(" #n ")" ::: "memory")
; #define PG8_BAR __builtin_amdgcn_s_barrier()
; #define PG8_SCHED __builtin_amdgcn_sched_barrier(0)
; template <class Epi, class Sched, bool ALIGN_EPI = false, bool SP2 = false, bool I8 = false>
; __device__ __forceinline__ void gemm_phase(PG8_LAS unsigned char* lds, const Gemm g, const Sched& S, const Epi& E) {
;     ...
;             PG8_LDA(At, 1, 1); PG8_STAGE(PG8_SB(1, 0), b3, voffB); PG8_STAGE(PG8_SB(1, 1), b3 + hstepB, voffB); PG8_STAGE(PG8_SA(1, 0), a3, voffA);
;             PG8_WAIT_V(8); PG8_WAIT_L(0); PG8_BAR; PG8_MMA(1, 0, At, B0); PG8_MMA(1, 1, At, B1); PG8_BAR; PG8_SCHED;
	s_add_u32 s24, s22, 0x8000
	s_addc_u32 s25, s23, 0
	s_add_i32 s84, s84, s26
	v_lshl_add_u64 v[148:149], s[24:25], 0, v[136:137]
	s_mov_b32 m0, s84
	ds_read_b128 v[188:191], v155 offset:49152
	ds_read_b128 v[192:195], v155 offset:50176
	ds_read_b128 v[198:201], v155 offset:51200
	ds_read_b128 v[202:205], v155 offset:52224
	ds_read_b128 v[206:209], v155 offset:53248
	ds_read_b128 v[218:221], v155 offset:54272
	ds_read_b128 v[222:225], v155 offset:55296
	ds_read_b128 v[226:229], v155 offset:56320
	global_load_lds_dwordx4 v[148:149], off
	s_add_i32 m0, s84, 0x2000
	s_add_u32 s22, s22, 0xc000
	v_lshl_add_u64 v[148:149], s[24:25], 0, v[132:133]
	s_addc_u32 s23, s23, 0
	s_add_i32 s24, s85, s26
	global_load_lds_dwordx4 v[148:149], off
	v_lshl_add_u64 v[148:149], s[22:23], 0, v[136:137]
	s_mov_b32 m0, s24
	s_nop 0
	global_load_lds_dwordx4 v[148:149], off
	v_lshl_add_u64 v[148:149], s[22:23], 0, v[132:133]
	s_add_i32 m0, s24, 0x2000
	s_nop 0
	global_load_lds_dwordx4 v[148:149], off
	v_lshl_add_u64 v[148:149], s[20:21], 0, v[138:139]
	s_mov_b32 m0, s71
	s_nop 0
	global_load_lds_dwordx4 v[148:149], off
	v_lshl_add_u64 v[148:149], s[20:21], 0, v[134:135]
	s_mov_b32 m0, s72
	s_nop 0
	global_load_lds_dwordx4 v[148:149], off
	s_waitcnt vmcnt(8)
	s_waitcnt lgkmcnt(0)
	s_barrier
	s_setprio 0
	s_waitcnt lgkmcnt(0)
	v_mfma_f32_16x16x32_bf16 v[62:65], v[156:159], v[188:191], v[62:65]
	v_mfma_f32_16x16x32_bf16 v[58:61], v[164:167], v[188:191], v[58:61]
	v_mfma_f32_16x16x32_bf16 v[54:57], v[156:159], v[198:201], v[54:57]
	v_mfma_f32_16x16x32_bf16 v[46:49], v[164:167], v[198:201], v[46:49]
	v_mfma_f32_16x16x32_bf16 v[38:41], v[156:159], v[206:209], v[38:41]
	v_mfma_f32_16x16x32_bf16 v[30:33], v[164:167], v[206:209], v[30:33]
	v_mfma_f32_16x16x32_bf16 v[22:25], v[156:159], v[222:225], v[22:25]
	v_mfma_f32_16x16x32_bf16 v[14:17], v[164:167], v[222:225], v[14:17]
	v_mfma_f32_16x16x32_bf16 v[62:65], v[160:163], v[192:195], v[62:65]
	v_mfma_f32_16x16x32_bf16 v[58:61], v[168:171], v[192:195], v[58:61]
	v_mfma_f32_16x16x32_bf16 v[54:57], v[160:163], v[202:205], v[54:57]
	v_mfma_f32_16x16x32_bf16 v[46:49], v[168:171], v[202:205], v[46:49]
	v_mfma_f32_16x16x32_bf16 v[38:41], v[160:163], v[218:221], v[38:41]
	v_mfma_f32_16x16x32_bf16 v[30:33], v[168:171], v[218:221], v[30:33]
	v_mfma_f32_16x16x32_bf16 v[22:25], v[160:163], v[226:229], v[22:25]
	v_mfma_f32_16x16x32_bf16 v[14:17], v[168:171], v[226:229], v[14:17]
	s_setprio 1
	s_setprio 0
	v_mfma_f32_16x16x32_bf16 v[50:53], v[172:175], v[188:191], v[50:53]
	v_mfma_f32_16x16x32_bf16 v[42:45], v[180:183], v[188:191], v[42:45]
	v_mfma_f32_16x16x32_bf16 v[34:37], v[172:175], v[198:201], v[34:37]
	v_mfma_f32_16x16x32_bf16 v[26:29], v[180:183], v[198:201], v[26:29]
	v_mfma_f32_16x16x32_bf16 v[18:21], v[172:175], v[206:209], v[18:21]
	v_mfma_f32_16x16x32_bf16 v[10:13], v[180:183], v[206:209], v[10:13]
	v_mfma_f32_16x16x32_bf16 v[6:9], v[172:175], v[222:225], v[6:9]
	v_mfma_f32_16x16x32_bf16 v[2:5], v[180:183], v[222:225], v[2:5]
	v_mfma_f32_16x16x32_bf16 v[50:53], v[176:179], v[192:195], v[50:53]
	v_mfma_f32_16x16x32_bf16 v[42:45], v[184:187], v[192:195], v[42:45]
	v_mfma_f32_16x16x32_bf16 v[34:37], v[176:179], v[202:205], v[34:37]
	v_mfma_f32_16x16x32_bf16 v[26:29], v[184:187], v[202:205], v[26:29]
	v_mfma_f32_16x16x32_bf16 v[18:21], v[176:179], v[218:221], v[18:21]
	v_mfma_f32_16x16x32_bf16 v[10:13], v[184:187], v[218:221], v[10:13]
	v_mfma_f32_16x16x32_bf16 v[6:9], v[176:179], v[226:229], v[6:9]
	v_mfma_f32_16x16x32_bf16 v[2:5], v[184:187], v[226:229], v[2:5]
	s_setprio 1
	s_barrier
	s_add_i32 s83, s83, 2
	s_add_u32 s18, s18, 0x10000
	s_addc_u32 s19, s19, 0
	s_add_u32 s81, s81, 0x10000
	s_addc_u32 s82, s82, 0
	s_cmp_gt_u32 s83, 61
	s_cbranch_scc0 .LBB0_682
	s_and_b64 vcc, exec, s[6:7]
	s_cbranch_vccz .LBB0_685
	s_barrier

; #define PG8_STAGE(bufoff, gbase, voff) do { _Pragma("unroll") for (int _i = 0; _i < 2; ++_i) \
;         __builtin_amdgcn_global_load_lds((const unsigned*)((const char*)(gbase) + (voff)[_i]), (PG8_LAS unsigned*)(lds + (bufoff) + ldsw + _i * 8192), 16, 0, 0); } while (0)
; #define PG8_LDA(dst, b, h) do { _Pragma("unroll") for (int m = 0; m < 4; ++m) _Pragma("unroll") for (int k = 0; k < 2; ++k) dst[m][k] = *(const PG8_LAS bf16x8*)(lds + PG8_SA(b, h) + aoff + m * 2048 + k * 1024); } while (0)
; #define PG8_LDB(dst, b, h) do { _Pragma("unroll") for (int n = 0; n < 2; ++n) _Pragma("unroll") for (int k = 0; k < 2; ++k) dst[n][k] = *(const PG8_LAS bf16x8*)(lds + PG8_SB(b, h) + boff + n * 2048 + k * 1024); } while (0)
; #define PG8_WAIT_V(n) asm volatile("s_waitcnt vmcnt(" #n ")" ::: "memory")
; #define PG8_WAIT_L(n) asm volatile("s_waitcnt lgkmcnt(" #n ")" ::: "memory")
; #define PG8_BAR __builtin_amdgcn_s_barrier()
; #define PG8_SCHED __builtin_amdgcn_sched_barrier(0)
; template <class Epi, class Sched, bool ALIGN_EPI = false, bool SP2 = false, bool I8 = false>
; __device__ __forceinline__ void gemm_phase(PG8_LAS unsigned char* lds, const Gemm g, const Sched& S, const Epi& E) {
;     ...
;             PG8_LDB(B0, 0, 0); PG8_LDB(B1, 0, 1); PG8_SCHED; PG8_LDA(At, 0, 0); PG8_STAGE(PG8_SA(1, 1), a1 + hstepA, voffA);
;             PG8_WAIT_V(8); PG8_WAIT_L(0); PG8_BAR; PG8_MMA(0, 0, At, B0); PG8_MMA(0, 1, At, B1); PG8_BAR; PG8_SCHED;
;             PG8_LDA(At, 0, 1); PG8_STAGE(PG8_SB(0, 0), b2, voffB); PG8_STAGE(PG8_SB(0, 1), b2 + hstepB, voffB); PG8_STAGE(PG8_SA(0, 0), a2, voffA);
.LBB0_865:
	ds_read_b128 v[154:157], v170
	ds_read_b128 v[158:161], v170 offset:1024
	ds_read_b128 v[162:165], v170 offset:2048
	ds_read_b128 v[174:177], v170 offset:3072
	ds_read_b128 v[178:181], v171
	ds_read_b128 v[182:185], v171 offset:1024
	ds_read_b128 v[186:189], v171 offset:2048
	ds_read_b128 v[190:193], v171 offset:3072
	s_add_u32 s20, s18, 0x4000
	s_addc_u32 s21, s19, 0
	s_cmp_eq_u32 s73, 60
	s_cselect_b32 s24, s17, s20
	s_cselect_b32 s25, s9, s21
	s_cselect_b32 s22, s70, s71
	s_cselect_b32 s23, s7, s72
	s_add_u32 s20, s24, 0x8000
	s_addc_u32 s21, s25, 0
	v_lshl_add_u64 v[194:195], s[18:19], 0, v[144:145]
	s_add_i32 m0, s15, 0xc000
	ds_read_b128 v[198:201], v172
	ds_read_b128 v[202:205], v172 offset:1024
	ds_read_b128 v[206:209], v172 offset:2048
	ds_read_b128 v[218:221], v172 offset:3072
	ds_read_b128 v[222:225], v172 offset:4096
	ds_read_b128 v[226:229], v172 offset:5120
	ds_read_b128 v[230:233], v172 offset:6144
	ds_read_b128 v[234:237], v172 offset:7168
	global_load_lds_dwordx4 v[194:195], off
	v_lshl_add_u64 v[194:195], s[18:19], 0, v[146:147]
	s_add_i32 m0, s15, 0xe000
	s_nop 0
	global_load_lds_dwordx4 v[194:195], off
	s_waitcnt vmcnt(8)
	s_waitcnt lgkmcnt(0)
	s_barrier
	s_setprio 0
	s_waitcnt lgkmcnt(0)
	v_mfma_f32_16x16x32_bf16 v[126:129], v[154:157], v[198:201], v[126:129]
	v_mfma_f32_16x16x32_bf16 v[122:125], v[162:165], v[198:201], v[122:125]
	v_mfma_f32_16x16x32_bf16 v[114:117], v[154:157], v[206:209], v[114:117]
	v_mfma_f32_16x16x32_bf16 v[106:109], v[162:165], v[206:209], v[106:109]
	v_mfma_f32_16x16x32_bf16 v[98:101], v[154:157], v[222:225], v[98:101]
	v_mfma_f32_16x16x32_bf16 v[90:93], v[162:165], v[222:225], v[90:93]
	v_mfma_f32_16x16x32_bf16 v[82:85], v[154:157], v[230:233], v[82:85]
	v_mfma_f32_16x16x32_bf16 v[74:77], v[162:165], v[230:233], v[74:77]
	v_mfma_f32_16x16x32_bf16 v[126:129], v[158:161], v[202:205], v[126:129]
	v_mfma_f32_16x16x32_bf16 v[122:125], v[174:177], v[202:205], v[122:125]
	v_mfma_f32_16x16x32_bf16 v[114:117], v[158:161], v[218:221], v[114:117]
	v_mfma_f32_16x16x32_bf16 v[106:109], v[174:177], v[218:221], v[106:109]
	v_mfma_f32_16x16x32_bf16 v[98:101], v[158:161], v[226:229], v[98:101]
	v_mfma_f32_16x16x32_bf16 v[90:93], v[174:177], v[226:229], v[90:93]
	v_mfma_f32_16x16x32_bf16 v[82:85], v[158:161], v[234:237], v[82:85]
	v_mfma_f32_16x16x32_bf16 v[74:77], v[174:177], v[234:237], v[74:77]
	s_setprio 1
	s_setprio 0
	v_mfma_f32_16x16x32_bf16 v[118:121], v[178:181], v[198:201], v[118:121]
	v_mfma_f32_16x16x32_bf16 v[110:113], v[186:189], v[198:201], v[110:113]
	v_mfma_f32_16x16x32_bf16 v[102:105], v[178:181], v[206:209], v[102:105]
	v_mfma_f32_16x16x32_bf16 v[94:97], v[186:189], v[206:209], v[94:97]
	v_mfma_f32_16x16x32_bf16 v[86:89], v[178:181], v[222:225], v[86:89]
	v_mfma_f32_16x16x32_bf16 v[78:81], v[186:189], v[222:225], v[78:81]
	v_mfma_f32_16x16x32_bf16 v[70:73], v[178:181], v[230:233], v[70:73]
	v_mfma_f32_16x16x32_bf16 v[66:69], v[186:189], v[230:233], v[66:69]
	v_mfma_f32_16x16x32_bf16 v[118:121], v[182:185], v[202:205], v[118:121]
	v_mfma_f32_16x16x32_bf16 v[110:113], v[190:193], v[202:205], v[110:113]
	v_mfma_f32_16x16x32_bf16 v[102:105], v[182:185], v[218:221], v[102:105]
	v_mfma_f32_16x16x32_bf16 v[94:97], v[190:193], v[218:221], v[94:97]
	v_mfma_f32_16x16x32_bf16 v[86:89], v[182:185], v[226:229], v[86:89]
	v_mfma_f32_16x16x32_bf16 v[78:81], v[190:193], v[226:229], v[78:81]
	v_mfma_f32_16x16x32_bf16 v[70:73], v[182:185], v[234:237], v[70:73]
	v_mfma_f32_16x16x32_bf16 v[66:69], v[190:193], v[234:237], v[66:69]
	s_setprio 1
	s_barrier
	s_add_i32 s76, s45, s26
	v_lshl_add_u64 v[194:195], s[22:23], 0, v[132:133]
	s_mov_b32 m0, s76
	ds_read_b128 v[198:201], v172 offset:16384
	ds_read_b128 v[202:205], v172 offset:17408
	ds_read_b128 v[206:209], v172 offset:18432
	ds_read_b128 v[218:221], v172 offset:19456
	ds_read_b128 v[222:225], v172 offset:20480
	ds_read_b128 v[226:229], v172 offset:21504
	ds_read_b128 v[230:233], v172 offset:22528
	ds_read_b128 v[234:237], v172 offset:23552
	global_load_lds_dwordx4 v[194:195], off
	s_add_i32 m0, s76, 0x2000
	s_add_u32 s76, s22, 0x4000
	v_lshl_add_u64 v[194:195], s[22:23], 0, v[136:137]
	s_addc_u32 s77, s23, 0
	s_add_i32 s78, s46, s26
	global_load_lds_dwordx4 v[194:195], off
	v_lshl_add_u64 v[194:195], s[76:77], 0, v[132:133]
	s_mov_b32 m0, s78
	s_nop 0
	global_load_lds_dwordx4 v[194:195], off
	v_lshl_add_u64 v[194:195], s[76:77], 0, v[136:137]
	s_add_i32 m0, s78, 0x2000
	s_nop 0
	global_load_lds_dwordx4 v[194:195], off
	v_lshl_add_u64 v[194:195], s[24:25], 0, v[130:131]
	s_mov_b32 m0, s15
	s_nop 0
	global_load_lds_dwordx4 v[194:195], off
	v_lshl_add_u64 v[194:195], s[24:25], 0, v[134:135]
	s_mov_b32 m0, s27
	s_nop 0
	global_load_lds_dwordx4 v[194:195], off
	s_waitcnt vmcnt(8)
	s_waitcnt lgkmcnt(0)
	s_barrier
; #define PG8_STAGE(bufoff, gbase, voff) do { _Pragma("unroll") for (int _i = 0; _i < 2; ++_i) \
;         __builtin_amdgcn_global_load_lds((const unsigned*)((const char*)(gbase) + (voff)[_i]), (PG8_LAS unsigned*)(lds + (bufoff) + ldsw + _i * 8192), 16, 0, 0); } while (0)
; #define PG8_LDA(dst, b, h) do { _Pragma("unroll") for (int m = 0; m < 4; ++m) _Pragma("unroll") for (int k = 0; k < 2; ++k) dst[m][k] = *(const PG8_LAS bf16x8*)(lds + PG8_SA(b, h) + aoff + m * 2048 + k * 1024); } while (0)
; #define PG8_LDB(dst, b, h) do { _Pragma("unroll") for (int n = 0; n < 2; ++n) _Pragma("unroll") for (int k = 0; k < 2; ++k) dst[n][k] = *(const PG8_LAS bf16x8*)(lds + PG8_SB(b, h) + boff + n * 2048 + k * 1024); } while (0)
; #define PG8_WAIT_V(n) asm volatile("s_waitcnt vmcnt(" #n ")" ::: "memory")
; #define PG8_WAIT_L(n) asm volatile("s_waitcnt lgkmcnt(" #n ")" ::: "memory")
; #define PG8_BAR __builtin_amdgcn_s_barrier()
; #define PG8_SCHED __builtin_amdgcn_sched_barrier(0)
; template <class Epi, class Sched, bool ALIGN_EPI = false, bool SP2 = false, bool I8 = false>
; __device__ __forceinline__ void gemm_phase(PG8_LAS unsigned char* lds, const Gemm g, const Sched& S, const Epi& E) {
;     ...
;             PG8_WAIT_V(8); PG8_WAIT_L(0); PG8_BAR; PG8_MMA(1, 0, At, B0); PG8_MMA(1, 1, At, B1); PG8_BAR; PG8_SCHED;
;             PG8_LDB(B0, 1, 0); PG8_LDB(B1, 1, 1); PG8_SCHED; PG8_LDA(At, 1, 0); PG8_STAGE(PG8_SA(0, 1), a2 + hstepA, voffA);
;             PG8_WAIT_V(8); PG8_WAIT_L(0); PG8_BAR; PG8_MMA(0, 0, At, B0); PG8_MMA(0, 1, At, B1); PG8_BAR; PG8_SCHED;
	s_setprio 0
	s_waitcnt lgkmcnt(0)
	v_mfma_f32_16x16x32_bf16 v[62:65], v[154:157], v[198:201], v[62:65]
	v_mfma_f32_16x16x32_bf16 v[58:61], v[162:165], v[198:201], v[58:61]
	v_mfma_f32_16x16x32_bf16 v[46:49], v[154:157], v[206:209], v[46:49]
	v_mfma_f32_16x16x32_bf16 v[42:45], v[162:165], v[206:209], v[42:45]
	v_mfma_f32_16x16x32_bf16 v[30:33], v[154:157], v[222:225], v[30:33]
	v_mfma_f32_16x16x32_bf16 v[26:29], v[162:165], v[222:225], v[26:29]
	v_mfma_f32_16x16x32_bf16 v[14:17], v[154:157], v[230:233], v[14:17]
	v_mfma_f32_16x16x32_bf16 v[10:13], v[162:165], v[230:233], v[10:13]
	v_mfma_f32_16x16x32_bf16 v[62:65], v[158:161], v[202:205], v[62:65]
	v_mfma_f32_16x16x32_bf16 v[58:61], v[174:177], v[202:205], v[58:61]
	v_mfma_f32_16x16x32_bf16 v[46:49], v[158:161], v[218:221], v[46:49]
	v_mfma_f32_16x16x32_bf16 v[42:45], v[174:177], v[218:221], v[42:45]
	v_mfma_f32_16x16x32_bf16 v[30:33], v[158:161], v[226:229], v[30:33]
	v_mfma_f32_16x16x32_bf16 v[26:29], v[174:177], v[226:229], v[26:29]
	v_mfma_f32_16x16x32_bf16 v[14:17], v[158:161], v[234:237], v[14:17]
	v_mfma_f32_16x16x32_bf16 v[10:13], v[174:177], v[234:237], v[10:13]
	s_setprio 1
	s_setprio 0
	v_mfma_f32_16x16x32_bf16 v[54:57], v[178:181], v[198:201], v[54:57]
	v_mfma_f32_16x16x32_bf16 v[50:53], v[186:189], v[198:201], v[50:53]
	v_mfma_f32_16x16x32_bf16 v[38:41], v[178:181], v[206:209], v[38:41]
	v_mfma_f32_16x16x32_bf16 v[34:37], v[186:189], v[206:209], v[34:37]
	v_mfma_f32_16x16x32_bf16 v[22:25], v[178:181], v[222:225], v[22:25]
	v_mfma_f32_16x16x32_bf16 v[18:21], v[186:189], v[222:225], v[18:21]
	v_mfma_f32_16x16x32_bf16 v[6:9], v[178:181], v[230:233], v[6:9]
	v_mfma_f32_16x16x32_bf16 v[2:5], v[186:189], v[230:233], v[2:5]
	v_mfma_f32_16x16x32_bf16 v[54:57], v[182:185], v[202:205], v[54:57]
	v_mfma_f32_16x16x32_bf16 v[50:53], v[190:193], v[202:205], v[50:53]
	v_mfma_f32_16x16x32_bf16 v[38:41], v[182:185], v[218:221], v[38:41]
	v_mfma_f32_16x16x32_bf16 v[34:37], v[190:193], v[218:221], v[34:37]
	v_mfma_f32_16x16x32_bf16 v[22:25], v[182:185], v[226:229], v[22:25]
	v_mfma_f32_16x16x32_bf16 v[18:21], v[190:193], v[226:229], v[18:21]
	v_mfma_f32_16x16x32_bf16 v[6:9], v[182:185], v[234:237], v[6:9]
	v_mfma_f32_16x16x32_bf16 v[2:5], v[190:193], v[234:237], v[2:5]
	s_setprio 1
	s_barrier
	s_add_i32 s76, 0, 0x18000
	v_add_u32_e32 v138, s76, v168
	s_add_i32 s77, 0, 0x1c000
	ds_read_b128 v[154:157], v138
	ds_read_b128 v[158:161], v138 offset:1024
	ds_read_b128 v[162:165], v138 offset:2048
	ds_read_b128 v[174:177], v138 offset:3072
	v_add_u32_e32 v138, s77, v168
	ds_read_b128 v[178:181], v138
	ds_read_b128 v[182:185], v138 offset:1024
	ds_read_b128 v[186:189], v138 offset:2048
	ds_read_b128 v[190:193], v138 offset:3072
	s_add_u32 s24, s24, 0x4000
	s_addc_u32 s25, s25, 0
	s_mov_b32 m0, s36
	v_lshl_add_u64 v[194:195], s[24:25], 0, v[130:131]
	ds_read_b128 v[198:201], v172 offset:32768
	ds_read_b128 v[202:205], v172 offset:33792
	ds_read_b128 v[206:209], v172 offset:34816
	ds_read_b128 v[218:221], v172 offset:35840
	ds_read_b128 v[222:225], v172 offset:36864
	ds_read_b128 v[226:229], v172 offset:37888
	ds_read_b128 v[230:233], v172 offset:38912
	ds_read_b128 v[234:237], v172 offset:39936
	global_load_lds_dwordx4 v[194:195], off
	v_lshl_add_u64 v[194:195], s[24:25], 0, v[134:135]
	s_mov_b32 m0, s37
	s_nop 0
	global_load_lds_dwordx4 v[194:195], off
	s_waitcnt vmcnt(8)
	s_waitcnt lgkmcnt(0)
	s_barrier
	s_setprio 0
	s_waitcnt lgkmcnt(0)
	v_mfma_f32_16x16x32_bf16 v[126:129], v[154:157], v[198:201], v[126:129]
	v_mfma_f32_16x16x32_bf16 v[122:125], v[162:165], v[198:201], v[122:125]
	v_mfma_f32_16x16x32_bf16 v[114:117], v[154:157], v[206:209], v[114:117]
	v_mfma_f32_16x16x32_bf16 v[106:109], v[162:165], v[206:209], v[106:109]
	v_mfma_f32_16x16x32_bf16 v[98:101], v[154:157], v[222:225], v[98:101]
	v_mfma_f32_16x16x32_bf16 v[90:93], v[162:165], v[222:225], v[90:93]
	v_mfma_f32_16x16x32_bf16 v[82:85], v[154:157], v[230:233], v[82:85]
	v_mfma_f32_16x16x32_bf16 v[74:77], v[162:165], v[230:233], v[74:77]
	v_mfma_f32_16x16x32_bf16 v[126:129], v[158:161], v[202:205], v[126:129]
	v_mfma_f32_16x16x32_bf16 v[122:125], v[174:177], v[202:205], v[122:125]
	v_mfma_f32_16x16x32_bf16 v[114:117], v[158:161], v[218:221], v[114:117]
	v_mfma_f32_16x16x32_bf16 v[106:109], v[174:177], v[218:221], v[106:109]
	v_mfma_f32_16x16x32_bf16 v[98:101], v[158:161], v[226:229], v[98:101]
	v_mfma_f32_16x16x32_bf16 v[90:93], v[174:177], v[226:229], v[90:93]
	v_mfma_f32_16x16x32_bf16 v[82:85], v[158:161], v[234:237], v[82:85]
	v_mfma_f32_16x16x32_bf16 v[74:77], v[174:177], v[234:237], v[74:77]
	s_setprio 1
	s_setprio 0
	v_mfma_f32_16x16x32_bf16 v[118:121], v[178:181], v[198:201], v[118:121]
	v_mfma_f32_16x16x32_bf16 v[110:113], v[186:189], v[198:201], v[110:113]
	v_mfma_f32_16x16x32_bf16 v[102:105], v[178:181], v[206:209], v[102:105]
	v_mfma_f32_16x16x32_bf16 v[94:97], v[186:189], v[206:209], v[94:97]
	v_mfma_f32_16x16x32_bf16 v[86:89], v[178:181], v[222:225], v[86:89]
	v_mfma_f32_16x16x32_bf16 v[78:81], v[186:189], v[222:225], v[78:81]
	v_mfma_f32_16x16x32_bf16 v[70:73], v[178:181], v[230:233], v[70:73]
	v_mfma_f32_16x16x32_bf16 v[66:69], v[186:189], v[230:233], v[66:69]
	v_mfma_f32_16x16x32_bf16 v[118:121], v[182:185], v[202:205], v[118:121]
	v_mfma_f32_16x16x32_bf16 v[110:113], v[190:193], v[202:205], v[110:113]
	v_mfma_f32_16x16x32_bf16 v[102:105], v[182:185], v[218:221], v[102:105]
	v_mfma_f32_16x16x32_bf16 v[94:97], v[190:193], v[218:221], v[94:97]
	v_mfma_f32_16x16x32_bf16 v[86:89], v[182:185], v[226:229], v[86:89]
	v_mfma_f32_16x16x32_bf16 v[78:81], v[190:193], v[226:229], v[78:81]
	v_mfma_f32_16x16x32_bf16 v[70:73], v[182:185], v[234:237], v[70:73]
	v_mfma_f32_16x16x32_bf16 v[66:69], v[190:193], v[234:237], v[66:69]
	s_setprio 1
	s_barrier
; #define PG8_STAGE(bufoff, gbase, voff) do { _Pragma("unroll") for (int _i = 0; _i < 2; ++_i) \
;         __builtin_amdgcn_global_load_lds((const unsigned*)((const char*)(gbase) + (voff)[_i]), (PG8_LAS unsigned*)(lds + (bufoff) + ldsw + _i * 8192), 16, 0, 0); } while (0)
; #define PG8_LDA(dst, b, h) do { _Pragma("unroll") for (int m = 0; m < 4; ++m) _Pragma("unroll") for (int k = 0; k < 2; ++k) dst[m][k] = *(const PG8_LAS bf16x8*)(lds + PG8_SA(b, h) + aoff + m * 2048 + k * 1024); } while (0)
; #define PG8_WAIT_V(n) asm volatile("s_waitcnt vmcnt(" #n ")" ::: "memory")
; #define PG8_WAIT_L(n) asm volatile("s_waitcnt lgkmcnt(" #n ")" ::: "memory")
; #define PG8_BAR __builtin_amdgcn_s_barrier()
; #define PG8_SCHED __builtin_amdgcn_sched_barrier(0)
; template <class Epi, class Sched, bool ALIGN_EPI = false, bool SP2 = false, bool I8 = false>
; __device__ __forceinline__ void gemm_phase(PG8_LAS unsigned char* lds, const Gemm g, const Sched& S, const Epi& E) {
;     ...
;         for (int t = 0; t < nt; t += 2) {
;             const bool last = (t == nt - 2);
;             const char* a1 = cA + (size_t)(t + 1) * kstepA;
;             const char* a2 = last ? nA : cA + (size_t)(t + 2) * kstepA; const char* b2 = last ? nB : cB + (size_t)(t + 2) * kstepB;
;             const char* a3 = a2 + kstepA; const char* b3 = b2 + kstepB;
;             if (last && has_next) S.a_ready(nxt);
;     ...
;             PG8_LDA(At, 1, 1); PG8_STAGE(PG8_SB(1, 0), b3, voffB); PG8_STAGE(PG8_SB(1, 1), b3 + hstepB, voffB); PG8_STAGE(PG8_SA(1, 0), a3, voffA);
;             PG8_WAIT_V(8); PG8_WAIT_L(0); PG8_BAR; PG8_MMA(1, 0, At, B0); PG8_MMA(1, 1, At, B1); PG8_BAR; PG8_SCHED;
	s_add_u32 s24, s22, 0x8000
	s_addc_u32 s25, s23, 0
	s_add_i32 s76, s76, s26
	v_lshl_add_u64 v[194:195], s[24:25], 0, v[132:133]
	s_mov_b32 m0, s76
	ds_read_b128 v[198:201], v172 offset:49152
	ds_read_b128 v[202:205], v172 offset:50176
	ds_read_b128 v[206:209], v172 offset:51200
	ds_read_b128 v[218:221], v172 offset:52224
	ds_read_b128 v[222:225], v172 offset:53248
	ds_read_b128 v[226:229], v172 offset:54272
	ds_read_b128 v[230:233], v172 offset:55296
	ds_read_b128 v[234:237], v172 offset:56320
	global_load_lds_dwordx4 v[194:195], off
	s_add_i32 m0, s76, 0x2000
	s_add_u32 s22, s22, 0xc000
	v_lshl_add_u64 v[194:195], s[24:25], 0, v[136:137]
	s_addc_u32 s23, s23, 0
	s_add_i32 s24, s77, s26
	global_load_lds_dwordx4 v[194:195], off
	v_lshl_add_u64 v[194:195], s[22:23], 0, v[132:133]
	s_mov_b32 m0, s24
	s_nop 0
	global_load_lds_dwordx4 v[194:195], off
	v_lshl_add_u64 v[194:195], s[22:23], 0, v[136:137]
	s_add_i32 m0, s24, 0x2000
	s_nop 0
	global_load_lds_dwordx4 v[194:195], off
	v_lshl_add_u64 v[194:195], s[20:21], 0, v[130:131]
	s_mov_b32 m0, s42
	s_nop 0
	global_load_lds_dwordx4 v[194:195], off
	v_lshl_add_u64 v[194:195], s[20:21], 0, v[134:135]
	s_mov_b32 m0, s43
	s_nop 0
	global_load_lds_dwordx4 v[194:195], off
	s_waitcnt vmcnt(8)
	s_waitcnt lgkmcnt(0)
	s_barrier
	s_setprio 0
	s_waitcnt lgkmcnt(0)
	v_mfma_f32_16x16x32_bf16 v[62:65], v[154:157], v[198:201], v[62:65]
	v_mfma_f32_16x16x32_bf16 v[58:61], v[162:165], v[198:201], v[58:61]
	v_mfma_f32_16x16x32_bf16 v[46:49], v[154:157], v[206:209], v[46:49]
	v_mfma_f32_16x16x32_bf16 v[42:45], v[162:165], v[206:209], v[42:45]
	v_mfma_f32_16x16x32_bf16 v[30:33], v[154:157], v[222:225], v[30:33]
	v_mfma_f32_16x16x32_bf16 v[26:29], v[162:165], v[222:225], v[26:29]
	v_mfma_f32_16x16x32_bf16 v[14:17], v[154:157], v[230:233], v[14:17]
	v_mfma_f32_16x16x32_bf16 v[10:13], v[162:165], v[230:233], v[10:13]
	v_mfma_f32_16x16x32_bf16 v[62:65], v[158:161], v[202:205], v[62:65]
	v_mfma_f32_16x16x32_bf16 v[58:61], v[174:177], v[202:205], v[58:61]
	v_mfma_f32_16x16x32_bf16 v[46:49], v[158:161], v[218:221], v[46:49]
	v_mfma_f32_16x16x32_bf16 v[42:45], v[174:177], v[218:221], v[42:45]
	v_mfma_f32_16x16x32_bf16 v[30:33], v[158:161], v[226:229], v[30:33]
	v_mfma_f32_16x16x32_bf16 v[26:29], v[174:177], v[226:229], v[26:29]
	v_mfma_f32_16x16x32_bf16 v[14:17], v[158:161], v[234:237], v[14:17]
	v_mfma_f32_16x16x32_bf16 v[10:13], v[174:177], v[234:237], v[10:13]
	s_setprio 1
	s_setprio 0
	v_mfma_f32_16x16x32_bf16 v[54:57], v[178:181], v[198:201], v[54:57]
	v_mfma_f32_16x16x32_bf16 v[50:53], v[186:189], v[198:201], v[50:53]
	v_mfma_f32_16x16x32_bf16 v[38:41], v[178:181], v[206:209], v[38:41]
	v_mfma_f32_16x16x32_bf16 v[34:37], v[186:189], v[206:209], v[34:37]
	v_mfma_f32_16x16x32_bf16 v[22:25], v[178:181], v[222:225], v[22:25]
	v_mfma_f32_16x16x32_bf16 v[18:21], v[186:189], v[222:225], v[18:21]
	v_mfma_f32_16x16x32_bf16 v[6:9], v[178:181], v[230:233], v[6:9]
	v_mfma_f32_16x16x32_bf16 v[2:5], v[186:189], v[230:233], v[2:5]
	v_mfma_f32_16x16x32_bf16 v[54:57], v[182:185], v[202:205], v[54:57]
	v_mfma_f32_16x16x32_bf16 v[50:53], v[190:193], v[202:205], v[50:53]
	v_mfma_f32_16x16x32_bf16 v[38:41], v[182:185], v[218:221], v[38:41]
	v_mfma_f32_16x16x32_bf16 v[34:37], v[190:193], v[218:221], v[34:37]
	v_mfma_f32_16x16x32_bf16 v[22:25], v[182:185], v[226:229], v[22:25]
	v_mfma_f32_16x16x32_bf16 v[18:21], v[190:193], v[226:229], v[18:21]
	v_mfma_f32_16x16x32_bf16 v[6:9], v[182:185], v[234:237], v[6:9]
	v_mfma_f32_16x16x32_bf16 v[2:5], v[190:193], v[234:237], v[2:5]
	s_setprio 1
	s_barrier
	s_add_i32 s73, s73, 2
	s_add_u32 s18, s18, 0x10000
	s_addc_u32 s19, s19, 0
	s_add_u32 s71, s71, 0x10000
	s_addc_u32 s72, s72, 0
	s_cmp_gt_u32 s73, 61
	s_cbranch_scc0 .LBB0_865
	s_and_b64 vcc, exec, s[4:5]
	s_cbranch_vccz .LBB0_868
	s_barrier

; #define PG8_STAGE(bufoff, gbase, voff) do { _Pragma("unroll") for (int _i = 0; _i < 2; ++_i) \
;         __builtin_amdgcn_global_load_lds((const unsigned*)((const char*)(gbase) + (voff)[_i]), (PG8_LAS unsigned*)(lds + (bufoff) + ldsw + _i * 8192), 16, 0, 0); } while (0)
; #define PG8_LDA(dst, b, h) do { _Pragma("unroll") for (int m = 0; m < 4; ++m) _Pragma("unroll") for (int k = 0; k < 2; ++k) dst[m][k] = *(const PG8_LAS bf16x8*)(lds + PG8_SA(b, h) + aoff + m * 2048 + k * 1024); } while (0)
; #define PG8_LDB(dst, b, h) do { _Pragma("unroll") for (int n = 0; n < 2; ++n) _Pragma("unroll") for (int k = 0; k < 2; ++k) dst[n][k] = *(const PG8_LAS bf16x8*)(lds + PG8_SB(b, h) + boff + n * 2048 + k * 1024); } while (0)
; #define PG8_WAIT_V(n) asm volatile("s_waitcnt vmcnt(" #n ")" ::: "memory")
; #define PG8_WAIT_L(n) asm volatile("s_waitcnt lgkmcnt(" #n ")" ::: "memory")
; #define PG8_BAR __builtin_amdgcn_s_barrier()
; #define PG8_SCHED __builtin_amdgcn_sched_barrier(0)
; template <class Epi, class Sched, bool ALIGN_EPI = false, bool SP2 = false, bool I8 = false>
; __device__ __forceinline__ void gemm_phase(PG8_LAS unsigned char* lds, const Gemm g, const Sched& S, const Epi& E) {
;     ...
;             PG8_LDB(B0, 0, 0); PG8_LDB(B1, 0, 1); PG8_SCHED; PG8_LDA(At, 0, 0); PG8_STAGE(PG8_SA(1, 1), a1 + hstepA, voffA);
;             PG8_WAIT_V(8); PG8_WAIT_L(0); PG8_BAR; PG8_MMA(0, 0, At, B0); PG8_MMA(0, 1, At, B1); PG8_BAR; PG8_SCHED;
;             PG8_LDA(At, 0, 1); PG8_STAGE(PG8_SB(0, 0), b2, voffB); PG8_STAGE(PG8_SB(0, 1), b2 + hstepB, voffB); PG8_STAGE(PG8_SA(0, 0), a2, voffA);
.LBB0_983:
	s_add_u32 s42, s24, s36
	s_addc_u32 s43, s25, s37
	s_add_u32 s40, s42, 0x100
	s_addc_u32 s41, s43, 0
	s_and_b64 s[38:39], s[28:29], exec
	s_cselect_b32 s39, s13, s41
	s_cselect_b32 s38, s64, s40
	s_add_u32 s36, s22, s36
	s_addc_u32 s37, s23, s37
	s_add_u32 s36, s36, 0x100
	s_addc_u32 s37, s37, 0
	ds_read_b128 v[152:155], v145
	ds_read_b128 v[156:159], v145 offset:1024
	ds_read_b128 v[160:163], v145 offset:2048
	ds_read_b128 v[164:167], v145 offset:3072
	ds_read_b128 v[168:171], v146
	ds_read_b128 v[172:175], v146 offset:1024
	ds_read_b128 v[176:179], v146 offset:2048
	ds_read_b128 v[180:183], v146 offset:3072
	s_and_b64 s[28:29], s[28:29], exec
	s_cselect_b32 s41, s15, s37
	s_cselect_b32 s40, s65, s36
	s_add_u32 s44, s42, 0x20080
	s_addc_u32 s45, s43, 0
	s_add_u32 s42, s40, 0x10000
	s_addc_u32 s43, s41, 0
	s_add_u32 s36, s38, 0x20000
	s_addc_u32 s37, s39, 0
	s_add_i32 s73, s61, s46
	s_add_i32 s71, s73, 0x2000
	s_add_u32 s28, s40, 0x10080
	s_addc_u32 s29, s41, 0
	s_add_i32 s72, s62, s46
	s_add_i32 s70, s72, 0x2000
	s_mov_b32 m0, s55
	v_lshl_add_u64 v[140:141], s[44:45], 0, v[136:137]
	ds_read_b128 v[184:187], v147
	ds_read_b128 v[188:191], v147 offset:1024
	ds_read_b128 v[192:195], v147 offset:2048
	ds_read_b128 v[198:201], v147 offset:3072
	ds_read_b128 v[202:205], v147 offset:4096
	ds_read_b128 v[206:209], v147 offset:5120
	ds_read_b128 v[216:219], v147 offset:6144
	ds_read_b128 v[220:223], v147 offset:7168
	global_load_lds_dwordx4 v[140:141], off
	v_lshl_add_u64 v[140:141], s[44:45], 0, v[132:133]
	s_mov_b32 m0, s56
	s_nop 0
	global_load_lds_dwordx4 v[140:141], off
	s_waitcnt vmcnt(8)
	s_waitcnt lgkmcnt(0)
	s_barrier
	s_setprio 0
	s_waitcnt lgkmcnt(0)
	v_mfma_f32_16x16x32_bf16 v[126:129], v[152:155], v[184:187], v[126:129]
	v_mfma_f32_16x16x32_bf16 v[122:125], v[160:163], v[184:187], v[122:125]
	v_mfma_f32_16x16x32_bf16 v[118:121], v[152:155], v[192:195], v[118:121]
	v_mfma_f32_16x16x32_bf16 v[110:113], v[160:163], v[192:195], v[110:113]
	v_mfma_f32_16x16x32_bf16 v[102:105], v[152:155], v[202:205], v[102:105]
	v_mfma_f32_16x16x32_bf16 v[94:97], v[160:163], v[202:205], v[94:97]
	v_mfma_f32_16x16x32_bf16 v[86:89], v[152:155], v[216:219], v[86:89]
	v_mfma_f32_16x16x32_bf16 v[78:81], v[160:163], v[216:219], v[78:81]
	v_mfma_f32_16x16x32_bf16 v[126:129], v[156:159], v[188:191], v[126:129]
	v_mfma_f32_16x16x32_bf16 v[122:125], v[164:167], v[188:191], v[122:125]
	v_mfma_f32_16x16x32_bf16 v[118:121], v[156:159], v[198:201], v[118:121]
	v_mfma_f32_16x16x32_bf16 v[110:113], v[164:167], v[198:201], v[110:113]
	v_mfma_f32_16x16x32_bf16 v[102:105], v[156:159], v[206:209], v[102:105]
	v_mfma_f32_16x16x32_bf16 v[94:97], v[164:167], v[206:209], v[94:97]
	v_mfma_f32_16x16x32_bf16 v[86:89], v[156:159], v[220:223], v[86:89]
	v_mfma_f32_16x16x32_bf16 v[78:81], v[164:167], v[220:223], v[78:81]
	s_setprio 1
	s_setprio 0
	v_mfma_f32_16x16x32_bf16 v[114:117], v[168:171], v[184:187], v[114:117]
	v_mfma_f32_16x16x32_bf16 v[106:109], v[176:179], v[184:187], v[106:109]
	v_mfma_f32_16x16x32_bf16 v[98:101], v[168:171], v[192:195], v[98:101]
	v_mfma_f32_16x16x32_bf16 v[90:93], v[176:179], v[192:195], v[90:93]
	v_mfma_f32_16x16x32_bf16 v[82:85], v[168:171], v[202:205], v[82:85]
	v_mfma_f32_16x16x32_bf16 v[74:77], v[176:179], v[202:205], v[74:77]
	v_mfma_f32_16x16x32_bf16 v[70:73], v[168:171], v[216:219], v[70:73]
	v_mfma_f32_16x16x32_bf16 v[66:69], v[176:179], v[216:219], v[66:69]
	v_mfma_f32_16x16x32_bf16 v[114:117], v[172:175], v[188:191], v[114:117]
	v_mfma_f32_16x16x32_bf16 v[106:109], v[180:183], v[188:191], v[106:109]
	v_mfma_f32_16x16x32_bf16 v[98:101], v[172:175], v[198:201], v[98:101]
	v_mfma_f32_16x16x32_bf16 v[90:93], v[180:183], v[198:201], v[90:93]
	v_mfma_f32_16x16x32_bf16 v[82:85], v[172:175], v[206:209], v[82:85]
	v_mfma_f32_16x16x32_bf16 v[74:77], v[180:183], v[206:209], v[74:77]
	v_mfma_f32_16x16x32_bf16 v[70:73], v[172:175], v[220:223], v[70:73]
	v_mfma_f32_16x16x32_bf16 v[66:69], v[180:183], v[220:223], v[66:69]
	s_setprio 1
	s_barrier
	s_mov_b32 m0, s57
	v_lshl_add_u64 v[140:141], s[40:41], 0, v[134:135]
	ds_read_b128 v[184:187], v147 offset:16384
	ds_read_b128 v[188:191], v147 offset:17408
	ds_read_b128 v[192:195], v147 offset:18432
	ds_read_b128 v[198:201], v147 offset:19456
	ds_read_b128 v[202:205], v147 offset:20480
	ds_read_b128 v[206:209], v147 offset:21504
	ds_read_b128 v[216:219], v147 offset:22528
	ds_read_b128 v[220:223], v147 offset:23552
	global_load_lds_dwordx4 v[140:141], off
	v_lshl_add_u64 v[224:225], s[40:41], 0, v[130:131]
	s_mov_b32 m0, s58
	v_lshl_add_u64 v[226:227], s[42:43], 0, v[134:135]
	global_load_lds_dwordx4 v[224:225], off
	s_mov_b32 m0, s59
	v_lshl_add_u64 v[228:229], s[38:39], 0, v[132:133]
	global_load_lds_dwordx4 v[226:227], off
	v_lshl_add_u64 v[226:227], s[42:43], 0, v[130:131]
	s_mov_b32 m0, s60
	s_nop 0
	global_load_lds_dwordx4 v[226:227], off
	v_lshl_add_u64 v[226:227], s[38:39], 0, v[136:137]
	s_mov_b32 m0, s9
	s_nop 0
	global_load_lds_dwordx4 v[226:227], off
	s_mov_b32 m0, s47
	s_nop 0
	global_load_lds_dwordx4 v[228:229], off
	s_waitcnt vmcnt(8)
	s_waitcnt lgkmcnt(0)
	s_barrier
; #define PG8_STAGE(bufoff, gbase, voff) do { _Pragma("unroll") for (int _i = 0; _i < 2; ++_i) \
;         __builtin_amdgcn_global_load_lds((const unsigned*)((const char*)(gbase) + (voff)[_i]), (PG8_LAS unsigned*)(lds + (bufoff) + ldsw + _i * 8192), 16, 0, 0); } while (0)
; #define PG8_LDA(dst, b, h) do { _Pragma("unroll") for (int m = 0; m < 4; ++m) _Pragma("unroll") for (int k = 0; k < 2; ++k) dst[m][k] = *(const PG8_LAS bf16x8*)(lds + PG8_SA(b, h) + aoff + m * 2048 + k * 1024); } while (0)
; #define PG8_LDB(dst, b, h) do { _Pragma("unroll") for (int n = 0; n < 2; ++n) _Pragma("unroll") for (int k = 0; k < 2; ++k) dst[n][k] = *(const PG8_LAS bf16x8*)(lds + PG8_SB(b, h) + boff + n * 2048 + k * 1024); } while (0)
; #define PG8_WAIT_V(n) asm volatile("s_waitcnt vmcnt(" #n ")" ::: "memory")
; #define PG8_WAIT_L(n) asm volatile("s_waitcnt lgkmcnt(" #n ")" ::: "memory")
; #define PG8_BAR __builtin_amdgcn_s_barrier()
; #define PG8_SCHED __builtin_amdgcn_sched_barrier(0)
; template <class Epi, class Sched, bool ALIGN_EPI = false, bool SP2 = false, bool I8 = false>
; __device__ __forceinline__ void gemm_phase(PG8_LAS unsigned char* lds, const Gemm g, const Sched& S, const Epi& E) {
;     ...
;             PG8_WAIT_V(8); PG8_WAIT_L(0); PG8_BAR; PG8_MMA(1, 0, At, B0); PG8_MMA(1, 1, At, B1); PG8_BAR; PG8_SCHED;
;             PG8_LDB(B0, 1, 0); PG8_LDB(B1, 1, 1); PG8_SCHED; PG8_LDA(At, 1, 0); PG8_STAGE(PG8_SA(0, 1), a2 + hstepA, voffA);
;             PG8_WAIT_V(8); PG8_WAIT_L(0); PG8_BAR; PG8_MMA(0, 0, At, B0); PG8_MMA(0, 1, At, B1); PG8_BAR; PG8_SCHED;
	s_setprio 0
	s_waitcnt lgkmcnt(0)
	v_mfma_f32_16x16x32_bf16 v[62:65], v[152:155], v[184:187], v[62:65]
	v_mfma_f32_16x16x32_bf16 v[58:61], v[160:163], v[184:187], v[58:61]
	v_mfma_f32_16x16x32_bf16 v[54:57], v[152:155], v[192:195], v[54:57]
	v_mfma_f32_16x16x32_bf16 v[46:49], v[160:163], v[192:195], v[46:49]
	v_mfma_f32_16x16x32_bf16 v[38:41], v[152:155], v[202:205], v[38:41]
	v_mfma_f32_16x16x32_bf16 v[30:33], v[160:163], v[202:205], v[30:33]
	v_mfma_f32_16x16x32_bf16 v[22:25], v[152:155], v[216:219], v[22:25]
	v_mfma_f32_16x16x32_bf16 v[14:17], v[160:163], v[216:219], v[14:17]
	v_mfma_f32_16x16x32_bf16 v[62:65], v[156:159], v[188:191], v[62:65]
	v_mfma_f32_16x16x32_bf16 v[58:61], v[164:167], v[188:191], v[58:61]
	v_mfma_f32_16x16x32_bf16 v[54:57], v[156:159], v[198:201], v[54:57]
	v_mfma_f32_16x16x32_bf16 v[46:49], v[164:167], v[198:201], v[46:49]
	v_mfma_f32_16x16x32_bf16 v[38:41], v[156:159], v[206:209], v[38:41]
	v_mfma_f32_16x16x32_bf16 v[30:33], v[164:167], v[206:209], v[30:33]
	v_mfma_f32_16x16x32_bf16 v[22:25], v[156:159], v[220:223], v[22:25]
	v_mfma_f32_16x16x32_bf16 v[14:17], v[164:167], v[220:223], v[14:17]
	s_setprio 1
	s_setprio 0
	v_mfma_f32_16x16x32_bf16 v[50:53], v[168:171], v[184:187], v[50:53]
	v_mfma_f32_16x16x32_bf16 v[42:45], v[176:179], v[184:187], v[42:45]
	v_mfma_f32_16x16x32_bf16 v[34:37], v[168:171], v[192:195], v[34:37]
	v_mfma_f32_16x16x32_bf16 v[26:29], v[176:179], v[192:195], v[26:29]
	v_mfma_f32_16x16x32_bf16 v[18:21], v[168:171], v[202:205], v[18:21]
	v_mfma_f32_16x16x32_bf16 v[10:13], v[176:179], v[202:205], v[10:13]
	v_mfma_f32_16x16x32_bf16 v[6:9], v[168:171], v[216:219], v[6:9]
	v_mfma_f32_16x16x32_bf16 v[2:5], v[176:179], v[216:219], v[2:5]
	v_mfma_f32_16x16x32_bf16 v[50:53], v[172:175], v[188:191], v[50:53]
	v_mfma_f32_16x16x32_bf16 v[42:45], v[180:183], v[188:191], v[42:45]
	v_mfma_f32_16x16x32_bf16 v[34:37], v[172:175], v[198:201], v[34:37]
	v_mfma_f32_16x16x32_bf16 v[26:29], v[180:183], v[198:201], v[26:29]
	v_mfma_f32_16x16x32_bf16 v[18:21], v[172:175], v[206:209], v[18:21]
	v_mfma_f32_16x16x32_bf16 v[10:13], v[180:183], v[206:209], v[10:13]
	v_mfma_f32_16x16x32_bf16 v[6:9], v[172:175], v[220:223], v[6:9]
	v_mfma_f32_16x16x32_bf16 v[2:5], v[180:183], v[220:223], v[2:5]
	s_setprio 1
	s_barrier
	ds_read_b128 v[152:155], v148
	ds_read_b128 v[156:159], v148 offset:1024
	ds_read_b128 v[160:163], v148 offset:2048
	ds_read_b128 v[164:167], v148 offset:3072
	ds_read_b128 v[168:171], v149
	ds_read_b128 v[172:175], v149 offset:1024
	ds_read_b128 v[176:179], v149 offset:2048
	ds_read_b128 v[180:183], v149 offset:3072
	s_mov_b32 m0, s48
	v_lshl_add_u64 v[230:231], s[36:37], 0, v[136:137]
	ds_read_b128 v[184:187], v147 offset:32768
	ds_read_b128 v[188:191], v147 offset:33792
	ds_read_b128 v[192:195], v147 offset:34816
	ds_read_b128 v[198:201], v147 offset:35840
	ds_read_b128 v[202:205], v147 offset:36864
	ds_read_b128 v[206:209], v147 offset:37888
	ds_read_b128 v[216:219], v147 offset:38912
	ds_read_b128 v[220:223], v147 offset:39936
	global_load_lds_dwordx4 v[230:231], off
	v_lshl_add_u64 v[230:231], s[36:37], 0, v[132:133]
	s_mov_b32 m0, s49
	s_nop 0
	global_load_lds_dwordx4 v[230:231], off
	s_waitcnt vmcnt(8)
	s_waitcnt lgkmcnt(0)
	s_barrier
	s_setprio 0
	s_waitcnt lgkmcnt(0)
	v_mfma_f32_16x16x32_bf16 v[126:129], v[152:155], v[184:187], v[126:129]
	v_mfma_f32_16x16x32_bf16 v[122:125], v[160:163], v[184:187], v[122:125]
	v_mfma_f32_16x16x32_bf16 v[118:121], v[152:155], v[192:195], v[118:121]
	v_mfma_f32_16x16x32_bf16 v[110:113], v[160:163], v[192:195], v[110:113]
	v_mfma_f32_16x16x32_bf16 v[102:105], v[152:155], v[202:205], v[102:105]
	v_mfma_f32_16x16x32_bf16 v[94:97], v[160:163], v[202:205], v[94:97]
	v_mfma_f32_16x16x32_bf16 v[86:89], v[152:155], v[216:219], v[86:89]
	v_mfma_f32_16x16x32_bf16 v[78:81], v[160:163], v[216:219], v[78:81]
	v_mfma_f32_16x16x32_bf16 v[126:129], v[156:159], v[188:191], v[126:129]
	v_mfma_f32_16x16x32_bf16 v[122:125], v[164:167], v[188:191], v[122:125]
	v_mfma_f32_16x16x32_bf16 v[118:121], v[156:159], v[198:201], v[118:121]
	v_mfma_f32_16x16x32_bf16 v[110:113], v[164:167], v[198:201], v[110:113]
	v_mfma_f32_16x16x32_bf16 v[102:105], v[156:159], v[206:209], v[102:105]
	v_mfma_f32_16x16x32_bf16 v[94:97], v[164:167], v[206:209], v[94:97]
	v_mfma_f32_16x16x32_bf16 v[86:89], v[156:159], v[220:223], v[86:89]
	v_mfma_f32_16x16x32_bf16 v[78:81], v[164:167], v[220:223], v[78:81]
	s_setprio 1
	s_setprio 0
	v_mfma_f32_16x16x32_bf16 v[114:117], v[168:171], v[184:187], v[114:117]
	v_mfma_f32_16x16x32_bf16 v[106:109], v[176:179], v[184:187], v[106:109]
	v_mfma_f32_16x16x32_bf16 v[98:101], v[168:171], v[192:195], v[98:101]
	v_mfma_f32_16x16x32_bf16 v[90:93], v[176:179], v[192:195], v[90:93]
	v_mfma_f32_16x16x32_bf16 v[82:85], v[168:171], v[202:205], v[82:85]
	v_mfma_f32_16x16x32_bf16 v[74:77], v[176:179], v[202:205], v[74:77]
	v_mfma_f32_16x16x32_bf16 v[70:73], v[168:171], v[216:219], v[70:73]
	v_mfma_f32_16x16x32_bf16 v[66:69], v[176:179], v[216:219], v[66:69]
	v_mfma_f32_16x16x32_bf16 v[114:117], v[172:175], v[188:191], v[114:117]
	v_mfma_f32_16x16x32_bf16 v[106:109], v[180:183], v[188:191], v[106:109]
	v_mfma_f32_16x16x32_bf16 v[98:101], v[172:175], v[198:201], v[98:101]
	v_mfma_f32_16x16x32_bf16 v[90:93], v[180:183], v[198:201], v[90:93]
	v_mfma_f32_16x16x32_bf16 v[82:85], v[172:175], v[206:209], v[82:85]
	v_mfma_f32_16x16x32_bf16 v[74:77], v[180:183], v[206:209], v[74:77]
	v_mfma_f32_16x16x32_bf16 v[70:73], v[172:175], v[220:223], v[70:73]
	v_mfma_f32_16x16x32_bf16 v[66:69], v[180:183], v[220:223], v[66:69]
	s_setprio 1
	s_barrier
; #define PG8_STAGE(bufoff, gbase, voff) do { _Pragma("unroll") for (int _i = 0; _i < 2; ++_i) \
;         __builtin_amdgcn_global_load_lds((const unsigned*)((const char*)(gbase) + (voff)[_i]), (PG8_LAS unsigned*)(lds + (bufoff) + ldsw + _i * 8192), 16, 0, 0); } while (0)
; #define PG8_LDA(dst, b, h) do { _Pragma("unroll") for (int m = 0; m < 4; ++m) _Pragma("unroll") for (int k = 0; k < 2; ++k) dst[m][k] = *(const PG8_LAS bf16x8*)(lds + PG8_SA(b, h) + aoff + m * 2048 + k * 1024); } while (0)
; #define PG8_WAIT_V(n) asm volatile("s_waitcnt vmcnt(" #n ")" ::: "memory")
; #define PG8_WAIT_L(n) asm volatile("s_waitcnt lgkmcnt(" #n ")" ::: "memory")
; #define PG8_BAR __builtin_amdgcn_s_barrier()
; #define PG8_SCHED __builtin_amdgcn_sched_barrier(0)
; template <class Epi, class Sched, bool ALIGN_EPI = false, bool SP2 = false, bool I8 = false>
; __device__ __forceinline__ void gemm_phase(PG8_LAS unsigned char* lds, const Gemm g, const Sched& S, const Epi& E) {
;     ...
;             PG8_LDA(At, 1, 1); PG8_STAGE(PG8_SB(1, 0), b3, voffB); PG8_STAGE(PG8_SB(1, 1), b3 + hstepB, voffB); PG8_STAGE(PG8_SA(1, 0), a3, voffA);
;             PG8_WAIT_V(8); PG8_WAIT_L(0); PG8_BAR; PG8_MMA(1, 0, At, B0); PG8_MMA(1, 1, At, B1); PG8_BAR; PG8_SCHED;
	s_mov_b32 m0, s73
	v_lshl_add_u64 v[140:141], v[140:141], 0, s[6:7]
	ds_read_b128 v[184:187], v147 offset:49152
	ds_read_b128 v[188:191], v147 offset:50176
	ds_read_b128 v[192:195], v147 offset:51200
	ds_read_b128 v[198:201], v147 offset:52224
	ds_read_b128 v[202:205], v147 offset:53248
	ds_read_b128 v[206:209], v147 offset:54272
	ds_read_b128 v[216:219], v147 offset:55296
	ds_read_b128 v[220:223], v147 offset:56320
	global_load_lds_dwordx4 v[140:141], off
	v_lshl_add_u64 v[140:141], v[224:225], 0, s[6:7]
	s_mov_b32 m0, s71
	s_nop 0
	global_load_lds_dwordx4 v[140:141], off
	v_lshl_add_u64 v[140:141], s[28:29], 0, v[134:135]
	s_mov_b32 m0, s72
	s_nop 0
	global_load_lds_dwordx4 v[140:141], off
	v_lshl_add_u64 v[140:141], s[28:29], 0, v[130:131]
	s_mov_b32 m0, s70
	s_nop 0
	global_load_lds_dwordx4 v[140:141], off
	v_lshl_add_u64 v[140:141], v[226:227], 0, s[6:7]
	s_mov_b32 m0, s53
	s_nop 0
	global_load_lds_dwordx4 v[140:141], off
	v_lshl_add_u64 v[140:141], v[228:229], 0, s[6:7]
	s_mov_b32 m0, s54
	s_nop 0
	global_load_lds_dwordx4 v[140:141], off
	s_waitcnt vmcnt(8)
	s_waitcnt lgkmcnt(0)
	s_barrier
	s_setprio 0
	s_waitcnt lgkmcnt(0)
	v_mfma_f32_16x16x32_bf16 v[62:65], v[152:155], v[184:187], v[62:65]
	v_mfma_f32_16x16x32_bf16 v[58:61], v[160:163], v[184:187], v[58:61]
	v_mfma_f32_16x16x32_bf16 v[54:57], v[152:155], v[192:195], v[54:57]
	v_mfma_f32_16x16x32_bf16 v[46:49], v[160:163], v[192:195], v[46:49]
	v_mfma_f32_16x16x32_bf16 v[38:41], v[152:155], v[202:205], v[38:41]
	v_mfma_f32_16x16x32_bf16 v[30:33], v[160:163], v[202:205], v[30:33]
	v_mfma_f32_16x16x32_bf16 v[22:25], v[152:155], v[216:219], v[22:25]
	v_mfma_f32_16x16x32_bf16 v[14:17], v[160:163], v[216:219], v[14:17]
	v_mfma_f32_16x16x32_bf16 v[62:65], v[156:159], v[188:191], v[62:65]
	v_mfma_f32_16x16x32_bf16 v[58:61], v[164:167], v[188:191], v[58:61]
	v_mfma_f32_16x16x32_bf16 v[54:57], v[156:159], v[198:201], v[54:57]
	v_mfma_f32_16x16x32_bf16 v[46:49], v[164:167], v[198:201], v[46:49]
	v_mfma_f32_16x16x32_bf16 v[38:41], v[156:159], v[206:209], v[38:41]
	v_mfma_f32_16x16x32_bf16 v[30:33], v[164:167], v[206:209], v[30:33]
	v_mfma_f32_16x16x32_bf16 v[22:25], v[156:159], v[220:223], v[22:25]
	v_mfma_f32_16x16x32_bf16 v[14:17], v[164:167], v[220:223], v[14:17]
	s_setprio 1
	s_setprio 0
	v_mfma_f32_16x16x32_bf16 v[50:53], v[168:171], v[184:187], v[50:53]
	v_mfma_f32_16x16x32_bf16 v[42:45], v[176:179], v[184:187], v[42:45]
	v_mfma_f32_16x16x32_bf16 v[34:37], v[168:171], v[192:195], v[34:37]
	v_mfma_f32_16x16x32_bf16 v[26:29], v[176:179], v[192:195], v[26:29]
	v_mfma_f32_16x16x32_bf16 v[18:21], v[168:171], v[202:205], v[18:21]
	v_mfma_f32_16x16x32_bf16 v[10:13], v[176:179], v[202:205], v[10:13]
	v_mfma_f32_16x16x32_bf16 v[6:9], v[168:171], v[216:219], v[6:9]
	v_mfma_f32_16x16x32_bf16 v[2:5], v[176:179], v[216:219], v[2:5]
	v_mfma_f32_16x16x32_bf16 v[50:53], v[172:175], v[188:191], v[50:53]
	v_mfma_f32_16x16x32_bf16 v[42:45], v[180:183], v[188:191], v[42:45]
	v_mfma_f32_16x16x32_bf16 v[34:37], v[172:175], v[198:201], v[34:37]
	v_mfma_f32_16x16x32_bf16 v[26:29], v[180:183], v[198:201], v[26:29]
	v_mfma_f32_16x16x32_bf16 v[18:21], v[172:175], v[206:209], v[18:21]
	v_mfma_f32_16x16x32_bf16 v[10:13], v[180:183], v[206:209], v[10:13]
	v_mfma_f32_16x16x32_bf16 v[6:9], v[172:175], v[220:223], v[6:9]
	v_mfma_f32_16x16x32_bf16 v[2:5], v[180:183], v[220:223], v[2:5]
	s_setprio 1
	s_barrier
	s_andn2_b64 vcc, exec, s[26:27]
	s_mov_b64 s[28:29], -1
	s_mov_b64 s[26:27], 0
	s_mov_b64 s[36:37], 0x100
	s_cbranch_vccz .LBB0_983
	s_and_b64 vcc, exec, s[10:11]
	s_cbranch_vccz .LBB0_986
	s_barrier

; #define PG8_STAGE(bufoff, gbase, voff) do { _Pragma("unroll") for (int _i = 0; _i < 2; ++_i) \
;         __builtin_amdgcn_global_load_lds((const unsigned*)((const char*)(gbase) + (voff)[_i]), (PG8_LAS unsigned*)(lds + (bufoff) + ldsw + _i * 8192), 16, 0, 0); } while (0)
; #define PG8_LDA(dst, b, h) do { _Pragma("unroll") for (int m = 0; m < 4; ++m) _Pragma("unroll") for (int k = 0; k < 2; ++k) dst[m][k] = *(const PG8_LAS bf16x8*)(lds + PG8_SA(b, h) + aoff + m * 2048 + k * 1024); } while (0)
; #define PG8_LDB(dst, b, h) do { _Pragma("unroll") for (int n = 0; n < 2; ++n) _Pragma("unroll") for (int k = 0; k < 2; ++k) dst[n][k] = *(const PG8_LAS bf16x8*)(lds + PG8_SB(b, h) + boff + n * 2048 + k * 1024); } while (0)
; #define PG8_WAIT_V(n) asm volatile("s_waitcnt vmcnt(" #n ")" ::: "memory")
; #define PG8_WAIT_L(n) asm volatile("s_waitcnt lgkmcnt(" #n ")" ::: "memory")
; #define PG8_BAR __builtin_amdgcn_s_barrier()
; #define PG8_SCHED __builtin_amdgcn_sched_barrier(0)
; template <class Epi, class Sched, bool ALIGN_EPI = false, bool SP2 = false, bool I8 = false>
; __device__ __forceinline__ void gemm_phase(PG8_LAS unsigned char* lds, const Gemm g, const Sched& S, const Epi& E) {
;     ...
;             PG8_LDB(B0, 0, 0); PG8_LDB(B1, 0, 1); PG8_SCHED; PG8_LDA(At, 0, 0); PG8_STAGE(PG8_SA(1, 1), a1 + hstepA, voffA);
;             PG8_WAIT_V(8); PG8_WAIT_L(0); PG8_BAR; PG8_MMA(0, 0, At, B0); PG8_MMA(0, 1, At, B1); PG8_BAR; PG8_SCHED;
;             PG8_LDA(At, 0, 1); PG8_STAGE(PG8_SB(0, 0), b2, voffB); PG8_STAGE(PG8_SB(0, 1), b2 + hstepB, voffB); PG8_STAGE(PG8_SA(0, 0), a2, voffA);
.LBB0_1002:
	ds_read_b128 v[144:147], v157
	ds_read_b128 v[160:163], v157 offset:1024
	ds_read_b128 v[164:167], v157 offset:2048
	ds_read_b128 v[168:171], v157 offset:3072
	ds_read_b128 v[172:175], v158
	ds_read_b128 v[176:179], v158 offset:1024
	ds_read_b128 v[180:183], v158 offset:2048
	ds_read_b128 v[184:187], v158 offset:3072
	s_add_u32 s24, s6, 0xfffe0080
	s_addc_u32 s25, s7, -1
	s_cmp_eq_u32 s65, 4
	s_cselect_b32 s37, s59, s25
	s_cselect_b32 s36, s60, s24
	s_cselect_b32 s25, s61, s64
	s_cselect_b32 s24, s62, s63
	v_lshl_add_u64 v[148:149], s[6:7], 0, v[140:141]
	s_add_i32 m0, s9, 0xc000
	ds_read_b128 v[188:191], v159
	ds_read_b128 v[192:195], v159 offset:1024
	ds_read_b128 v[196:199], v159 offset:2048
	ds_read_b128 v[200:203], v159 offset:3072
	ds_read_b128 v[204:207], v159 offset:4096
	ds_read_b128 v[216:219], v159 offset:5120
	ds_read_b128 v[220:223], v159 offset:6144
	ds_read_b128 v[224:227], v159 offset:7168
	global_load_lds_dwordx4 v[148:149], off
	v_lshl_add_u64 v[148:149], s[6:7], 0, v[142:143]
	s_add_i32 m0, s9, 0xe000
	s_nop 0
	global_load_lds_dwordx4 v[148:149], off
	s_waitcnt vmcnt(8)
	s_waitcnt lgkmcnt(0)
	s_barrier
	s_setprio 0
	s_waitcnt lgkmcnt(0)
	v_mfma_f32_16x16x32_bf16 v[126:129], v[144:147], v[188:191], v[126:129]
	v_mfma_f32_16x16x32_bf16 v[122:125], v[164:167], v[188:191], v[122:125]
	v_mfma_f32_16x16x32_bf16 v[110:113], v[144:147], v[196:199], v[110:113]
	v_mfma_f32_16x16x32_bf16 v[106:109], v[164:167], v[196:199], v[106:109]
	v_mfma_f32_16x16x32_bf16 v[94:97], v[144:147], v[204:207], v[94:97]
	v_mfma_f32_16x16x32_bf16 v[90:93], v[164:167], v[204:207], v[90:93]
	v_mfma_f32_16x16x32_bf16 v[78:81], v[144:147], v[220:223], v[78:81]
	v_mfma_f32_16x16x32_bf16 v[74:77], v[164:167], v[220:223], v[74:77]
	v_mfma_f32_16x16x32_bf16 v[126:129], v[160:163], v[192:195], v[126:129]
	v_mfma_f32_16x16x32_bf16 v[122:125], v[168:171], v[192:195], v[122:125]
	v_mfma_f32_16x16x32_bf16 v[110:113], v[160:163], v[200:203], v[110:113]
	v_mfma_f32_16x16x32_bf16 v[106:109], v[168:171], v[200:203], v[106:109]
	v_mfma_f32_16x16x32_bf16 v[94:97], v[160:163], v[216:219], v[94:97]
	v_mfma_f32_16x16x32_bf16 v[90:93], v[168:171], v[216:219], v[90:93]
	v_mfma_f32_16x16x32_bf16 v[78:81], v[160:163], v[224:227], v[78:81]
	v_mfma_f32_16x16x32_bf16 v[74:77], v[168:171], v[224:227], v[74:77]
	s_setprio 1
	s_setprio 0
	v_mfma_f32_16x16x32_bf16 v[118:121], v[172:175], v[188:191], v[118:121]
	v_mfma_f32_16x16x32_bf16 v[114:117], v[180:183], v[188:191], v[114:117]
	v_mfma_f32_16x16x32_bf16 v[102:105], v[172:175], v[196:199], v[102:105]
	v_mfma_f32_16x16x32_bf16 v[98:101], v[180:183], v[196:199], v[98:101]
	v_mfma_f32_16x16x32_bf16 v[86:89], v[172:175], v[204:207], v[86:89]
	v_mfma_f32_16x16x32_bf16 v[82:85], v[180:183], v[204:207], v[82:85]
	v_mfma_f32_16x16x32_bf16 v[70:73], v[172:175], v[220:223], v[70:73]
	v_mfma_f32_16x16x32_bf16 v[66:69], v[180:183], v[220:223], v[66:69]
	v_mfma_f32_16x16x32_bf16 v[118:121], v[176:179], v[192:195], v[118:121]
	v_mfma_f32_16x16x32_bf16 v[114:117], v[184:187], v[192:195], v[114:117]
	v_mfma_f32_16x16x32_bf16 v[102:105], v[176:179], v[200:203], v[102:105]
	v_mfma_f32_16x16x32_bf16 v[98:101], v[184:187], v[200:203], v[98:101]
	v_mfma_f32_16x16x32_bf16 v[86:89], v[176:179], v[216:219], v[86:89]
	v_mfma_f32_16x16x32_bf16 v[82:85], v[184:187], v[216:219], v[82:85]
	v_mfma_f32_16x16x32_bf16 v[70:73], v[176:179], v[224:227], v[70:73]
	v_mfma_f32_16x16x32_bf16 v[66:69], v[184:187], v[224:227], v[66:69]
	s_setprio 1
	s_barrier
	s_add_i32 s70, s54, s38
	v_lshl_add_u64 v[148:149], s[24:25], 0, v[134:135]
	s_mov_b32 m0, s70
	ds_read_b128 v[188:191], v159 offset:16384
	ds_read_b128 v[192:195], v159 offset:17408
	ds_read_b128 v[196:199], v159 offset:18432
	ds_read_b128 v[200:203], v159 offset:19456
	ds_read_b128 v[204:207], v159 offset:20480
	ds_read_b128 v[216:219], v159 offset:21504
	ds_read_b128 v[220:223], v159 offset:22528
	ds_read_b128 v[224:227], v159 offset:23552
	global_load_lds_dwordx4 v[148:149], off
	s_add_i32 m0, s70, 0x2000
	s_add_u32 s70, s24, 0x20000
	v_lshl_add_u64 v[208:209], s[24:25], 0, v[130:131]
	s_addc_u32 s71, s25, 0
	s_add_i32 s72, s55, s38
	global_load_lds_dwordx4 v[208:209], off
	v_lshl_add_u64 v[228:229], s[70:71], 0, v[134:135]
	s_mov_b32 m0, s72
	v_lshl_add_u64 v[230:231], s[36:37], 0, v[132:133]
	global_load_lds_dwordx4 v[228:229], off
	v_lshl_add_u64 v[228:229], s[70:71], 0, v[130:131]
	s_add_i32 m0, s72, 0x2000
	s_nop 0
	global_load_lds_dwordx4 v[228:229], off
	v_lshl_add_u64 v[228:229], s[36:37], 0, v[136:137]
	s_mov_b32 m0, s9
	s_nop 0
	global_load_lds_dwordx4 v[228:229], off
	s_mov_b32 m0, s41
	s_nop 0
	global_load_lds_dwordx4 v[230:231], off
	s_waitcnt vmcnt(8)
	s_waitcnt lgkmcnt(0)
	s_barrier
; #define PG8_STAGE(bufoff, gbase, voff) do { _Pragma("unroll") for (int _i = 0; _i < 2; ++_i) \
;         __builtin_amdgcn_global_load_lds((const unsigned*)((const char*)(gbase) + (voff)[_i]), (PG8_LAS unsigned*)(lds + (bufoff) + ldsw + _i * 8192), 16, 0, 0); } while (0)
; #define PG8_LDA(dst, b, h) do { _Pragma("unroll") for (int m = 0; m < 4; ++m) _Pragma("unroll") for (int k = 0; k < 2; ++k) dst[m][k] = *(const PG8_LAS bf16x8*)(lds + PG8_SA(b, h) + aoff + m * 2048 + k * 1024); } while (0)
; #define PG8_LDB(dst, b, h) do { _Pragma("unroll") for (int n = 0; n < 2; ++n) _Pragma("unroll") for (int k = 0; k < 2; ++k) dst[n][k] = *(const PG8_LAS bf16x8*)(lds + PG8_SB(b, h) + boff + n * 2048 + k * 1024); } while (0)
; #define PG8_WAIT_V(n) asm volatile("s_waitcnt vmcnt(" #n ")" ::: "memory")
; #define PG8_WAIT_L(n) asm volatile("s_waitcnt lgkmcnt(" #n ")" ::: "memory")
; #define PG8_BAR __builtin_amdgcn_s_barrier()
; #define PG8_SCHED __builtin_amdgcn_sched_barrier(0)
; template <class Epi, class Sched, bool ALIGN_EPI = false, bool SP2 = false, bool I8 = false>
; __device__ __forceinline__ void gemm_phase(PG8_LAS unsigned char* lds, const Gemm g, const Sched& S, const Epi& E) {
;     ...
;             PG8_WAIT_V(8); PG8_WAIT_L(0); PG8_BAR; PG8_MMA(1, 0, At, B0); PG8_MMA(1, 1, At, B1); PG8_BAR; PG8_SCHED;
;             PG8_LDB(B0, 1, 0); PG8_LDB(B1, 1, 1); PG8_SCHED; PG8_LDA(At, 1, 0); PG8_STAGE(PG8_SA(0, 1), a2 + hstepA, voffA);
;             PG8_WAIT_V(8); PG8_WAIT_L(0); PG8_BAR; PG8_MMA(0, 0, At, B0); PG8_MMA(0, 1, At, B1); PG8_BAR; PG8_SCHED;
	s_setprio 0
	s_waitcnt lgkmcnt(0)
	v_mfma_f32_16x16x32_bf16 v[62:65], v[144:147], v[188:191], v[62:65]
	v_mfma_f32_16x16x32_bf16 v[58:61], v[164:167], v[188:191], v[58:61]
	v_mfma_f32_16x16x32_bf16 v[46:49], v[144:147], v[196:199], v[46:49]
	v_mfma_f32_16x16x32_bf16 v[42:45], v[164:167], v[196:199], v[42:45]
	v_mfma_f32_16x16x32_bf16 v[30:33], v[144:147], v[204:207], v[30:33]
	v_mfma_f32_16x16x32_bf16 v[26:29], v[164:167], v[204:207], v[26:29]
	v_mfma_f32_16x16x32_bf16 v[14:17], v[144:147], v[220:223], v[14:17]
	v_mfma_f32_16x16x32_bf16 v[10:13], v[164:167], v[220:223], v[10:13]
	v_mfma_f32_16x16x32_bf16 v[62:65], v[160:163], v[192:195], v[62:65]
	v_mfma_f32_16x16x32_bf16 v[58:61], v[168:171], v[192:195], v[58:61]
	v_mfma_f32_16x16x32_bf16 v[46:49], v[160:163], v[200:203], v[46:49]
	v_mfma_f32_16x16x32_bf16 v[42:45], v[168:171], v[200:203], v[42:45]
	v_mfma_f32_16x16x32_bf16 v[30:33], v[160:163], v[216:219], v[30:33]
	v_mfma_f32_16x16x32_bf16 v[26:29], v[168:171], v[216:219], v[26:29]
	v_mfma_f32_16x16x32_bf16 v[14:17], v[160:163], v[224:227], v[14:17]
	v_mfma_f32_16x16x32_bf16 v[10:13], v[168:171], v[224:227], v[10:13]
	s_setprio 1
	s_setprio 0
	v_mfma_f32_16x16x32_bf16 v[54:57], v[172:175], v[188:191], v[54:57]
	v_mfma_f32_16x16x32_bf16 v[50:53], v[180:183], v[188:191], v[50:53]
	v_mfma_f32_16x16x32_bf16 v[38:41], v[172:175], v[196:199], v[38:41]
	v_mfma_f32_16x16x32_bf16 v[34:37], v[180:183], v[196:199], v[34:37]
	v_mfma_f32_16x16x32_bf16 v[22:25], v[172:175], v[204:207], v[22:25]
	v_mfma_f32_16x16x32_bf16 v[18:21], v[180:183], v[204:207], v[18:21]
	v_mfma_f32_16x16x32_bf16 v[6:9], v[172:175], v[220:223], v[6:9]
	v_mfma_f32_16x16x32_bf16 v[2:5], v[180:183], v[220:223], v[2:5]
	v_mfma_f32_16x16x32_bf16 v[54:57], v[176:179], v[192:195], v[54:57]
	v_mfma_f32_16x16x32_bf16 v[50:53], v[184:187], v[192:195], v[50:53]
	v_mfma_f32_16x16x32_bf16 v[38:41], v[176:179], v[200:203], v[38:41]
	v_mfma_f32_16x16x32_bf16 v[34:37], v[184:187], v[200:203], v[34:37]
	v_mfma_f32_16x16x32_bf16 v[22:25], v[176:179], v[216:219], v[22:25]
	v_mfma_f32_16x16x32_bf16 v[18:21], v[184:187], v[216:219], v[18:21]
	v_mfma_f32_16x16x32_bf16 v[6:9], v[176:179], v[224:227], v[6:9]
	v_mfma_f32_16x16x32_bf16 v[2:5], v[184:187], v[224:227], v[2:5]
	s_setprio 1
	s_barrier
	s_add_i32 s70, 0, 0x18000
	s_add_i32 s71, 0, 0x1c000
	v_add_u32_e32 v168, s70, v151
	v_add_u32_e32 v184, s71, v151
	ds_read_b128 v[144:147], v168
	ds_read_b128 v[160:163], v168 offset:1024
	ds_read_b128 v[164:167], v168 offset:2048
	ds_read_b128 v[168:171], v168 offset:3072
	ds_read_b128 v[172:175], v184
	ds_read_b128 v[176:179], v184 offset:1024
	ds_read_b128 v[180:183], v184 offset:2048
	ds_read_b128 v[184:187], v184 offset:3072
	s_add_u32 s36, s36, 0x20000
	s_addc_u32 s37, s37, 0
	s_mov_b32 m0, s42
	v_lshl_add_u64 v[232:233], s[36:37], 0, v[136:137]
	ds_read_b128 v[188:191], v159 offset:32768
	ds_read_b128 v[192:195], v159 offset:33792
	ds_read_b128 v[196:199], v159 offset:34816
	ds_read_b128 v[200:203], v159 offset:35840
	ds_read_b128 v[204:207], v159 offset:36864
	ds_read_b128 v[216:219], v159 offset:37888
	ds_read_b128 v[220:223], v159 offset:38912
	ds_read_b128 v[224:227], v159 offset:39936
	global_load_lds_dwordx4 v[232:233], off
	v_lshl_add_u64 v[232:233], s[36:37], 0, v[132:133]
	s_mov_b32 m0, s43
	s_nop 0
	global_load_lds_dwordx4 v[232:233], off
	s_waitcnt vmcnt(8)
	s_waitcnt lgkmcnt(0)
	s_barrier
	s_setprio 0
	s_waitcnt lgkmcnt(0)
	v_mfma_f32_16x16x32_bf16 v[126:129], v[144:147], v[188:191], v[126:129]
	v_mfma_f32_16x16x32_bf16 v[122:125], v[164:167], v[188:191], v[122:125]
	v_mfma_f32_16x16x32_bf16 v[110:113], v[144:147], v[196:199], v[110:113]
	v_mfma_f32_16x16x32_bf16 v[106:109], v[164:167], v[196:199], v[106:109]
	v_mfma_f32_16x16x32_bf16 v[94:97], v[144:147], v[204:207], v[94:97]
	v_mfma_f32_16x16x32_bf16 v[90:93], v[164:167], v[204:207], v[90:93]
	v_mfma_f32_16x16x32_bf16 v[78:81], v[144:147], v[220:223], v[78:81]
	v_mfma_f32_16x16x32_bf16 v[74:77], v[164:167], v[220:223], v[74:77]
	v_mfma_f32_16x16x32_bf16 v[126:129], v[160:163], v[192:195], v[126:129]
	v_mfma_f32_16x16x32_bf16 v[122:125], v[168:171], v[192:195], v[122:125]
	v_mfma_f32_16x16x32_bf16 v[110:113], v[160:163], v[200:203], v[110:113]
	v_mfma_f32_16x16x32_bf16 v[106:109], v[168:171], v[200:203], v[106:109]
	v_mfma_f32_16x16x32_bf16 v[94:97], v[160:163], v[216:219], v[94:97]
	v_mfma_f32_16x16x32_bf16 v[90:93], v[168:171], v[216:219], v[90:93]
	v_mfma_f32_16x16x32_bf16 v[78:81], v[160:163], v[224:227], v[78:81]
	v_mfma_f32_16x16x32_bf16 v[74:77], v[168:171], v[224:227], v[74:77]
	s_setprio 1
	s_setprio 0
	v_mfma_f32_16x16x32_bf16 v[118:121], v[172:175], v[188:191], v[118:121]
	v_mfma_f32_16x16x32_bf16 v[114:117], v[180:183], v[188:191], v[114:117]
	v_mfma_f32_16x16x32_bf16 v[102:105], v[172:175], v[196:199], v[102:105]
	v_mfma_f32_16x16x32_bf16 v[98:101], v[180:183], v[196:199], v[98:101]
	v_mfma_f32_16x16x32_bf16 v[86:89], v[172:175], v[204:207], v[86:89]
	v_mfma_f32_16x16x32_bf16 v[82:85], v[180:183], v[204:207], v[82:85]
	v_mfma_f32_16x16x32_bf16 v[70:73], v[172:175], v[220:223], v[70:73]
	v_mfma_f32_16x16x32_bf16 v[66:69], v[180:183], v[220:223], v[66:69]
	v_mfma_f32_16x16x32_bf16 v[118:121], v[176:179], v[192:195], v[118:121]
	v_mfma_f32_16x16x32_bf16 v[114:117], v[184:187], v[192:195], v[114:117]
	v_mfma_f32_16x16x32_bf16 v[102:105], v[176:179], v[200:203], v[102:105]
	v_mfma_f32_16x16x32_bf16 v[98:101], v[184:187], v[200:203], v[98:101]
	v_mfma_f32_16x16x32_bf16 v[86:89], v[176:179], v[216:219], v[86:89]
	v_mfma_f32_16x16x32_bf16 v[82:85], v[184:187], v[216:219], v[82:85]
	v_mfma_f32_16x16x32_bf16 v[70:73], v[176:179], v[224:227], v[70:73]
	v_mfma_f32_16x16x32_bf16 v[66:69], v[184:187], v[224:227], v[66:69]
	s_setprio 1
	s_barrier
; #define PG8_STAGE(bufoff, gbase, voff) do { _Pragma("unroll") for (int _i = 0; _i < 2; ++_i) \
;         __builtin_amdgcn_global_load_lds((const unsigned*)((const char*)(gbase) + (voff)[_i]), (PG8_LAS unsigned*)(lds + (bufoff) + ldsw + _i * 8192), 16, 0, 0); } while (0)
; #define PG8_LDA(dst, b, h) do { _Pragma("unroll") for (int m = 0; m < 4; ++m) _Pragma("unroll") for (int k = 0; k < 2; ++k) dst[m][k] = *(const PG8_LAS bf16x8*)(lds + PG8_SA(b, h) + aoff + m * 2048 + k * 1024); } while (0)
; #define PG8_WAIT_V(n) asm volatile("s_waitcnt vmcnt(" #n ")" ::: "memory")
; #define PG8_WAIT_L(n) asm volatile("s_waitcnt lgkmcnt(" #n ")" ::: "memory")
; #define PG8_BAR __builtin_amdgcn_s_barrier()
; #define PG8_SCHED __builtin_amdgcn_sched_barrier(0)
; template <class Epi, class Sched, bool ALIGN_EPI = false, bool SP2 = false, bool I8 = false>
; __device__ __forceinline__ void gemm_phase(PG8_LAS unsigned char* lds, const Gemm g, const Sched& S, const Epi& E) {
;     ...
;         for (int t = 0; t < nt; t += 2) {
;             const bool last = (t == nt - 2);
;             const char* a1 = cA + (size_t)(t + 1) * kstepA;
;             const char* a2 = last ? nA : cA + (size_t)(t + 2) * kstepA; const char* b2 = last ? nB : cB + (size_t)(t + 2) * kstepB;
;             const char* a3 = a2 + kstepA; const char* b3 = b2 + kstepB;
;             if (last && has_next) S.a_ready(nxt);
;     ...
;             PG8_LDA(At, 1, 1); PG8_STAGE(PG8_SB(1, 0), b3, voffB); PG8_STAGE(PG8_SB(1, 1), b3 + hstepB, voffB); PG8_STAGE(PG8_SA(1, 0), a3, voffA);
;             PG8_WAIT_V(8); PG8_WAIT_L(0); PG8_BAR; PG8_MMA(1, 0, At, B0); PG8_MMA(1, 1, At, B1); PG8_BAR; PG8_SCHED;
	s_add_i32 s36, s70, s38
	v_lshl_add_u64 v[148:149], v[148:149], 0, s[14:15]
	s_mov_b32 m0, s36
	ds_read_b128 v[188:191], v159 offset:49152
	ds_read_b128 v[192:195], v159 offset:50176
	ds_read_b128 v[196:199], v159 offset:51200
	ds_read_b128 v[200:203], v159 offset:52224
	ds_read_b128 v[204:207], v159 offset:53248
	ds_read_b128 v[216:219], v159 offset:54272
	ds_read_b128 v[220:223], v159 offset:55296
	ds_read_b128 v[224:227], v159 offset:56320
	global_load_lds_dwordx4 v[148:149], off
	s_add_i32 m0, s36, 0x2000
	s_add_u32 s24, s24, 0x20080
	v_lshl_add_u64 v[148:149], v[208:209], 0, s[14:15]
	s_addc_u32 s25, s25, 0
	s_add_i32 s36, s71, s38
	global_load_lds_dwordx4 v[148:149], off
	v_lshl_add_u64 v[148:149], s[24:25], 0, v[134:135]
	s_mov_b32 m0, s36
	s_nop 0
	global_load_lds_dwordx4 v[148:149], off
	v_lshl_add_u64 v[148:149], s[24:25], 0, v[130:131]
	s_add_i32 m0, s36, 0x2000
	s_nop 0
	global_load_lds_dwordx4 v[148:149], off
	v_lshl_add_u64 v[148:149], v[228:229], 0, s[14:15]
	s_mov_b32 m0, s52
	s_nop 0
	global_load_lds_dwordx4 v[148:149], off
	v_lshl_add_u64 v[148:149], v[230:231], 0, s[14:15]
	s_mov_b32 m0, s53
	s_nop 0
	global_load_lds_dwordx4 v[148:149], off
	s_waitcnt vmcnt(8)
	s_waitcnt lgkmcnt(0)
	s_barrier
	s_setprio 0
	s_waitcnt lgkmcnt(0)
	v_mfma_f32_16x16x32_bf16 v[62:65], v[144:147], v[188:191], v[62:65]
	v_mfma_f32_16x16x32_bf16 v[58:61], v[164:167], v[188:191], v[58:61]
	v_mfma_f32_16x16x32_bf16 v[46:49], v[144:147], v[196:199], v[46:49]
	v_mfma_f32_16x16x32_bf16 v[42:45], v[164:167], v[196:199], v[42:45]
	v_mfma_f32_16x16x32_bf16 v[30:33], v[144:147], v[204:207], v[30:33]
	v_mfma_f32_16x16x32_bf16 v[26:29], v[164:167], v[204:207], v[26:29]
	v_mfma_f32_16x16x32_bf16 v[14:17], v[144:147], v[220:223], v[14:17]
	v_mfma_f32_16x16x32_bf16 v[10:13], v[164:167], v[220:223], v[10:13]
	v_mfma_f32_16x16x32_bf16 v[62:65], v[160:163], v[192:195], v[62:65]
	v_mfma_f32_16x16x32_bf16 v[58:61], v[168:171], v[192:195], v[58:61]
	v_mfma_f32_16x16x32_bf16 v[46:49], v[160:163], v[200:203], v[46:49]
	v_mfma_f32_16x16x32_bf16 v[42:45], v[168:171], v[200:203], v[42:45]
	v_mfma_f32_16x16x32_bf16 v[30:33], v[160:163], v[216:219], v[30:33]
	v_mfma_f32_16x16x32_bf16 v[26:29], v[168:171], v[216:219], v[26:29]
	v_mfma_f32_16x16x32_bf16 v[14:17], v[160:163], v[224:227], v[14:17]
	v_mfma_f32_16x16x32_bf16 v[10:13], v[168:171], v[224:227], v[10:13]
	s_setprio 1
	s_setprio 0
	v_mfma_f32_16x16x32_bf16 v[54:57], v[172:175], v[188:191], v[54:57]
	v_mfma_f32_16x16x32_bf16 v[50:53], v[180:183], v[188:191], v[50:53]
	v_mfma_f32_16x16x32_bf16 v[38:41], v[172:175], v[196:199], v[38:41]
	v_mfma_f32_16x16x32_bf16 v[34:37], v[180:183], v[196:199], v[34:37]
	v_mfma_f32_16x16x32_bf16 v[22:25], v[172:175], v[204:207], v[22:25]
	v_mfma_f32_16x16x32_bf16 v[18:21], v[180:183], v[204:207], v[18:21]
	v_mfma_f32_16x16x32_bf16 v[6:9], v[172:175], v[220:223], v[6:9]
	v_mfma_f32_16x16x32_bf16 v[2:5], v[180:183], v[220:223], v[2:5]
	v_mfma_f32_16x16x32_bf16 v[54:57], v[176:179], v[192:195], v[54:57]
	v_mfma_f32_16x16x32_bf16 v[50:53], v[184:187], v[192:195], v[50:53]
	v_mfma_f32_16x16x32_bf16 v[38:41], v[176:179], v[200:203], v[38:41]
	v_mfma_f32_16x16x32_bf16 v[34:37], v[184:187], v[200:203], v[34:37]
	v_mfma_f32_16x16x32_bf16 v[22:25], v[176:179], v[216:219], v[22:25]
	v_mfma_f32_16x16x32_bf16 v[18:21], v[184:187], v[216:219], v[18:21]
	v_mfma_f32_16x16x32_bf16 v[6:9], v[176:179], v[224:227], v[6:9]
	v_mfma_f32_16x16x32_bf16 v[2:5], v[184:187], v[224:227], v[2:5]
	s_setprio 1
	s_barrier
	s_add_i32 s65, s65, 2
	s_add_u32 s6, s6, 0x100
	s_addc_u32 s7, s7, 0
	s_add_u32 s63, s63, 0x100
	s_addc_u32 s64, s64, 0
	s_cmp_gt_u32 s65, 5
	s_cbranch_scc0 .LBB0_1002
	s_and_b64 vcc, exec, s[16:17]
	s_cbranch_vccz .LBB0_1005
	s_barrier

; #define PG8_STAGE(bufoff, gbase, voff) do { _Pragma("unroll") for (int _i = 0; _i < 2; ++_i) \
;         __builtin_amdgcn_global_load_lds((const unsigned*)((const char*)(gbase) + (voff)[_i]), (PG8_LAS unsigned*)(lds + (bufoff) + ldsw + _i * 8192), 16, 0, 0); } while (0)
; #define PG8_LDA(dst, b, h) do { _Pragma("unroll") for (int m = 0; m < 4; ++m) _Pragma("unroll") for (int k = 0; k < 2; ++k) dst[m][k] = *(const PG8_LAS bf16x8*)(lds + PG8_SA(b, h) + aoff + m * 2048 + k * 1024); } while (0)
; #define PG8_LDB(dst, b, h) do { _Pragma("unroll") for (int n = 0; n < 2; ++n) _Pragma("unroll") for (int k = 0; k < 2; ++k) dst[n][k] = *(const PG8_LAS bf16x8*)(lds + PG8_SB(b, h) + boff + n * 2048 + k * 1024); } while (0)
; #define PG8_WAIT_V(n) asm volatile("s_waitcnt vmcnt(" #n ")" ::: "memory")
; #define PG8_WAIT_L(n) asm volatile("s_waitcnt lgkmcnt(" #n ")" ::: "memory")
; #define PG8_BAR __builtin_amdgcn_s_barrier()
; #define PG8_SCHED __builtin_amdgcn_sched_barrier(0)
; template <class Epi, class Sched, bool ALIGN_EPI = false, bool SP2 = false, bool I8 = false>
; __device__ __forceinline__ void gemm_phase(PG8_LAS unsigned char* lds, const Gemm g, const Sched& S, const Epi& E) {
;     ...
;             PG8_LDB(B0, 0, 0); PG8_LDB(B1, 0, 1); PG8_SCHED; PG8_LDA(At, 0, 0); PG8_STAGE(PG8_SA(1, 1), a1 + hstepA, voffA);
;             PG8_WAIT_V(8); PG8_WAIT_L(0); PG8_BAR; PG8_MMA(0, 0, At, B0); PG8_MMA(0, 1, At, B1); PG8_BAR; PG8_SCHED;
;             PG8_LDA(At, 0, 1); PG8_STAGE(PG8_SB(0, 0), b2, voffB); PG8_STAGE(PG8_SB(0, 1), b2 + hstepB, voffB); PG8_STAGE(PG8_SA(0, 0), a2, voffA);
.LBB0_1184:
	ds_read_b128 v[66:69], v195
	ds_read_b128 v[70:73], v195 offset:1024
	ds_read_b128 v[138:141], v195 offset:2048
	ds_read_b128 v[142:145], v195 offset:3072
	ds_read_b128 v[146:149], v196
	ds_read_b128 v[150:153], v196 offset:1024
	ds_read_b128 v[154:157], v196 offset:2048
	ds_read_b128 v[158:161], v196 offset:3072
	s_add_u32 s20, s18, 0x4000
	s_addc_u32 s21, s19, 0
	s_cmp_eq_u32 s53, 28
	s_cselect_b32 s24, s47, s20
	s_cselect_b32 s25, s11, s21
	s_cselect_b32 s22, s48, s49
	s_cselect_b32 s23, s9, s52
	s_add_u32 s20, s24, 0x8000
	s_addc_u32 s21, s25, 0
	v_lshl_add_u64 v[190:191], s[18:19], 0, v[174:175]
	s_add_i32 m0, s28, 0xc000
	ds_read_b128 v[182:185], v197
	ds_read_b128 v[186:189], v197 offset:1024
	ds_read_b128 v[198:201], v197 offset:2048
	ds_read_b128 v[202:205], v197 offset:3072
	ds_read_b128 v[206:209], v197 offset:4096
	ds_read_b128 v[216:219], v197 offset:5120
	ds_read_b128 v[220:223], v197 offset:6144
	ds_read_b128 v[224:227], v197 offset:7168
	global_load_lds_dwordx4 v[190:191], off
	v_lshl_add_u64 v[190:191], s[18:19], 0, v[176:177]
	s_add_i32 m0, s28, 0xe000
	s_nop 0
	global_load_lds_dwordx4 v[190:191], off
	s_waitcnt vmcnt(8)
	s_waitcnt lgkmcnt(0)
	s_barrier
	s_setprio 0
	s_waitcnt lgkmcnt(0)
	v_mfma_i32_16x16x64_i8 v[62:65], v[66:69], v[182:185], v[62:65]
	v_mfma_i32_16x16x64_i8 v[58:61], v[138:141], v[182:185], v[58:61]
	v_mfma_i32_16x16x64_i8 v[126:129], v[66:69], v[198:201], v[126:129]
	v_mfma_i32_16x16x64_i8 v[122:125], v[138:141], v[198:201], v[122:125]
	v_mfma_i32_16x16x64_i8 v[110:113], v[66:69], v[206:209], v[110:113]
	v_mfma_i32_16x16x64_i8 v[106:109], v[138:141], v[206:209], v[106:109]
	v_mfma_i32_16x16x64_i8 v[94:97], v[66:69], v[220:223], v[94:97]
	v_mfma_i32_16x16x64_i8 v[90:93], v[138:141], v[220:223], v[90:93]
	v_mfma_i32_16x16x64_i8 v[62:65], v[70:73], v[186:189], v[62:65]
	v_mfma_i32_16x16x64_i8 v[58:61], v[142:145], v[186:189], v[58:61]
	v_mfma_i32_16x16x64_i8 v[126:129], v[70:73], v[202:205], v[126:129]
	v_mfma_i32_16x16x64_i8 v[122:125], v[142:145], v[202:205], v[122:125]
	v_mfma_i32_16x16x64_i8 v[110:113], v[70:73], v[216:219], v[110:113]
	v_mfma_i32_16x16x64_i8 v[106:109], v[142:145], v[216:219], v[106:109]
	v_mfma_i32_16x16x64_i8 v[94:97], v[70:73], v[224:227], v[94:97]
	v_mfma_i32_16x16x64_i8 v[90:93], v[142:145], v[224:227], v[90:93]
	s_setprio 1
	s_setprio 0
	v_mfma_i32_16x16x64_i8 v[134:137], v[146:149], v[182:185], v[134:137]
	v_mfma_i32_16x16x64_i8 v[130:133], v[154:157], v[182:185], v[130:133]
	v_mfma_i32_16x16x64_i8 v[118:121], v[146:149], v[198:201], v[118:121]
	v_mfma_i32_16x16x64_i8 v[114:117], v[154:157], v[198:201], v[114:117]
	v_mfma_i32_16x16x64_i8 v[102:105], v[146:149], v[206:209], v[102:105]
	v_mfma_i32_16x16x64_i8 v[98:101], v[154:157], v[206:209], v[98:101]
	v_mfma_i32_16x16x64_i8 v[86:89], v[146:149], v[220:223], v[86:89]
	v_mfma_i32_16x16x64_i8 v[82:85], v[154:157], v[220:223], v[82:85]
	v_mfma_i32_16x16x64_i8 v[134:137], v[150:153], v[186:189], v[134:137]
	v_mfma_i32_16x16x64_i8 v[130:133], v[158:161], v[186:189], v[130:133]
	v_mfma_i32_16x16x64_i8 v[118:121], v[150:153], v[202:205], v[118:121]
	v_mfma_i32_16x16x64_i8 v[114:117], v[158:161], v[202:205], v[114:117]
	v_mfma_i32_16x16x64_i8 v[102:105], v[150:153], v[216:219], v[102:105]
	v_mfma_i32_16x16x64_i8 v[98:101], v[158:161], v[216:219], v[98:101]
	v_mfma_i32_16x16x64_i8 v[86:89], v[150:153], v[224:227], v[86:89]
	v_mfma_i32_16x16x64_i8 v[82:85], v[158:161], v[224:227], v[82:85]
	s_setprio 1
	s_barrier
	s_add_i32 s54, s44, s27
	v_lshl_add_u64 v[190:191], s[22:23], 0, v[164:165]
	s_mov_b32 m0, s54
	ds_read_b128 v[182:185], v197 offset:16384
	ds_read_b128 v[186:189], v197 offset:17408
	ds_read_b128 v[198:201], v197 offset:18432
	ds_read_b128 v[202:205], v197 offset:19456
	ds_read_b128 v[206:209], v197 offset:20480
	ds_read_b128 v[216:219], v197 offset:21504
	ds_read_b128 v[220:223], v197 offset:22528
	ds_read_b128 v[224:227], v197 offset:23552
	global_load_lds_dwordx4 v[190:191], off
	s_add_i32 m0, s54, 0x2000
	s_add_u32 s54, s22, 0x4000
	v_lshl_add_u64 v[190:191], s[22:23], 0, v[168:169]
	s_addc_u32 s55, s23, 0
	s_add_i32 s56, s45, s27
	global_load_lds_dwordx4 v[190:191], off
	v_lshl_add_u64 v[190:191], s[54:55], 0, v[164:165]
	s_mov_b32 m0, s56
	s_nop 0
	global_load_lds_dwordx4 v[190:191], off
	v_lshl_add_u64 v[190:191], s[54:55], 0, v[168:169]
	s_add_i32 m0, s56, 0x2000
	s_nop 0
	global_load_lds_dwordx4 v[190:191], off
	v_lshl_add_u64 v[190:191], s[24:25], 0, v[162:163]
	s_mov_b32 m0, s28
	s_nop 0
	global_load_lds_dwordx4 v[190:191], off
	v_lshl_add_u64 v[190:191], s[24:25], 0, v[166:167]
	s_mov_b32 m0, s29
	s_nop 0
	global_load_lds_dwordx4 v[190:191], off
	s_waitcnt vmcnt(8)
	s_waitcnt lgkmcnt(0)
	s_barrier
; #define PG8_STAGE(bufoff, gbase, voff) do { _Pragma("unroll") for (int _i = 0; _i < 2; ++_i) \
;         __builtin_amdgcn_global_load_lds((const unsigned*)((const char*)(gbase) + (voff)[_i]), (PG8_LAS unsigned*)(lds + (bufoff) + ldsw + _i * 8192), 16, 0, 0); } while (0)
; #define PG8_LDA(dst, b, h) do { _Pragma("unroll") for (int m = 0; m < 4; ++m) _Pragma("unroll") for (int k = 0; k < 2; ++k) dst[m][k] = *(const PG8_LAS bf16x8*)(lds + PG8_SA(b, h) + aoff + m * 2048 + k * 1024); } while (0)
; #define PG8_LDB(dst, b, h) do { _Pragma("unroll") for (int n = 0; n < 2; ++n) _Pragma("unroll") for (int k = 0; k < 2; ++k) dst[n][k] = *(const PG8_LAS bf16x8*)(lds + PG8_SB(b, h) + boff + n * 2048 + k * 1024); } while (0)
; #define PG8_WAIT_V(n) asm volatile("s_waitcnt vmcnt(" #n ")" ::: "memory")
; #define PG8_WAIT_L(n) asm volatile("s_waitcnt lgkmcnt(" #n ")" ::: "memory")
; #define PG8_BAR __builtin_amdgcn_s_barrier()
; #define PG8_SCHED __builtin_amdgcn_sched_barrier(0)
; template <class Epi, class Sched, bool ALIGN_EPI = false, bool SP2 = false, bool I8 = false>
; __device__ __forceinline__ void gemm_phase(PG8_LAS unsigned char* lds, const Gemm g, const Sched& S, const Epi& E) {
;     ...
;             PG8_WAIT_V(8); PG8_WAIT_L(0); PG8_BAR; PG8_MMA(1, 0, At, B0); PG8_MMA(1, 1, At, B1); PG8_BAR; PG8_SCHED;
;             PG8_LDB(B0, 1, 0); PG8_LDB(B1, 1, 1); PG8_SCHED; PG8_LDA(At, 1, 0); PG8_STAGE(PG8_SA(0, 1), a2 + hstepA, voffA);
;             PG8_WAIT_V(8); PG8_WAIT_L(0); PG8_BAR; PG8_MMA(0, 0, At, B0); PG8_MMA(0, 1, At, B1); PG8_BAR; PG8_SCHED;
	s_setprio 0
	s_waitcnt lgkmcnt(0)
	v_mfma_i32_16x16x64_i8 v[78:81], v[66:69], v[182:185], v[78:81]
	v_mfma_i32_16x16x64_i8 v[74:77], v[138:141], v[182:185], v[74:77]
	v_mfma_i32_16x16x64_i8 v[46:49], v[66:69], v[198:201], v[46:49]
	v_mfma_i32_16x16x64_i8 v[42:45], v[138:141], v[198:201], v[42:45]
	v_mfma_i32_16x16x64_i8 v[30:33], v[66:69], v[206:209], v[30:33]
	v_mfma_i32_16x16x64_i8 v[26:29], v[138:141], v[206:209], v[26:29]
	v_mfma_i32_16x16x64_i8 v[14:17], v[66:69], v[220:223], v[14:17]
	v_mfma_i32_16x16x64_i8 v[10:13], v[138:141], v[220:223], v[10:13]
	v_mfma_i32_16x16x64_i8 v[78:81], v[70:73], v[186:189], v[78:81]
	v_mfma_i32_16x16x64_i8 v[74:77], v[142:145], v[186:189], v[74:77]
	v_mfma_i32_16x16x64_i8 v[46:49], v[70:73], v[202:205], v[46:49]
	v_mfma_i32_16x16x64_i8 v[42:45], v[142:145], v[202:205], v[42:45]
	v_mfma_i32_16x16x64_i8 v[30:33], v[70:73], v[216:219], v[30:33]
	v_mfma_i32_16x16x64_i8 v[26:29], v[142:145], v[216:219], v[26:29]
	v_mfma_i32_16x16x64_i8 v[14:17], v[70:73], v[224:227], v[14:17]
	v_mfma_i32_16x16x64_i8 v[10:13], v[142:145], v[224:227], v[10:13]
	s_setprio 1
	s_setprio 0
	v_mfma_i32_16x16x64_i8 v[54:57], v[146:149], v[182:185], v[54:57]
	v_mfma_i32_16x16x64_i8 v[50:53], v[154:157], v[182:185], v[50:53]
	v_mfma_i32_16x16x64_i8 v[38:41], v[146:149], v[198:201], v[38:41]
	v_mfma_i32_16x16x64_i8 v[34:37], v[154:157], v[198:201], v[34:37]
	v_mfma_i32_16x16x64_i8 v[22:25], v[146:149], v[206:209], v[22:25]
	v_mfma_i32_16x16x64_i8 v[18:21], v[154:157], v[206:209], v[18:21]
	v_mfma_i32_16x16x64_i8 v[6:9], v[146:149], v[220:223], v[6:9]
	v_mfma_i32_16x16x64_i8 v[2:5], v[154:157], v[220:223], v[2:5]
	v_mfma_i32_16x16x64_i8 v[54:57], v[150:153], v[186:189], v[54:57]
	v_mfma_i32_16x16x64_i8 v[50:53], v[158:161], v[186:189], v[50:53]
	v_mfma_i32_16x16x64_i8 v[38:41], v[150:153], v[202:205], v[38:41]
	v_mfma_i32_16x16x64_i8 v[34:37], v[158:161], v[202:205], v[34:37]
	v_mfma_i32_16x16x64_i8 v[22:25], v[150:153], v[216:219], v[22:25]
	v_mfma_i32_16x16x64_i8 v[18:21], v[158:161], v[216:219], v[18:21]
	v_mfma_i32_16x16x64_i8 v[6:9], v[150:153], v[224:227], v[6:9]
	v_mfma_i32_16x16x64_i8 v[2:5], v[158:161], v[224:227], v[2:5]
	s_setprio 1
	s_barrier
	s_add_i32 s54, 0, 0x18000
	s_add_i32 s55, 0, 0x1c000
	v_add_u32_e32 v142, s54, v194
	v_add_u32_e32 v158, s55, v194
	ds_read_b128 v[66:69], v142
	ds_read_b128 v[70:73], v142 offset:1024
	ds_read_b128 v[138:141], v142 offset:2048
	ds_read_b128 v[142:145], v142 offset:3072
	ds_read_b128 v[146:149], v158
	ds_read_b128 v[150:153], v158 offset:1024
	ds_read_b128 v[154:157], v158 offset:2048
	ds_read_b128 v[158:161], v158 offset:3072
	s_add_u32 s24, s24, 0x4000
	s_addc_u32 s25, s25, 0
	s_mov_b32 m0, s36
	v_lshl_add_u64 v[190:191], s[24:25], 0, v[162:163]
	ds_read_b128 v[182:185], v197 offset:32768
	ds_read_b128 v[186:189], v197 offset:33792
	ds_read_b128 v[198:201], v197 offset:34816
	ds_read_b128 v[202:205], v197 offset:35840
	ds_read_b128 v[206:209], v197 offset:36864
	ds_read_b128 v[216:219], v197 offset:37888
	ds_read_b128 v[220:223], v197 offset:38912
	ds_read_b128 v[224:227], v197 offset:39936
	global_load_lds_dwordx4 v[190:191], off
	v_lshl_add_u64 v[190:191], s[24:25], 0, v[166:167]
	s_mov_b32 m0, s37
	s_nop 0
	global_load_lds_dwordx4 v[190:191], off
	s_waitcnt vmcnt(8)
	s_waitcnt lgkmcnt(0)
	s_barrier
	s_setprio 0
	s_waitcnt lgkmcnt(0)
	v_mfma_i32_16x16x64_i8 v[62:65], v[66:69], v[182:185], v[62:65]
	v_mfma_i32_16x16x64_i8 v[58:61], v[138:141], v[182:185], v[58:61]
	v_mfma_i32_16x16x64_i8 v[126:129], v[66:69], v[198:201], v[126:129]
	v_mfma_i32_16x16x64_i8 v[122:125], v[138:141], v[198:201], v[122:125]
	v_mfma_i32_16x16x64_i8 v[110:113], v[66:69], v[206:209], v[110:113]
	v_mfma_i32_16x16x64_i8 v[106:109], v[138:141], v[206:209], v[106:109]
	v_mfma_i32_16x16x64_i8 v[94:97], v[66:69], v[220:223], v[94:97]
	v_mfma_i32_16x16x64_i8 v[90:93], v[138:141], v[220:223], v[90:93]
	v_mfma_i32_16x16x64_i8 v[62:65], v[70:73], v[186:189], v[62:65]
	v_mfma_i32_16x16x64_i8 v[58:61], v[142:145], v[186:189], v[58:61]
	v_mfma_i32_16x16x64_i8 v[126:129], v[70:73], v[202:205], v[126:129]
	v_mfma_i32_16x16x64_i8 v[122:125], v[142:145], v[202:205], v[122:125]
	v_mfma_i32_16x16x64_i8 v[110:113], v[70:73], v[216:219], v[110:113]
	v_mfma_i32_16x16x64_i8 v[106:109], v[142:145], v[216:219], v[106:109]
	v_mfma_i32_16x16x64_i8 v[94:97], v[70:73], v[224:227], v[94:97]
	v_mfma_i32_16x16x64_i8 v[90:93], v[142:145], v[224:227], v[90:93]
	s_setprio 1
	s_setprio 0
	v_mfma_i32_16x16x64_i8 v[134:137], v[146:149], v[182:185], v[134:137]
	v_mfma_i32_16x16x64_i8 v[130:133], v[154:157], v[182:185], v[130:133]
	v_mfma_i32_16x16x64_i8 v[118:121], v[146:149], v[198:201], v[118:121]
	v_mfma_i32_16x16x64_i8 v[114:117], v[154:157], v[198:201], v[114:117]
	v_mfma_i32_16x16x64_i8 v[102:105], v[146:149], v[206:209], v[102:105]
	v_mfma_i32_16x16x64_i8 v[98:101], v[154:157], v[206:209], v[98:101]
	v_mfma_i32_16x16x64_i8 v[86:89], v[146:149], v[220:223], v[86:89]
	v_mfma_i32_16x16x64_i8 v[82:85], v[154:157], v[220:223], v[82:85]
	v_mfma_i32_16x16x64_i8 v[134:137], v[150:153], v[186:189], v[134:137]
	v_mfma_i32_16x16x64_i8 v[130:133], v[158:161], v[186:189], v[130:133]
	v_mfma_i32_16x16x64_i8 v[118:121], v[150:153], v[202:205], v[118:121]
	v_mfma_i32_16x16x64_i8 v[114:117], v[158:161], v[202:205], v[114:117]
	v_mfma_i32_16x16x64_i8 v[102:105], v[150:153], v[216:219], v[102:105]
	v_mfma_i32_16x16x64_i8 v[98:101], v[158:161], v[216:219], v[98:101]
	v_mfma_i32_16x16x64_i8 v[86:89], v[150:153], v[224:227], v[86:89]
	v_mfma_i32_16x16x64_i8 v[82:85], v[158:161], v[224:227], v[82:85]
	s_setprio 1
	s_barrier
; #define PG8_STAGE(bufoff, gbase, voff) do { _Pragma("unroll") for (int _i = 0; _i < 2; ++_i) \
;         __builtin_amdgcn_global_load_lds((const unsigned*)((const char*)(gbase) + (voff)[_i]), (PG8_LAS unsigned*)(lds + (bufoff) + ldsw + _i * 8192), 16, 0, 0); } while (0)
; #define PG8_LDA(dst, b, h) do { _Pragma("unroll") for (int m = 0; m < 4; ++m) _Pragma("unroll") for (int k = 0; k < 2; ++k) dst[m][k] = *(const PG8_LAS bf16x8*)(lds + PG8_SA(b, h) + aoff + m * 2048 + k * 1024); } while (0)
; #define PG8_WAIT_V(n) asm volatile("s_waitcnt vmcnt(" #n ")" ::: "memory")
; #define PG8_WAIT_L(n) asm volatile("s_waitcnt lgkmcnt(" #n ")" ::: "memory")
; #define PG8_BAR __builtin_amdgcn_s_barrier()
; #define PG8_SCHED __builtin_amdgcn_sched_barrier(0)
; template <class Epi, class Sched, bool ALIGN_EPI = false, bool SP2 = false, bool I8 = false>
; __device__ __forceinline__ void gemm_phase(PG8_LAS unsigned char* lds, const Gemm g, const Sched& S, const Epi& E) {
;     ...
;         for (int t = 0; t < nt; t += 2) {
;             const bool last = (t == nt - 2);
;             const char* a1 = cA + (size_t)(t + 1) * kstepA;
;             const char* a2 = last ? nA : cA + (size_t)(t + 2) * kstepA; const char* b2 = last ? nB : cB + (size_t)(t + 2) * kstepB;
;             const char* a3 = a2 + kstepA; const char* b3 = b2 + kstepB;
;             if (last && has_next) S.a_ready(nxt);
;     ...
;             PG8_LDA(At, 1, 1); PG8_STAGE(PG8_SB(1, 0), b3, voffB); PG8_STAGE(PG8_SB(1, 1), b3 + hstepB, voffB); PG8_STAGE(PG8_SA(1, 0), a3, voffA);
;             PG8_WAIT_V(8); PG8_WAIT_L(0); PG8_BAR; PG8_MMA(1, 0, At, B0); PG8_MMA(1, 1, At, B1); PG8_BAR; PG8_SCHED;
	s_add_u32 s24, s22, 0x8000
	s_addc_u32 s25, s23, 0
	s_add_i32 s54, s54, s27
	v_lshl_add_u64 v[190:191], s[24:25], 0, v[164:165]
	s_mov_b32 m0, s54
	ds_read_b128 v[182:185], v197 offset:49152
	ds_read_b128 v[186:189], v197 offset:50176
	ds_read_b128 v[198:201], v197 offset:51200
	ds_read_b128 v[202:205], v197 offset:52224
	ds_read_b128 v[206:209], v197 offset:53248
	ds_read_b128 v[216:219], v197 offset:54272
	ds_read_b128 v[220:223], v197 offset:55296
	ds_read_b128 v[224:227], v197 offset:56320
	global_load_lds_dwordx4 v[190:191], off
	s_add_i32 m0, s54, 0x2000
	s_add_u32 s22, s22, 0xc000
	v_lshl_add_u64 v[190:191], s[24:25], 0, v[168:169]
	s_addc_u32 s23, s23, 0
	s_add_i32 s24, s55, s27
	global_load_lds_dwordx4 v[190:191], off
	v_lshl_add_u64 v[190:191], s[22:23], 0, v[164:165]
	s_mov_b32 m0, s24
	s_nop 0
	global_load_lds_dwordx4 v[190:191], off
	v_lshl_add_u64 v[190:191], s[22:23], 0, v[168:169]
	s_add_i32 m0, s24, 0x2000
	s_nop 0
	global_load_lds_dwordx4 v[190:191], off
	v_lshl_add_u64 v[190:191], s[20:21], 0, v[162:163]
	s_mov_b32 m0, s41
	s_nop 0
	global_load_lds_dwordx4 v[190:191], off
	v_lshl_add_u64 v[190:191], s[20:21], 0, v[166:167]
	s_mov_b32 m0, s42
	s_nop 0
	global_load_lds_dwordx4 v[190:191], off
	s_waitcnt vmcnt(8)
	s_waitcnt lgkmcnt(0)
	s_barrier
	s_setprio 0
	s_waitcnt lgkmcnt(0)
	v_mfma_i32_16x16x64_i8 v[78:81], v[66:69], v[182:185], v[78:81]
	v_mfma_i32_16x16x64_i8 v[74:77], v[138:141], v[182:185], v[74:77]
	v_mfma_i32_16x16x64_i8 v[46:49], v[66:69], v[198:201], v[46:49]
	v_mfma_i32_16x16x64_i8 v[42:45], v[138:141], v[198:201], v[42:45]
	v_mfma_i32_16x16x64_i8 v[30:33], v[66:69], v[206:209], v[30:33]
	v_mfma_i32_16x16x64_i8 v[26:29], v[138:141], v[206:209], v[26:29]
	v_mfma_i32_16x16x64_i8 v[14:17], v[66:69], v[220:223], v[14:17]
	v_mfma_i32_16x16x64_i8 v[10:13], v[138:141], v[220:223], v[10:13]
	v_mfma_i32_16x16x64_i8 v[78:81], v[70:73], v[186:189], v[78:81]
	v_mfma_i32_16x16x64_i8 v[74:77], v[142:145], v[186:189], v[74:77]
	v_mfma_i32_16x16x64_i8 v[46:49], v[70:73], v[202:205], v[46:49]
	v_mfma_i32_16x16x64_i8 v[42:45], v[142:145], v[202:205], v[42:45]
	v_mfma_i32_16x16x64_i8 v[30:33], v[70:73], v[216:219], v[30:33]
	v_mfma_i32_16x16x64_i8 v[26:29], v[142:145], v[216:219], v[26:29]
	v_mfma_i32_16x16x64_i8 v[14:17], v[70:73], v[224:227], v[14:17]
	v_mfma_i32_16x16x64_i8 v[10:13], v[142:145], v[224:227], v[10:13]
	s_setprio 1
	s_setprio 0
	v_mfma_i32_16x16x64_i8 v[54:57], v[146:149], v[182:185], v[54:57]
	v_mfma_i32_16x16x64_i8 v[50:53], v[154:157], v[182:185], v[50:53]
	v_mfma_i32_16x16x64_i8 v[38:41], v[146:149], v[198:201], v[38:41]
	v_mfma_i32_16x16x64_i8 v[34:37], v[154:157], v[198:201], v[34:37]
	v_mfma_i32_16x16x64_i8 v[22:25], v[146:149], v[206:209], v[22:25]
	v_mfma_i32_16x16x64_i8 v[18:21], v[154:157], v[206:209], v[18:21]
	v_mfma_i32_16x16x64_i8 v[6:9], v[146:149], v[220:223], v[6:9]
	v_mfma_i32_16x16x64_i8 v[2:5], v[154:157], v[220:223], v[2:5]
	v_mfma_i32_16x16x64_i8 v[54:57], v[150:153], v[186:189], v[54:57]
	v_mfma_i32_16x16x64_i8 v[50:53], v[158:161], v[186:189], v[50:53]
	v_mfma_i32_16x16x64_i8 v[38:41], v[150:153], v[202:205], v[38:41]
	v_mfma_i32_16x16x64_i8 v[34:37], v[158:161], v[202:205], v[34:37]
	v_mfma_i32_16x16x64_i8 v[22:25], v[150:153], v[216:219], v[22:25]
	v_mfma_i32_16x16x64_i8 v[18:21], v[158:161], v[216:219], v[18:21]
	v_mfma_i32_16x16x64_i8 v[6:9], v[150:153], v[224:227], v[6:9]
	v_mfma_i32_16x16x64_i8 v[2:5], v[158:161], v[224:227], v[2:5]
	s_setprio 1
	s_barrier
	s_add_i32 s53, s53, 2
	s_add_u32 s18, s18, 0x10000
	s_addc_u32 s19, s19, 0
	s_add_u32 s49, s49, 0x10000
	s_addc_u32 s52, s52, 0
	s_cmp_gt_u32 s53, 29
	s_cbranch_scc0 .LBB0_1184
	s_and_b64 vcc, exec, s[4:5]
	s_cbranch_vccz .LBB0_1187
	s_barrier

; #define PG8_STAGE(bufoff, gbase, voff) do { _Pragma("unroll") for (int _i = 0; _i < 2; ++_i) \
;         __builtin_amdgcn_global_load_lds((const unsigned*)((const char*)(gbase) + (voff)[_i]), (PG8_LAS unsigned*)(lds + (bufoff) + ldsw + _i * 8192), 16, 0, 0); } while (0)
; #define PG8_LDA(dst, b, h) do { _Pragma("unroll") for (int m = 0; m < 4; ++m) _Pragma("unroll") for (int k = 0; k < 2; ++k) dst[m][k] = *(const PG8_LAS bf16x8*)(lds + PG8_SA(b, h) + aoff + m * 2048 + k * 1024); } while (0)
; #define PG8_LDB(dst, b, h) do { _Pragma("unroll") for (int n = 0; n < 2; ++n) _Pragma("unroll") for (int k = 0; k < 2; ++k) dst[n][k] = *(const PG8_LAS bf16x8*)(lds + PG8_SB(b, h) + boff + n * 2048 + k * 1024); } while (0)
; #define PG8_WAIT_V(n) asm volatile("s_waitcnt vmcnt(" #n ")" ::: "memory")
; #define PG8_WAIT_L(n) asm volatile("s_waitcnt lgkmcnt(" #n ")" ::: "memory")
; #define PG8_BAR __builtin_amdgcn_s_barrier()
; #define PG8_SCHED __builtin_amdgcn_sched_barrier(0)
; template <class Epi, class Sched, bool ALIGN_EPI = false, bool SP2 = false, bool I8 = false>
; __device__ __forceinline__ void gemm_phase(PG8_LAS unsigned char* lds, const Gemm g, const Sched& S, const Epi& E) {
;     ...
;             PG8_LDB(B0, 0, 0); PG8_LDB(B1, 0, 1); PG8_SCHED; PG8_LDA(At, 0, 0); PG8_STAGE(PG8_SA(1, 1), a1 + hstepA, voffA);
;             PG8_WAIT_V(8); PG8_WAIT_L(0); PG8_BAR; PG8_MMA(0, 0, At, B0); PG8_MMA(0, 1, At, B1); PG8_BAR; PG8_SCHED;
;             PG8_LDA(At, 0, 1); PG8_STAGE(PG8_SB(0, 0), b2, voffB); PG8_STAGE(PG8_SB(0, 1), b2 + hstepB, voffB); PG8_STAGE(PG8_SA(0, 0), a2, voffA);
.LBB0_1263:
	ds_read_b128 v[154:157], v151
	ds_read_b128 v[158:161], v151 offset:1024
	ds_read_b128 v[162:165], v151 offset:2048
	ds_read_b128 v[166:169], v151 offset:3072
	ds_read_b128 v[170:173], v152
	ds_read_b128 v[174:177], v152 offset:1024
	ds_read_b128 v[178:181], v152 offset:2048
	ds_read_b128 v[182:185], v152 offset:3072
	s_add_u32 s28, s26, 0x4000
	s_addc_u32 s29, s27, 0
	s_cmp_eq_u32 s60, 60
	s_cselect_b32 s36, s56, s28
	s_cselect_b32 s37, s19, s29
	s_cselect_b32 s34, s57, s58
	s_cselect_b32 s35, s17, s59
	s_add_u32 s28, s36, 0x8000
	s_addc_u32 s29, s37, 0
	v_lshl_add_u64 v[146:147], s[26:27], 0, v[138:139]
	s_add_i32 m0, s25, 0xc000
	ds_read_b128 v[186:189], v153
	ds_read_b128 v[190:193], v153 offset:1024
	ds_read_b128 v[194:197], v153 offset:2048
	ds_read_b128 v[198:201], v153 offset:3072
	ds_read_b128 v[202:205], v153 offset:4096
	ds_read_b128 v[206:209], v153 offset:5120
	ds_read_b128 v[216:219], v153 offset:6144
	ds_read_b128 v[220:223], v153 offset:7168
	global_load_lds_dwordx4 v[146:147], off
	v_lshl_add_u64 v[146:147], s[26:27], 0, v[140:141]
	s_add_i32 m0, s25, 0xe000
	s_nop 0
	global_load_lds_dwordx4 v[146:147], off
	s_waitcnt vmcnt(8)
	s_waitcnt lgkmcnt(0)
	s_barrier
	s_setprio 0
	s_waitcnt lgkmcnt(0)
	v_mfma_f32_16x16x32_bf16 v[126:129], v[154:157], v[186:189], v[126:129]
	v_mfma_f32_16x16x32_bf16 v[122:125], v[162:165], v[186:189], v[122:125]
	v_mfma_f32_16x16x32_bf16 v[118:121], v[154:157], v[194:197], v[118:121]
	v_mfma_f32_16x16x32_bf16 v[110:113], v[162:165], v[194:197], v[110:113]
	v_mfma_f32_16x16x32_bf16 v[102:105], v[154:157], v[202:205], v[102:105]
	v_mfma_f32_16x16x32_bf16 v[94:97], v[162:165], v[202:205], v[94:97]
	v_mfma_f32_16x16x32_bf16 v[86:89], v[154:157], v[216:219], v[86:89]
	v_mfma_f32_16x16x32_bf16 v[78:81], v[162:165], v[216:219], v[78:81]
	v_mfma_f32_16x16x32_bf16 v[126:129], v[158:161], v[190:193], v[126:129]
	v_mfma_f32_16x16x32_bf16 v[122:125], v[166:169], v[190:193], v[122:125]
	v_mfma_f32_16x16x32_bf16 v[118:121], v[158:161], v[198:201], v[118:121]
	v_mfma_f32_16x16x32_bf16 v[110:113], v[166:169], v[198:201], v[110:113]
	v_mfma_f32_16x16x32_bf16 v[102:105], v[158:161], v[206:209], v[102:105]
	v_mfma_f32_16x16x32_bf16 v[94:97], v[166:169], v[206:209], v[94:97]
	v_mfma_f32_16x16x32_bf16 v[86:89], v[158:161], v[220:223], v[86:89]
	v_mfma_f32_16x16x32_bf16 v[78:81], v[166:169], v[220:223], v[78:81]
	s_setprio 1
	s_setprio 0
	v_mfma_f32_16x16x32_bf16 v[114:117], v[170:173], v[186:189], v[114:117]
	v_mfma_f32_16x16x32_bf16 v[106:109], v[178:181], v[186:189], v[106:109]
	v_mfma_f32_16x16x32_bf16 v[98:101], v[170:173], v[194:197], v[98:101]
	v_mfma_f32_16x16x32_bf16 v[90:93], v[178:181], v[194:197], v[90:93]
	v_mfma_f32_16x16x32_bf16 v[82:85], v[170:173], v[202:205], v[82:85]
	v_mfma_f32_16x16x32_bf16 v[74:77], v[178:181], v[202:205], v[74:77]
	v_mfma_f32_16x16x32_bf16 v[70:73], v[170:173], v[216:219], v[70:73]
	v_mfma_f32_16x16x32_bf16 v[66:69], v[178:181], v[216:219], v[66:69]
	v_mfma_f32_16x16x32_bf16 v[114:117], v[174:177], v[190:193], v[114:117]
	v_mfma_f32_16x16x32_bf16 v[106:109], v[182:185], v[190:193], v[106:109]
	v_mfma_f32_16x16x32_bf16 v[98:101], v[174:177], v[198:201], v[98:101]
	v_mfma_f32_16x16x32_bf16 v[90:93], v[182:185], v[198:201], v[90:93]
	v_mfma_f32_16x16x32_bf16 v[82:85], v[174:177], v[206:209], v[82:85]
	v_mfma_f32_16x16x32_bf16 v[74:77], v[182:185], v[206:209], v[74:77]
	v_mfma_f32_16x16x32_bf16 v[70:73], v[174:177], v[220:223], v[70:73]
	v_mfma_f32_16x16x32_bf16 v[66:69], v[182:185], v[220:223], v[66:69]
	s_setprio 1
	s_barrier
	s_add_i32 s61, s47, s39
	v_lshl_add_u64 v[146:147], s[34:35], 0, v[132:133]
	s_mov_b32 m0, s61
	ds_read_b128 v[186:189], v153 offset:16384
	ds_read_b128 v[190:193], v153 offset:17408
	ds_read_b128 v[194:197], v153 offset:18432
	ds_read_b128 v[198:201], v153 offset:19456
	ds_read_b128 v[202:205], v153 offset:20480
	ds_read_b128 v[206:209], v153 offset:21504
	ds_read_b128 v[216:219], v153 offset:22528
	ds_read_b128 v[220:223], v153 offset:23552
	global_load_lds_dwordx4 v[146:147], off
	s_add_i32 m0, s61, 0x2000
	s_add_u32 s62, s34, 0x4000
	v_lshl_add_u64 v[146:147], s[34:35], 0, v[136:137]
	s_addc_u32 s63, s35, 0
	s_add_i32 s61, s48, s39
	global_load_lds_dwordx4 v[146:147], off
	v_lshl_add_u64 v[146:147], s[62:63], 0, v[132:133]
	s_mov_b32 m0, s61
	s_nop 0
	global_load_lds_dwordx4 v[146:147], off
	v_lshl_add_u64 v[146:147], s[62:63], 0, v[136:137]
	s_add_i32 m0, s61, 0x2000
	s_nop 0
	global_load_lds_dwordx4 v[146:147], off
	v_lshl_add_u64 v[146:147], s[36:37], 0, v[130:131]
	s_mov_b32 m0, s25
	s_nop 0
	global_load_lds_dwordx4 v[146:147], off
	v_lshl_add_u64 v[146:147], s[36:37], 0, v[134:135]
	s_mov_b32 m0, s40
	s_nop 0
	global_load_lds_dwordx4 v[146:147], off
	s_waitcnt vmcnt(8)
	s_waitcnt lgkmcnt(0)
	s_barrier
; #define PG8_STAGE(bufoff, gbase, voff) do { _Pragma("unroll") for (int _i = 0; _i < 2; ++_i) \
;         __builtin_amdgcn_global_load_lds((const unsigned*)((const char*)(gbase) + (voff)[_i]), (PG8_LAS unsigned*)(lds + (bufoff) + ldsw + _i * 8192), 16, 0, 0); } while (0)
; #define PG8_LDA(dst, b, h) do { _Pragma("unroll") for (int m = 0; m < 4; ++m) _Pragma("unroll") for (int k = 0; k < 2; ++k) dst[m][k] = *(const PG8_LAS bf16x8*)(lds + PG8_SA(b, h) + aoff + m * 2048 + k * 1024); } while (0)
; #define PG8_LDB(dst, b, h) do { _Pragma("unroll") for (int n = 0; n < 2; ++n) _Pragma("unroll") for (int k = 0; k < 2; ++k) dst[n][k] = *(const PG8_LAS bf16x8*)(lds + PG8_SB(b, h) + boff + n * 2048 + k * 1024); } while (0)
; #define PG8_WAIT_V(n) asm volatile("s_waitcnt vmcnt(" #n ")" ::: "memory")
; #define PG8_WAIT_L(n) asm volatile("s_waitcnt lgkmcnt(" #n ")" ::: "memory")
; #define PG8_BAR __builtin_amdgcn_s_barrier()
; #define PG8_SCHED __builtin_amdgcn_sched_barrier(0)
; template <class Epi, class Sched, bool ALIGN_EPI = false, bool SP2 = false, bool I8 = false>
; __device__ __forceinline__ void gemm_phase(PG8_LAS unsigned char* lds, const Gemm g, const Sched& S, const Epi& E) {
;     ...
;             PG8_WAIT_V(8); PG8_WAIT_L(0); PG8_BAR; PG8_MMA(1, 0, At, B0); PG8_MMA(1, 1, At, B1); PG8_BAR; PG8_SCHED;
;             PG8_LDB(B0, 1, 0); PG8_LDB(B1, 1, 1); PG8_SCHED; PG8_LDA(At, 1, 0); PG8_STAGE(PG8_SA(0, 1), a2 + hstepA, voffA);
;             PG8_WAIT_V(8); PG8_WAIT_L(0); PG8_BAR; PG8_MMA(0, 0, At, B0); PG8_MMA(0, 1, At, B1); PG8_BAR; PG8_SCHED;
	s_setprio 0
	s_waitcnt lgkmcnt(0)
	v_mfma_f32_16x16x32_bf16 v[62:65], v[154:157], v[186:189], v[62:65]
	v_mfma_f32_16x16x32_bf16 v[58:61], v[162:165], v[186:189], v[58:61]
	v_mfma_f32_16x16x32_bf16 v[54:57], v[154:157], v[194:197], v[54:57]
	v_mfma_f32_16x16x32_bf16 v[46:49], v[162:165], v[194:197], v[46:49]
	v_mfma_f32_16x16x32_bf16 v[38:41], v[154:157], v[202:205], v[38:41]
	v_mfma_f32_16x16x32_bf16 v[30:33], v[162:165], v[202:205], v[30:33]
	v_mfma_f32_16x16x32_bf16 v[22:25], v[154:157], v[216:219], v[22:25]
	v_mfma_f32_16x16x32_bf16 v[14:17], v[162:165], v[216:219], v[14:17]
	v_mfma_f32_16x16x32_bf16 v[62:65], v[158:161], v[190:193], v[62:65]
	v_mfma_f32_16x16x32_bf16 v[58:61], v[166:169], v[190:193], v[58:61]
	v_mfma_f32_16x16x32_bf16 v[54:57], v[158:161], v[198:201], v[54:57]
	v_mfma_f32_16x16x32_bf16 v[46:49], v[166:169], v[198:201], v[46:49]
	v_mfma_f32_16x16x32_bf16 v[38:41], v[158:161], v[206:209], v[38:41]
	v_mfma_f32_16x16x32_bf16 v[30:33], v[166:169], v[206:209], v[30:33]
	v_mfma_f32_16x16x32_bf16 v[22:25], v[158:161], v[220:223], v[22:25]
	v_mfma_f32_16x16x32_bf16 v[14:17], v[166:169], v[220:223], v[14:17]
	s_setprio 1
	s_setprio 0
	v_mfma_f32_16x16x32_bf16 v[50:53], v[170:173], v[186:189], v[50:53]
	v_mfma_f32_16x16x32_bf16 v[42:45], v[178:181], v[186:189], v[42:45]
	v_mfma_f32_16x16x32_bf16 v[34:37], v[170:173], v[194:197], v[34:37]
	v_mfma_f32_16x16x32_bf16 v[26:29], v[178:181], v[194:197], v[26:29]
	v_mfma_f32_16x16x32_bf16 v[18:21], v[170:173], v[202:205], v[18:21]
	v_mfma_f32_16x16x32_bf16 v[10:13], v[178:181], v[202:205], v[10:13]
	v_mfma_f32_16x16x32_bf16 v[6:9], v[170:173], v[216:219], v[6:9]
	v_mfma_f32_16x16x32_bf16 v[2:5], v[178:181], v[216:219], v[2:5]
	v_mfma_f32_16x16x32_bf16 v[50:53], v[174:177], v[190:193], v[50:53]
	v_mfma_f32_16x16x32_bf16 v[42:45], v[182:185], v[190:193], v[42:45]
	v_mfma_f32_16x16x32_bf16 v[34:37], v[174:177], v[198:201], v[34:37]
	v_mfma_f32_16x16x32_bf16 v[26:29], v[182:185], v[198:201], v[26:29]
	v_mfma_f32_16x16x32_bf16 v[18:21], v[174:177], v[206:209], v[18:21]
	v_mfma_f32_16x16x32_bf16 v[10:13], v[182:185], v[206:209], v[10:13]
	v_mfma_f32_16x16x32_bf16 v[6:9], v[174:177], v[220:223], v[6:9]
	v_mfma_f32_16x16x32_bf16 v[2:5], v[182:185], v[220:223], v[2:5]
	s_setprio 1
	s_barrier
	s_add_i32 s61, 0, 0x18000
	v_add_u32_e32 v146, s61, v149
	s_add_i32 s62, 0, 0x1c000
	ds_read_b128 v[154:157], v146
	ds_read_b128 v[158:161], v146 offset:1024
	ds_read_b128 v[162:165], v146 offset:2048
	ds_read_b128 v[166:169], v146 offset:3072
	v_add_u32_e32 v146, s62, v149
	ds_read_b128 v[170:173], v146
	ds_read_b128 v[174:177], v146 offset:1024
	ds_read_b128 v[178:181], v146 offset:2048
	ds_read_b128 v[182:185], v146 offset:3072
	s_add_u32 s36, s36, 0x4000
	s_addc_u32 s37, s37, 0
	s_mov_b32 m0, s41
	v_lshl_add_u64 v[146:147], s[36:37], 0, v[130:131]
	ds_read_b128 v[186:189], v153 offset:32768
	ds_read_b128 v[190:193], v153 offset:33792
	ds_read_b128 v[194:197], v153 offset:34816
	ds_read_b128 v[198:201], v153 offset:35840
	ds_read_b128 v[202:205], v153 offset:36864
	ds_read_b128 v[206:209], v153 offset:37888
	ds_read_b128 v[216:219], v153 offset:38912
	ds_read_b128 v[220:223], v153 offset:39936
	global_load_lds_dwordx4 v[146:147], off
	v_lshl_add_u64 v[146:147], s[36:37], 0, v[134:135]
	s_mov_b32 m0, s42
	s_nop 0
	global_load_lds_dwordx4 v[146:147], off
	s_waitcnt vmcnt(8)
	s_waitcnt lgkmcnt(0)
	s_barrier
	s_setprio 0
	s_waitcnt lgkmcnt(0)
	v_mfma_f32_16x16x32_bf16 v[126:129], v[154:157], v[186:189], v[126:129]
	v_mfma_f32_16x16x32_bf16 v[122:125], v[162:165], v[186:189], v[122:125]
	v_mfma_f32_16x16x32_bf16 v[118:121], v[154:157], v[194:197], v[118:121]
	v_mfma_f32_16x16x32_bf16 v[110:113], v[162:165], v[194:197], v[110:113]
	v_mfma_f32_16x16x32_bf16 v[102:105], v[154:157], v[202:205], v[102:105]
	v_mfma_f32_16x16x32_bf16 v[94:97], v[162:165], v[202:205], v[94:97]
	v_mfma_f32_16x16x32_bf16 v[86:89], v[154:157], v[216:219], v[86:89]
	v_mfma_f32_16x16x32_bf16 v[78:81], v[162:165], v[216:219], v[78:81]
	v_mfma_f32_16x16x32_bf16 v[126:129], v[158:161], v[190:193], v[126:129]
	v_mfma_f32_16x16x32_bf16 v[122:125], v[166:169], v[190:193], v[122:125]
	v_mfma_f32_16x16x32_bf16 v[118:121], v[158:161], v[198:201], v[118:121]
	v_mfma_f32_16x16x32_bf16 v[110:113], v[166:169], v[198:201], v[110:113]
	v_mfma_f32_16x16x32_bf16 v[102:105], v[158:161], v[206:209], v[102:105]
	v_mfma_f32_16x16x32_bf16 v[94:97], v[166:169], v[206:209], v[94:97]
	v_mfma_f32_16x16x32_bf16 v[86:89], v[158:161], v[220:223], v[86:89]
	v_mfma_f32_16x16x32_bf16 v[78:81], v[166:169], v[220:223], v[78:81]
	s_setprio 1
	s_setprio 0
	v_mfma_f32_16x16x32_bf16 v[114:117], v[170:173], v[186:189], v[114:117]
	v_mfma_f32_16x16x32_bf16 v[106:109], v[178:181], v[186:189], v[106:109]
	v_mfma_f32_16x16x32_bf16 v[98:101], v[170:173], v[194:197], v[98:101]
	v_mfma_f32_16x16x32_bf16 v[90:93], v[178:181], v[194:197], v[90:93]
	v_mfma_f32_16x16x32_bf16 v[82:85], v[170:173], v[202:205], v[82:85]
	v_mfma_f32_16x16x32_bf16 v[74:77], v[178:181], v[202:205], v[74:77]
	v_mfma_f32_16x16x32_bf16 v[70:73], v[170:173], v[216:219], v[70:73]
	v_mfma_f32_16x16x32_bf16 v[66:69], v[178:181], v[216:219], v[66:69]
	v_mfma_f32_16x16x32_bf16 v[114:117], v[174:177], v[190:193], v[114:117]
	v_mfma_f32_16x16x32_bf16 v[106:109], v[182:185], v[190:193], v[106:109]
	v_mfma_f32_16x16x32_bf16 v[98:101], v[174:177], v[198:201], v[98:101]
	v_mfma_f32_16x16x32_bf16 v[90:93], v[182:185], v[198:201], v[90:93]
	v_mfma_f32_16x16x32_bf16 v[82:85], v[174:177], v[206:209], v[82:85]
	v_mfma_f32_16x16x32_bf16 v[74:77], v[182:185], v[206:209], v[74:77]
	v_mfma_f32_16x16x32_bf16 v[70:73], v[174:177], v[220:223], v[70:73]
	v_mfma_f32_16x16x32_bf16 v[66:69], v[182:185], v[220:223], v[66:69]
	s_setprio 1
	s_barrier
; #define PG8_STAGE(bufoff, gbase, voff) do { _Pragma("unroll") for (int _i = 0; _i < 2; ++_i) \
;         __builtin_amdgcn_global_load_lds((const unsigned*)((const char*)(gbase) + (voff)[_i]), (PG8_LAS unsigned*)(lds + (bufoff) + ldsw + _i * 8192), 16, 0, 0); } while (0)
; #define PG8_LDA(dst, b, h) do { _Pragma("unroll") for (int m = 0; m < 4; ++m) _Pragma("unroll") for (int k = 0; k < 2; ++k) dst[m][k] = *(const PG8_LAS bf16x8*)(lds + PG8_SA(b, h) + aoff + m * 2048 + k * 1024); } while (0)
; #define PG8_WAIT_V(n) asm volatile("s_waitcnt vmcnt(" #n ")" ::: "memory")
; #define PG8_WAIT_L(n) asm volatile("s_waitcnt lgkmcnt(" #n ")" ::: "memory")
; #define PG8_BAR __builtin_amdgcn_s_barrier()
; #define PG8_SCHED __builtin_amdgcn_sched_barrier(0)
; template <class Epi, class Sched, bool ALIGN_EPI = false, bool SP2 = false, bool I8 = false>
; __device__ __forceinline__ void gemm_phase(PG8_LAS unsigned char* lds, const Gemm g, const Sched& S, const Epi& E) {
;     ...
;         for (int t = 0; t < nt; t += 2) {
;             const bool last = (t == nt - 2);
;             const char* a1 = cA + (size_t)(t + 1) * kstepA;
;             const char* a2 = last ? nA : cA + (size_t)(t + 2) * kstepA; const char* b2 = last ? nB : cB + (size_t)(t + 2) * kstepB;
;             const char* a3 = a2 + kstepA; const char* b3 = b2 + kstepB;
;             if (last && has_next) S.a_ready(nxt);
;     ...
;             PG8_LDA(At, 1, 1); PG8_STAGE(PG8_SB(1, 0), b3, voffB); PG8_STAGE(PG8_SB(1, 1), b3 + hstepB, voffB); PG8_STAGE(PG8_SA(1, 0), a3, voffA);
;             PG8_WAIT_V(8); PG8_WAIT_L(0); PG8_BAR; PG8_MMA(1, 0, At, B0); PG8_MMA(1, 1, At, B1); PG8_BAR; PG8_SCHED;
	s_add_u32 s36, s34, 0x8000
	s_addc_u32 s37, s35, 0
	s_add_i32 s61, s61, s39
	v_lshl_add_u64 v[146:147], s[36:37], 0, v[132:133]
	s_mov_b32 m0, s61
	ds_read_b128 v[186:189], v153 offset:49152
	ds_read_b128 v[190:193], v153 offset:50176
	ds_read_b128 v[194:197], v153 offset:51200
	ds_read_b128 v[198:201], v153 offset:52224
	ds_read_b128 v[202:205], v153 offset:53248
	ds_read_b128 v[206:209], v153 offset:54272
	ds_read_b128 v[216:219], v153 offset:55296
	ds_read_b128 v[220:223], v153 offset:56320
	global_load_lds_dwordx4 v[146:147], off
	s_add_i32 m0, s61, 0x2000
	s_add_u32 s34, s34, 0xc000
	v_lshl_add_u64 v[146:147], s[36:37], 0, v[136:137]
	s_addc_u32 s35, s35, 0
	s_add_i32 s36, s62, s39
	global_load_lds_dwordx4 v[146:147], off
	v_lshl_add_u64 v[146:147], s[34:35], 0, v[132:133]
	s_mov_b32 m0, s36
	s_nop 0
	global_load_lds_dwordx4 v[146:147], off
	v_lshl_add_u64 v[146:147], s[34:35], 0, v[136:137]
	s_add_i32 m0, s36, 0x2000
	s_nop 0
	global_load_lds_dwordx4 v[146:147], off
	v_lshl_add_u64 v[146:147], s[28:29], 0, v[130:131]
	s_mov_b32 m0, s44
	s_nop 0
	global_load_lds_dwordx4 v[146:147], off
	v_lshl_add_u64 v[146:147], s[28:29], 0, v[134:135]
	s_mov_b32 m0, s45
	s_nop 0
	global_load_lds_dwordx4 v[146:147], off
	s_waitcnt vmcnt(8)
	s_waitcnt lgkmcnt(0)
	s_barrier
	s_setprio 0
	s_waitcnt lgkmcnt(0)
	v_mfma_f32_16x16x32_bf16 v[62:65], v[154:157], v[186:189], v[62:65]
	v_mfma_f32_16x16x32_bf16 v[58:61], v[162:165], v[186:189], v[58:61]
	v_mfma_f32_16x16x32_bf16 v[54:57], v[154:157], v[194:197], v[54:57]
	v_mfma_f32_16x16x32_bf16 v[46:49], v[162:165], v[194:197], v[46:49]
	v_mfma_f32_16x16x32_bf16 v[38:41], v[154:157], v[202:205], v[38:41]
	v_mfma_f32_16x16x32_bf16 v[30:33], v[162:165], v[202:205], v[30:33]
	v_mfma_f32_16x16x32_bf16 v[22:25], v[154:157], v[216:219], v[22:25]
	v_mfma_f32_16x16x32_bf16 v[14:17], v[162:165], v[216:219], v[14:17]
	v_mfma_f32_16x16x32_bf16 v[62:65], v[158:161], v[190:193], v[62:65]
	v_mfma_f32_16x16x32_bf16 v[58:61], v[166:169], v[190:193], v[58:61]
	v_mfma_f32_16x16x32_bf16 v[54:57], v[158:161], v[198:201], v[54:57]
	v_mfma_f32_16x16x32_bf16 v[46:49], v[166:169], v[198:201], v[46:49]
	v_mfma_f32_16x16x32_bf16 v[38:41], v[158:161], v[206:209], v[38:41]
	v_mfma_f32_16x16x32_bf16 v[30:33], v[166:169], v[206:209], v[30:33]
	v_mfma_f32_16x16x32_bf16 v[22:25], v[158:161], v[220:223], v[22:25]
	v_mfma_f32_16x16x32_bf16 v[14:17], v[166:169], v[220:223], v[14:17]
	s_setprio 1
	s_setprio 0
	v_mfma_f32_16x16x32_bf16 v[50:53], v[170:173], v[186:189], v[50:53]
	v_mfma_f32_16x16x32_bf16 v[42:45], v[178:181], v[186:189], v[42:45]
	v_mfma_f32_16x16x32_bf16 v[34:37], v[170:173], v[194:197], v[34:37]
	v_mfma_f32_16x16x32_bf16 v[26:29], v[178:181], v[194:197], v[26:29]
	v_mfma_f32_16x16x32_bf16 v[18:21], v[170:173], v[202:205], v[18:21]
	v_mfma_f32_16x16x32_bf16 v[10:13], v[178:181], v[202:205], v[10:13]
	v_mfma_f32_16x16x32_bf16 v[6:9], v[170:173], v[216:219], v[6:9]
	v_mfma_f32_16x16x32_bf16 v[2:5], v[178:181], v[216:219], v[2:5]
	v_mfma_f32_16x16x32_bf16 v[50:53], v[174:177], v[190:193], v[50:53]
	v_mfma_f32_16x16x32_bf16 v[42:45], v[182:185], v[190:193], v[42:45]
	v_mfma_f32_16x16x32_bf16 v[34:37], v[174:177], v[198:201], v[34:37]
	v_mfma_f32_16x16x32_bf16 v[26:29], v[182:185], v[198:201], v[26:29]
	v_mfma_f32_16x16x32_bf16 v[18:21], v[174:177], v[206:209], v[18:21]
	v_mfma_f32_16x16x32_bf16 v[10:13], v[182:185], v[206:209], v[10:13]
	v_mfma_f32_16x16x32_bf16 v[6:9], v[174:177], v[220:223], v[6:9]
	v_mfma_f32_16x16x32_bf16 v[2:5], v[182:185], v[220:223], v[2:5]
	s_setprio 1
	s_barrier
	s_add_i32 s60, s60, 2
	s_add_u32 s26, s26, 0x10000
	s_addc_u32 s27, s27, 0
	s_add_u32 s58, s58, 0x10000
	s_addc_u32 s59, s59, 0
	s_cmp_gt_u32 s60, 61
	s_cbranch_scc0 .LBB0_1263
	s_and_b64 vcc, exec, s[6:7]
	s_cbranch_vccz .LBB0_1266
	s_barrier
